# v38 + residual epilogues (out-proj, FFN down): both column halves' residual loads issued together per 16-row group
# speedup vs baseline: 1.0067x; 1.0067x over previous
; __device__ __forceinline__ u32x2 pack8i8(const f32x4 a, const f32x4 b) { return (u32x2){pack4i8(a), pack4i8(b)}; }
; __device__ __forceinline__ u32x4 pack8bf(const f32x4 a, const f32x4 b) { u32x4 w; w.x = cvt_pk_bf16(a[0], a[1]); w.y = cvt_pk_bf16(a[2], a[3]); w.z = cvt_pk_bf16(b[0], b[1]); w.w = cvt_pk_bf16(b[2], b[3]); return w; }
;     __device__ __forceinline__ void operator()(EPI_ARGS) const {
;     ...
;             for (int m = 0; m < 4; ++m) { const int row = row0 + ai * HALF + m * 16; const size_t off = (size_t)row * DM + col0;
;                 float mu = 0.f, rs = 1.f; if constexpr (RESLN) ln_stats(stin, row, mu, rs);
;                 float ss = 0.f, qq = 0.f;
; #pragma unroll
;                 for (int bj = 0; bj < 2; ++bj) { f32x4 r0 = __builtin_nontemporal_load((const f32x4*)(res + off + bj * HALF)), r1 = __builtin_nontemporal_load((const f32x4*)(res + off + bj * HALF + 4));
;                     if constexpr (RESLN) { r0 = (r0 - mu) * rs * gg[bj][0] + bb[bj][0]; r1 = (r1 - mu) * rs * gg[bj][1] + bb[bj][1]; }
;                     const f32x4 y0 = r0 * DN_ALPHA + acc[ai][bj][m][0] * ascale, y1 = r1 * DN_ALPHA + acc[ai][bj][m][1] * ascale;
;                     if constexpr (COPY != 4) { __builtin_nontemporal_store(y0, (f32x4*)(Y + off + bj * HALF)); __builtin_nontemporal_store(y1, (f32x4*)(Y + off + bj * HALF + 4)); }
;                     if constexpr (STATS) { ss += ((y0[0] + y0[1]) + (y0[2] + y0[3])) + ((y1[0] + y1[1]) + (y1[2] + y1[3]));
;                         qq += ((y0[0] * y0[0] + y0[1] * y0[1]) + (y0[2] * y0[2] + y0[3] * y0[3])) + ((y1[0] * y1[0] + y1[1] * y1[1]) + (y1[2] * y1[2] + y1[3] * y1[3])); }
;                     if constexpr (COPY == 1) *(u32x2*)((unsigned char*)copy + off + bj * HALF) = pack8fp8(y0 * cscale, y1 * cscale);
;                     if constexpr (COPY == 3) *(u32x2*)((unsigned char*)copy + off + bj * HALF) = pack8i8(y0 * cscale, y1 * cscale);
;                     if constexpr (COPY == 2 || COPY == 4) *(u32x4*)((bf16_t*)copy + off + bj * HALF) = pack8bf(y0, y1); }
;                 if constexpr (STATS) { ss += __shfl_xor(ss, 16); ss += __shfl_xor(ss, 32); qq += __shfl_xor(qq, 16); qq += __shfl_xor(qq, 32);
;                     if (fq == 0) { unsafeAtomicAdd(stout + 2 * (size_t)row, ss); unsafeAtomicAdd(stout + 2 * (size_t)row + 1, qq); } }
.LBB0_3689:
	v_lshl_add_u32 v2, s40, 8, v184
	v_lshl_or_b32 v0, s42, 8, v186
	v_ashrrev_i32_e32 v3, 31, v2
	v_ashrrev_i32_e32 v1, 31, v0
	v_lshlrev_b64 v[4:5], 11, v[2:3]
	v_lshl_add_u64 v[12:13], v[4:5], 0, v[0:1]
	v_lshlrev_b64 v[14:15], 2, v[12:13]
	v_lshl_add_u64 v[20:21], s[6:7], 0, v[14:15]
	global_load_dwordx4 v[4:7], v[20:21], off nt
	global_load_dwordx4 v[8:11], v[20:21], off offset:16 nt
	global_load_dwordx4 v[228:231], v[20:21], off offset:512 nt
	global_load_dwordx4 v[232:235], v[20:21], off offset:528 nt
	v_lshl_add_u64 v[24:25], s[12:13], 0, v[12:13]
	v_lshl_add_u64 v[26:27], s[10:11], 0, v[14:15]
	s_waitcnt vmcnt(2)
	v_pk_mul_f32 v[6:7], v[6:7], s[20:21] op_sel_hi:[1,0]
	v_pk_mul_f32 v[4:5], v[4:5], s[20:21] op_sel_hi:[1,0]
	v_pk_mul_f32 v[12:13], v[10:11], s[20:21] op_sel_hi:[1,0]
	v_pk_mul_f32 v[16:17], v[8:9], s[20:21] op_sel_hi:[1,0]
	v_pk_fma_f32 v[10:11], v[158:159], s[24:25], v[6:7] op_sel_hi:[1,0,1]
	v_pk_fma_f32 v[8:9], v[156:157], s[24:25], v[4:5] op_sel_hi:[1,0,1]
	v_pk_fma_f32 v[14:15], v[154:155], s[24:25], v[12:13] op_sel_hi:[1,0,1]
	v_pk_fma_f32 v[12:13], v[152:153], s[24:25], v[16:17] op_sel_hi:[1,0,1]
	v_pk_mul_f32 v[4:5], v[10:11], s[26:27] op_sel_hi:[1,0]
	v_pk_mul_f32 v[6:7], v[8:9], s[26:27] op_sel_hi:[1,0]
	v_pk_mul_f32 v[16:17], v[14:15], s[26:27] op_sel_hi:[1,0]
	v_pk_mul_f32 v[18:19], v[12:13], s[26:27] op_sel_hi:[1,0]
	v_med3_f32 v6, v6, s63, v192
	v_med3_f32 v7, v7, s63, v192
	v_med3_f32 v4, v4, s63, v192
	v_med3_f32 v5, v5, s63, v192
	v_med3_f32 v18, v18, s63, v192
	v_med3_f32 v19, v19, s63, v192
	v_med3_f32 v16, v16, s63, v192
	v_med3_f32 v17, v17, s63, v192
	v_add_f32_e32 v6, 0x4b400000, v6
	v_add_f32_e32 v7, 0x4b400000, v7
	v_add_f32_e32 v4, 0x4b400000, v4
	v_add_f32_e32 v5, 0x4b400000, v5
	v_add_f32_e32 v18, 0x4b400000, v18
	v_add_f32_e32 v19, 0x4b400000, v19
	v_add_f32_e32 v16, 0x4b400000, v16
	v_add_f32_e32 v17, 0x4b400000, v17
	v_perm_b32 v6, v7, v6, s64
	v_perm_b32 v4, v5, v4, s65
	v_perm_b32 v5, v19, v18, s64
	v_perm_b32 v7, v17, v16, s65
	v_or_b32_e32 v4, v6, v4
	v_or_b32_e32 v5, v5, v7
	global_store_dwordx4 v[26:27], v[8:11], off nt
	global_store_dwordx4 v[26:27], v[12:15], off offset:16 nt
	global_store_dwordx2 v[24:25], v[4:5], off
	s_waitcnt vmcnt(3)
	s_nop 1
	v_mov_b32_e32 v16, v228
	v_mov_b32_e32 v17, v229
	v_mov_b32_e32 v18, v230
	v_mov_b32_e32 v19, v231
	v_mov_b32_e32 v20, v232
	v_mov_b32_e32 v21, v233
	v_mov_b32_e32 v22, v234
	v_mov_b32_e32 v23, v235
	v_and_b32_e32 v5, 64, v191
	v_xor_b32_e32 v4, 16, v191
	v_add_u32_e32 v5, 64, v5
	v_xor_b32_e32 v6, 32, v191
	v_cmp_lt_i32_e32 vcc, v4, v5
	v_add_f32_e32 v28, v12, v13
	v_add_f32_e32 v29, v14, v15
	v_cndmask_b32_e32 v4, v191, v4, vcc
	v_cmp_lt_i32_e32 vcc, v6, v5
	v_lshlrev_b32_e32 v7, 2, v4
	v_add_f32_e32 v4, v8, v9
	v_cndmask_b32_e32 v5, v191, v6, vcc
	v_lshlrev_b32_e32 v6, 2, v5
	v_add_f32_e32 v5, v10, v11
	v_mul_f32_e32 v9, v9, v9
	v_mul_f32_e32 v11, v11, v11
	v_mul_f32_e32 v13, v13, v13
	v_mul_f32_e32 v15, v15, v15
	v_add_f32_e32 v4, v4, v5
	v_add_f32_e32 v5, v28, v29
	v_fmac_f32_e32 v9, v8, v8
	v_fmac_f32_e32 v11, v10, v10
	v_fmac_f32_e32 v13, v12, v12
	v_fmac_f32_e32 v15, v14, v14
	v_add_f32_e32 v4, v4, v5
	v_add_f32_e32 v5, v9, v11
	v_add_f32_e32 v8, v13, v15
	v_add_f32_e32 v28, 0, v4
	v_add_f32_e32 v29, v5, v8
	v_pk_mul_f32 v[4:5], v[18:19], s[20:21] op_sel_hi:[1,0]
	v_pk_mul_f32 v[8:9], v[16:17], s[20:21] op_sel_hi:[1,0]
	v_pk_mul_f32 v[12:13], v[22:23], s[20:21] op_sel_hi:[1,0]
	v_pk_mul_f32 v[16:17], v[20:21], s[20:21] op_sel_hi:[1,0]
	v_pk_fma_f32 v[10:11], v[150:151], s[24:25], v[4:5] op_sel_hi:[1,0,1]
	v_pk_fma_f32 v[8:9], v[148:149], s[24:25], v[8:9] op_sel_hi:[1,0,1]
	v_pk_fma_f32 v[14:15], v[146:147], s[24:25], v[12:13] op_sel_hi:[1,0,1]
	v_pk_fma_f32 v[12:13], v[144:145], s[24:25], v[16:17] op_sel_hi:[1,0,1]
	global_store_dwordx4 v[26:27], v[8:11], off offset:512 nt
	global_store_dwordx4 v[26:27], v[12:15], off offset:528 nt
	v_add_f32_e32 v22, v8, v9
	v_add_f32_e32 v23, v10, v11
	v_add_f32_e32 v26, v12, v13
	v_add_f32_e32 v27, v14, v15
	v_mul_f32_e32 v30, v9, v9
	v_mul_f32_e32 v31, v11, v11
	v_mul_f32_e32 v144, v13, v13
	v_mul_f32_e32 v145, v15, v15
	v_pk_mul_f32 v[4:5], v[10:11], s[26:27] op_sel_hi:[1,0]
	v_pk_mul_f32 v[16:17], v[8:9], s[26:27] op_sel_hi:[1,0]
	v_add_f32_e32 v9, v22, v23
	v_add_f32_e32 v11, v26, v27
	v_fmac_f32_e32 v30, v8, v8
	v_fmac_f32_e32 v31, v10, v10
	v_fmac_f32_e32 v144, v12, v12
	v_fmac_f32_e32 v145, v14, v14
	v_med3_f32 v8, v16, s63, v192
	v_add_f32_e32 v9, v9, v11
	v_add_f32_e32 v11, v30, v31
	v_add_f32_e32 v16, v144, v145
	v_add_f32_e32 v11, v11, v16
	v_add_f32_e32 v9, v28, v9
	v_add_f32_e32 v11, v29, v11
	v_med3_f32 v10, v17, s63, v192
	v_mov_b32_e32 v16, v9
	s_nop 1
	v_permlane16_swap_b32_e32 v9, v16
	v_mov_b32_e32 v17, v11
	s_nop 1
	v_permlane16_swap_b32_e32 v11, v17
	v_med3_f32 v4, v4, s63, v192
	v_med3_f32 v5, v5, s63, v192
	v_add_f32_e32 v8, 0x4b400000, v8
	v_add_f32_e32 v10, 0x4b400000, v10
	v_add_f32_e32 v4, 0x4b400000, v4
	v_add_f32_e32 v5, 0x4b400000, v5
	v_perm_b32 v8, v10, v8, s64
	v_perm_b32 v4, v5, v4, s65
	v_or_b32_e32 v10, v8, v4
	s_waitcnt lgkmcnt(0)
	v_add_f32_e32 v4, v9, v16
	s_waitcnt lgkmcnt(0)
	v_add_f32_e32 v8, v11, v17
	v_pk_mul_f32 v[18:19], v[14:15], s[26:27] op_sel_hi:[1,0]
	v_pk_mul_f32 v[20:21], v[12:13], s[26:27] op_sel_hi:[1,0]
	v_mov_b32_e32 v5, v4
	s_nop 1
	v_permlane32_swap_b32_e32 v4, v5
	v_mov_b32_e32 v9, v8
	s_nop 1
	v_permlane32_swap_b32_e32 v8, v9
	v_med3_f32 v12, v20, s63, v192
	v_med3_f32 v13, v21, s63, v192
	v_med3_f32 v14, v18, s63, v192
	v_med3_f32 v15, v19, s63, v192
	v_add_f32_e32 v12, 0x4b400000, v12
	v_add_f32_e32 v13, 0x4b400000, v13
	v_add_f32_e32 v14, 0x4b400000, v14
	v_add_f32_e32 v15, 0x4b400000, v15
	v_perm_b32 v11, v13, v12, s64
	v_perm_b32 v12, v15, v14, s65
	v_or_b32_e32 v11, v11, v12
	global_store_dwordx2 v[24:25], v[10:11], off offset:128
	s_and_saveexec_b64 s[40:41], s[2:3]
	s_cbranch_execz .LBB0_3691
	v_lshl_add_u64 v[10:11], v[2:3], 3, s[14:15]
	s_waitcnt lgkmcnt(0)
	v_add_f32_e32 v3, v4, v5
	s_waitcnt lgkmcnt(0)
	v_add_f32_e32 v4, v8, v9
	global_atomic_add_f32 v[10:11], v3, off
	global_atomic_add_f32 v[10:11], v4, off offset:4
; __device__ __forceinline__ u32x2 pack8i8(const f32x4 a, const f32x4 b) { return (u32x2){pack4i8(a), pack4i8(b)}; }
; __device__ __forceinline__ u32x4 pack8bf(const f32x4 a, const f32x4 b) { u32x4 w; w.x = cvt_pk_bf16(a[0], a[1]); w.y = cvt_pk_bf16(a[2], a[3]); w.z = cvt_pk_bf16(b[0], b[1]); w.w = cvt_pk_bf16(b[2], b[3]); return w; }
;     __device__ __forceinline__ void operator()(EPI_ARGS) const {
;     ...
;             for (int m = 0; m < 4; ++m) { const int row = row0 + ai * HALF + m * 16; const size_t off = (size_t)row * DM + col0;
;                 float mu = 0.f, rs = 1.f; if constexpr (RESLN) ln_stats(stin, row, mu, rs);
;                 float ss = 0.f, qq = 0.f;
; #pragma unroll
;                 for (int bj = 0; bj < 2; ++bj) { f32x4 r0 = __builtin_nontemporal_load((const f32x4*)(res + off + bj * HALF)), r1 = __builtin_nontemporal_load((const f32x4*)(res + off + bj * HALF + 4));
;                     if constexpr (RESLN) { r0 = (r0 - mu) * rs * gg[bj][0] + bb[bj][0]; r1 = (r1 - mu) * rs * gg[bj][1] + bb[bj][1]; }
;                     const f32x4 y0 = r0 * DN_ALPHA + acc[ai][bj][m][0] * ascale, y1 = r1 * DN_ALPHA + acc[ai][bj][m][1] * ascale;
;                     if constexpr (COPY != 4) { __builtin_nontemporal_store(y0, (f32x4*)(Y + off + bj * HALF)); __builtin_nontemporal_store(y1, (f32x4*)(Y + off + bj * HALF + 4)); }
;                     if constexpr (STATS) { ss += ((y0[0] + y0[1]) + (y0[2] + y0[3])) + ((y1[0] + y1[1]) + (y1[2] + y1[3]));
;                         qq += ((y0[0] * y0[0] + y0[1] * y0[1]) + (y0[2] * y0[2] + y0[3] * y0[3])) + ((y1[0] * y1[0] + y1[1] * y1[1]) + (y1[2] * y1[2] + y1[3] * y1[3])); }
;                     if constexpr (COPY == 1) *(u32x2*)((unsigned char*)copy + off + bj * HALF) = pack8fp8(y0 * cscale, y1 * cscale);
;                     if constexpr (COPY == 3) *(u32x2*)((unsigned char*)copy + off + bj * HALF) = pack8i8(y0 * cscale, y1 * cscale);
;                     if constexpr (COPY == 2 || COPY == 4) *(u32x4*)((bf16_t*)copy + off + bj * HALF) = pack8bf(y0, y1); }
;                 if constexpr (STATS) { ss += __shfl_xor(ss, 16); ss += __shfl_xor(ss, 32); qq += __shfl_xor(qq, 16); qq += __shfl_xor(qq, 32);
;                     if (fq == 0) { unsafeAtomicAdd(stout + 2 * (size_t)row, ss); unsafeAtomicAdd(stout + 2 * (size_t)row + 1, qq); } }
.LBB0_3691:
	s_or_b64 exec, exec, s[40:41]
	v_or_b32_e32 v4, 16, v2
	s_waitcnt lgkmcnt(1)
	v_ashrrev_i32_e32 v5, 31, v4
	s_waitcnt lgkmcnt(0)
	v_lshlrev_b64 v[8:9], 11, v[4:5]
	v_lshl_add_u64 v[16:17], v[8:9], 0, v[0:1]
	v_lshlrev_b64 v[18:19], 2, v[16:17]
	v_lshl_add_u64 v[20:21], s[6:7], 0, v[18:19]
	global_load_dwordx4 v[8:11], v[20:21], off nt
	global_load_dwordx4 v[12:15], v[20:21], off offset:16 nt
	global_load_dwordx4 v[228:231], v[20:21], off offset:512 nt
	global_load_dwordx4 v[232:235], v[20:21], off offset:528 nt
	v_lshl_add_u64 v[24:25], s[12:13], 0, v[16:17]
	v_lshl_add_u64 v[26:27], s[10:11], 0, v[18:19]
	s_waitcnt vmcnt(3)
	v_pk_mul_f32 v[10:11], v[10:11], s[20:21] op_sel_hi:[1,0]
	v_pk_mul_f32 v[8:9], v[8:9], s[20:21] op_sel_hi:[1,0]
	s_waitcnt vmcnt(2)
	v_pk_mul_f32 v[14:15], v[14:15], s[20:21] op_sel_hi:[1,0]
	v_pk_mul_f32 v[12:13], v[12:13], s[20:21] op_sel_hi:[1,0]
	v_pk_fma_f32 v[10:11], v[142:143], s[24:25], v[10:11] op_sel_hi:[1,0,1]
	v_pk_fma_f32 v[8:9], v[140:141], s[24:25], v[8:9] op_sel_hi:[1,0,1]
	v_pk_fma_f32 v[14:15], v[138:139], s[24:25], v[14:15] op_sel_hi:[1,0,1]
	v_pk_fma_f32 v[12:13], v[136:137], s[24:25], v[12:13] op_sel_hi:[1,0,1]
	v_pk_mul_f32 v[16:17], v[10:11], s[26:27] op_sel_hi:[1,0]
	v_pk_mul_f32 v[18:19], v[8:9], s[26:27] op_sel_hi:[1,0]
	v_pk_mul_f32 v[22:23], v[14:15], s[26:27] op_sel_hi:[1,0]
	v_pk_mul_f32 v[28:29], v[12:13], s[26:27] op_sel_hi:[1,0]
	v_med3_f32 v3, v18, s63, v192
	v_med3_f32 v18, v19, s63, v192
	v_med3_f32 v16, v16, s63, v192
	v_med3_f32 v17, v17, s63, v192
	v_med3_f32 v19, v28, s63, v192
	v_med3_f32 v28, v29, s63, v192
	v_med3_f32 v22, v22, s63, v192
	v_med3_f32 v23, v23, s63, v192
	v_add_f32_e32 v3, 0x4b400000, v3
	v_add_f32_e32 v18, 0x4b400000, v18
	v_add_f32_e32 v16, 0x4b400000, v16
	v_add_f32_e32 v17, 0x4b400000, v17
	v_add_f32_e32 v19, 0x4b400000, v19
	v_add_f32_e32 v28, 0x4b400000, v28
	v_add_f32_e32 v22, 0x4b400000, v22
	v_add_f32_e32 v23, 0x4b400000, v23
	v_perm_b32 v3, v18, v3, s64
	v_perm_b32 v16, v17, v16, s65
	v_perm_b32 v17, v28, v19, s64
	v_perm_b32 v18, v23, v22, s65
	v_or_b32_e32 v16, v3, v16
	v_or_b32_e32 v17, v17, v18
	global_store_dwordx4 v[26:27], v[8:11], off nt
	global_store_dwordx4 v[26:27], v[12:15], off offset:16 nt
	global_store_dwordx2 v[24:25], v[16:17], off
	s_waitcnt vmcnt(3)
	s_nop 1
	v_mov_b32_e32 v16, v228
	v_mov_b32_e32 v17, v229
	v_mov_b32_e32 v18, v230
	v_mov_b32_e32 v19, v231
	v_mov_b32_e32 v20, v232
	v_mov_b32_e32 v21, v233
	v_mov_b32_e32 v22, v234
	v_mov_b32_e32 v23, v235
	v_add_f32_e32 v3, v8, v9
	v_add_f32_e32 v28, v10, v11
	v_add_f32_e32 v29, v12, v13
	v_add_f32_e32 v30, v14, v15
	v_mul_f32_e32 v9, v9, v9
	v_mul_f32_e32 v11, v11, v11
	v_mul_f32_e32 v13, v13, v13
	v_mul_f32_e32 v15, v15, v15
	v_fmac_f32_e32 v9, v8, v8
	v_fmac_f32_e32 v11, v10, v10
	v_fmac_f32_e32 v13, v12, v12
	v_fmac_f32_e32 v15, v14, v14
	v_add_f32_e32 v3, v3, v28
	v_add_f32_e32 v28, v29, v30
	v_add_f32_e32 v8, v9, v11
	v_add_f32_e32 v9, v13, v15
	v_add_f32_e32 v3, v3, v28
	v_add_f32_e32 v28, v8, v9
	v_add_f32_e32 v3, 0, v3
	v_pk_mul_f32 v[8:9], v[18:19], s[20:21] op_sel_hi:[1,0]
	v_pk_mul_f32 v[12:13], v[16:17], s[20:21] op_sel_hi:[1,0]
	v_pk_mul_f32 v[14:15], v[22:23], s[20:21] op_sel_hi:[1,0]
	v_pk_mul_f32 v[16:17], v[20:21], s[20:21] op_sel_hi:[1,0]
	v_pk_fma_f32 v[10:11], v[134:135], s[24:25], v[8:9] op_sel_hi:[1,0,1]
	v_pk_fma_f32 v[8:9], v[132:133], s[24:25], v[12:13] op_sel_hi:[1,0,1]
	v_pk_fma_f32 v[14:15], v[130:131], s[24:25], v[14:15] op_sel_hi:[1,0,1]
	v_pk_fma_f32 v[12:13], v[128:129], s[24:25], v[16:17] op_sel_hi:[1,0,1]
	global_store_dwordx4 v[26:27], v[8:11], off offset:512 nt
	global_store_dwordx4 v[26:27], v[12:15], off offset:528 nt
	v_add_f32_e32 v26, v8, v9
	v_add_f32_e32 v27, v10, v11
	v_add_f32_e32 v29, v12, v13
	v_add_f32_e32 v30, v14, v15
	v_mul_f32_e32 v31, v9, v9
	v_mul_f32_e32 v128, v11, v11
	v_mul_f32_e32 v129, v13, v13
	v_mul_f32_e32 v130, v15, v15
	v_pk_mul_f32 v[16:17], v[10:11], s[26:27] op_sel_hi:[1,0]
	v_pk_mul_f32 v[18:19], v[8:9], s[26:27] op_sel_hi:[1,0]
	v_add_f32_e32 v9, v26, v27
	v_add_f32_e32 v11, v29, v30
	v_fmac_f32_e32 v31, v8, v8
	v_fmac_f32_e32 v128, v10, v10
	v_fmac_f32_e32 v129, v12, v12
	v_fmac_f32_e32 v130, v14, v14
	v_med3_f32 v8, v18, s63, v192
	v_add_f32_e32 v9, v9, v11
	v_add_f32_e32 v11, v31, v128
	v_add_f32_e32 v18, v129, v130
	v_med3_f32 v10, v19, s63, v192
	v_add_f32_e32 v3, v3, v9
	v_add_f32_e32 v9, v11, v18
	v_add_f32_e32 v8, 0x4b400000, v8
	v_add_f32_e32 v10, 0x4b400000, v10
	v_add_f32_e32 v9, v28, v9
	v_perm_b32 v8, v10, v8, s64
	v_mov_b32_e32 v10, v3
	s_nop 1
	v_permlane16_swap_b32_e32 v3, v10
	v_mov_b32_e32 v11, v9
	s_nop 1
	v_permlane16_swap_b32_e32 v9, v11
	v_pk_mul_f32 v[22:23], v[12:13], s[26:27] op_sel_hi:[1,0]
	v_med3_f32 v12, v16, s63, v192
	v_med3_f32 v13, v17, s63, v192
	v_add_f32_e32 v12, 0x4b400000, v12
	v_add_f32_e32 v13, 0x4b400000, v13
	v_perm_b32 v12, v13, v12, s65
	s_waitcnt lgkmcnt(0)
	v_add_f32_e32 v3, v3, v10
	s_waitcnt lgkmcnt(0)
	v_add_f32_e32 v9, v9, v11
	v_pk_mul_f32 v[20:21], v[14:15], s[26:27] op_sel_hi:[1,0]
	v_or_b32_e32 v12, v8, v12
	v_mov_b32_e32 v8, v3
	s_nop 1
	v_permlane32_swap_b32_e32 v3, v8
	v_mov_b32_e32 v10, v9
	s_nop 1
	v_permlane32_swap_b32_e32 v9, v10
	v_med3_f32 v14, v22, s63, v192
	v_med3_f32 v15, v23, s63, v192
	v_med3_f32 v16, v20, s63, v192
	v_med3_f32 v17, v21, s63, v192
	v_add_f32_e32 v14, 0x4b400000, v14
	v_add_f32_e32 v15, 0x4b400000, v15
	v_add_f32_e32 v16, 0x4b400000, v16
	v_add_f32_e32 v17, 0x4b400000, v17
	v_perm_b32 v11, v15, v14, s64
	v_perm_b32 v13, v17, v16, s65
	v_or_b32_e32 v13, v11, v13
	global_store_dwordx2 v[24:25], v[12:13], off offset:128
	s_and_saveexec_b64 s[40:41], s[2:3]
	s_cbranch_execz .LBB0_3693
	v_lshl_add_u64 v[4:5], v[4:5], 3, s[14:15]
	s_waitcnt lgkmcnt(0)
	v_add_f32_e32 v3, v3, v8
	s_waitcnt lgkmcnt(0)
	v_add_f32_e32 v8, v9, v10
	global_atomic_add_f32 v[4:5], v3, off
	global_atomic_add_f32 v[4:5], v8, off offset:4
; __device__ __forceinline__ u32x2 pack8i8(const f32x4 a, const f32x4 b) { return (u32x2){pack4i8(a), pack4i8(b)}; }
; __device__ __forceinline__ u32x4 pack8bf(const f32x4 a, const f32x4 b) { u32x4 w; w.x = cvt_pk_bf16(a[0], a[1]); w.y = cvt_pk_bf16(a[2], a[3]); w.z = cvt_pk_bf16(b[0], b[1]); w.w = cvt_pk_bf16(b[2], b[3]); return w; }
;     __device__ __forceinline__ void operator()(EPI_ARGS) const {
;     ...
;             for (int m = 0; m < 4; ++m) { const int row = row0 + ai * HALF + m * 16; const size_t off = (size_t)row * DM + col0;
;                 float mu = 0.f, rs = 1.f; if constexpr (RESLN) ln_stats(stin, row, mu, rs);
;                 float ss = 0.f, qq = 0.f;
; #pragma unroll
;                 for (int bj = 0; bj < 2; ++bj) { f32x4 r0 = __builtin_nontemporal_load((const f32x4*)(res + off + bj * HALF)), r1 = __builtin_nontemporal_load((const f32x4*)(res + off + bj * HALF + 4));
;                     if constexpr (RESLN) { r0 = (r0 - mu) * rs * gg[bj][0] + bb[bj][0]; r1 = (r1 - mu) * rs * gg[bj][1] + bb[bj][1]; }
;                     const f32x4 y0 = r0 * DN_ALPHA + acc[ai][bj][m][0] * ascale, y1 = r1 * DN_ALPHA + acc[ai][bj][m][1] * ascale;
;                     if constexpr (COPY != 4) { __builtin_nontemporal_store(y0, (f32x4*)(Y + off + bj * HALF)); __builtin_nontemporal_store(y1, (f32x4*)(Y + off + bj * HALF + 4)); }
;                     if constexpr (STATS) { ss += ((y0[0] + y0[1]) + (y0[2] + y0[3])) + ((y1[0] + y1[1]) + (y1[2] + y1[3]));
;                         qq += ((y0[0] * y0[0] + y0[1] * y0[1]) + (y0[2] * y0[2] + y0[3] * y0[3])) + ((y1[0] * y1[0] + y1[1] * y1[1]) + (y1[2] * y1[2] + y1[3] * y1[3])); }
;                     if constexpr (COPY == 1) *(u32x2*)((unsigned char*)copy + off + bj * HALF) = pack8fp8(y0 * cscale, y1 * cscale);
;                     if constexpr (COPY == 3) *(u32x2*)((unsigned char*)copy + off + bj * HALF) = pack8i8(y0 * cscale, y1 * cscale);
;                     if constexpr (COPY == 2 || COPY == 4) *(u32x4*)((bf16_t*)copy + off + bj * HALF) = pack8bf(y0, y1); }
;                 if constexpr (STATS) { ss += __shfl_xor(ss, 16); ss += __shfl_xor(ss, 32); qq += __shfl_xor(qq, 16); qq += __shfl_xor(qq, 32);
;                     if (fq == 0) { unsafeAtomicAdd(stout + 2 * (size_t)row, ss); unsafeAtomicAdd(stout + 2 * (size_t)row + 1, qq); } }
.LBB0_3693:
	s_or_b64 exec, exec, s[40:41]
	v_or_b32_e32 v4, 32, v2
	v_ashrrev_i32_e32 v5, 31, v4
	s_waitcnt lgkmcnt(1)
	v_lshlrev_b64 v[8:9], 11, v[4:5]
	v_lshl_add_u64 v[16:17], v[8:9], 0, v[0:1]
	v_lshlrev_b64 v[18:19], 2, v[16:17]
	v_lshl_add_u64 v[20:21], s[6:7], 0, v[18:19]
	s_waitcnt lgkmcnt(0)
	global_load_dwordx4 v[8:11], v[20:21], off nt
	global_load_dwordx4 v[12:15], v[20:21], off offset:16 nt
	global_load_dwordx4 v[228:231], v[20:21], off offset:512 nt
	global_load_dwordx4 v[232:235], v[20:21], off offset:528 nt
	v_lshl_add_u64 v[24:25], s[12:13], 0, v[16:17]
	v_lshl_add_u64 v[26:27], s[10:11], 0, v[18:19]
	s_waitcnt vmcnt(3)
	v_pk_mul_f32 v[10:11], v[10:11], s[20:21] op_sel_hi:[1,0]
	v_pk_mul_f32 v[8:9], v[8:9], s[20:21] op_sel_hi:[1,0]
	s_waitcnt vmcnt(2)
	v_pk_mul_f32 v[14:15], v[14:15], s[20:21] op_sel_hi:[1,0]
	v_pk_mul_f32 v[12:13], v[12:13], s[20:21] op_sel_hi:[1,0]
	v_pk_fma_f32 v[10:11], v[126:127], s[24:25], v[10:11] op_sel_hi:[1,0,1]
	v_pk_fma_f32 v[8:9], v[124:125], s[24:25], v[8:9] op_sel_hi:[1,0,1]
	v_pk_fma_f32 v[14:15], v[122:123], s[24:25], v[14:15] op_sel_hi:[1,0,1]
	v_pk_fma_f32 v[12:13], v[120:121], s[24:25], v[12:13] op_sel_hi:[1,0,1]
	v_pk_mul_f32 v[16:17], v[10:11], s[26:27] op_sel_hi:[1,0]
	v_pk_mul_f32 v[18:19], v[8:9], s[26:27] op_sel_hi:[1,0]
	v_pk_mul_f32 v[22:23], v[14:15], s[26:27] op_sel_hi:[1,0]
	v_pk_mul_f32 v[28:29], v[12:13], s[26:27] op_sel_hi:[1,0]
	v_med3_f32 v3, v18, s63, v192
	v_med3_f32 v18, v19, s63, v192
	v_med3_f32 v16, v16, s63, v192
	v_med3_f32 v17, v17, s63, v192
	v_med3_f32 v19, v28, s63, v192
	v_med3_f32 v28, v29, s63, v192
	v_med3_f32 v22, v22, s63, v192
	v_med3_f32 v23, v23, s63, v192
	v_add_f32_e32 v3, 0x4b400000, v3
	v_add_f32_e32 v18, 0x4b400000, v18
	v_add_f32_e32 v16, 0x4b400000, v16
	v_add_f32_e32 v17, 0x4b400000, v17
	v_add_f32_e32 v19, 0x4b400000, v19
	v_add_f32_e32 v28, 0x4b400000, v28
	v_add_f32_e32 v22, 0x4b400000, v22
	v_add_f32_e32 v23, 0x4b400000, v23
	v_perm_b32 v3, v18, v3, s64
	v_perm_b32 v16, v17, v16, s65
	v_perm_b32 v17, v28, v19, s64
	v_perm_b32 v18, v23, v22, s65
	v_or_b32_e32 v16, v3, v16
	v_or_b32_e32 v17, v17, v18
	global_store_dwordx4 v[26:27], v[8:11], off nt
	global_store_dwordx4 v[26:27], v[12:15], off offset:16 nt
	global_store_dwordx2 v[24:25], v[16:17], off
	s_waitcnt vmcnt(3)
	s_nop 1
	v_mov_b32_e32 v16, v228
	v_mov_b32_e32 v17, v229
	v_mov_b32_e32 v18, v230
	v_mov_b32_e32 v19, v231
	v_mov_b32_e32 v20, v232
	v_mov_b32_e32 v21, v233
	v_mov_b32_e32 v22, v234
	v_mov_b32_e32 v23, v235
	v_add_f32_e32 v3, v8, v9
	v_add_f32_e32 v28, v10, v11
	v_add_f32_e32 v29, v12, v13
	v_add_f32_e32 v30, v14, v15
	v_mul_f32_e32 v9, v9, v9
	v_mul_f32_e32 v11, v11, v11
	v_mul_f32_e32 v13, v13, v13
	v_mul_f32_e32 v15, v15, v15
	v_fmac_f32_e32 v9, v8, v8
	v_fmac_f32_e32 v11, v10, v10
	v_fmac_f32_e32 v13, v12, v12
	v_fmac_f32_e32 v15, v14, v14
	v_add_f32_e32 v3, v3, v28
	v_add_f32_e32 v28, v29, v30
	v_add_f32_e32 v8, v9, v11
	v_add_f32_e32 v9, v13, v15
	v_add_f32_e32 v3, v3, v28
	v_add_f32_e32 v28, v8, v9
	v_add_f32_e32 v3, 0, v3
	v_pk_mul_f32 v[8:9], v[18:19], s[20:21] op_sel_hi:[1,0]
	v_pk_mul_f32 v[12:13], v[16:17], s[20:21] op_sel_hi:[1,0]
	v_pk_mul_f32 v[14:15], v[22:23], s[20:21] op_sel_hi:[1,0]
	v_pk_mul_f32 v[16:17], v[20:21], s[20:21] op_sel_hi:[1,0]
	v_pk_fma_f32 v[10:11], v[118:119], s[24:25], v[8:9] op_sel_hi:[1,0,1]
	v_pk_fma_f32 v[8:9], v[116:117], s[24:25], v[12:13] op_sel_hi:[1,0,1]
	v_pk_fma_f32 v[14:15], v[114:115], s[24:25], v[14:15] op_sel_hi:[1,0,1]
	v_pk_fma_f32 v[12:13], v[112:113], s[24:25], v[16:17] op_sel_hi:[1,0,1]
	global_store_dwordx4 v[26:27], v[8:11], off offset:512 nt
	global_store_dwordx4 v[26:27], v[12:15], off offset:528 nt
	v_add_f32_e32 v26, v8, v9
	v_add_f32_e32 v27, v10, v11
	v_add_f32_e32 v29, v12, v13
	v_add_f32_e32 v30, v14, v15
	v_mul_f32_e32 v31, v9, v9
	v_mul_f32_e32 v112, v11, v11
	v_mul_f32_e32 v113, v13, v13
	v_mul_f32_e32 v114, v15, v15
	v_pk_mul_f32 v[16:17], v[10:11], s[26:27] op_sel_hi:[1,0]
	v_pk_mul_f32 v[18:19], v[8:9], s[26:27] op_sel_hi:[1,0]
	v_add_f32_e32 v9, v26, v27
	v_add_f32_e32 v11, v29, v30
	v_fmac_f32_e32 v31, v8, v8
	v_fmac_f32_e32 v112, v10, v10
	v_fmac_f32_e32 v113, v12, v12
	v_fmac_f32_e32 v114, v14, v14
	v_med3_f32 v8, v18, s63, v192
	v_add_f32_e32 v9, v9, v11
	v_add_f32_e32 v11, v31, v112
	v_add_f32_e32 v18, v113, v114
	v_med3_f32 v10, v19, s63, v192
	v_add_f32_e32 v3, v3, v9
	v_add_f32_e32 v9, v11, v18
	v_add_f32_e32 v8, 0x4b400000, v8
	v_add_f32_e32 v10, 0x4b400000, v10
	v_add_f32_e32 v9, v28, v9
	v_perm_b32 v8, v10, v8, s64
	v_mov_b32_e32 v10, v3
	s_nop 1
	v_permlane16_swap_b32_e32 v3, v10
	v_mov_b32_e32 v11, v9
	s_nop 1
	v_permlane16_swap_b32_e32 v9, v11
	v_pk_mul_f32 v[22:23], v[12:13], s[26:27] op_sel_hi:[1,0]
	v_med3_f32 v12, v16, s63, v192
	v_med3_f32 v13, v17, s63, v192
	v_add_f32_e32 v12, 0x4b400000, v12
	v_add_f32_e32 v13, 0x4b400000, v13
	v_perm_b32 v12, v13, v12, s65
	s_waitcnt lgkmcnt(0)
	v_add_f32_e32 v3, v3, v10
	s_waitcnt lgkmcnt(0)
	v_add_f32_e32 v9, v9, v11
	v_pk_mul_f32 v[20:21], v[14:15], s[26:27] op_sel_hi:[1,0]
	v_or_b32_e32 v12, v8, v12
	v_mov_b32_e32 v8, v3
	s_nop 1
	v_permlane32_swap_b32_e32 v3, v8
	v_mov_b32_e32 v10, v9
	s_nop 1
	v_permlane32_swap_b32_e32 v9, v10
	v_med3_f32 v14, v22, s63, v192
	v_med3_f32 v15, v23, s63, v192
	v_med3_f32 v16, v20, s63, v192
	v_med3_f32 v17, v21, s63, v192
	v_add_f32_e32 v14, 0x4b400000, v14
	v_add_f32_e32 v15, 0x4b400000, v15
	v_add_f32_e32 v16, 0x4b400000, v16
	v_add_f32_e32 v17, 0x4b400000, v17
	v_perm_b32 v11, v15, v14, s64
	v_perm_b32 v13, v17, v16, s65
	v_or_b32_e32 v13, v11, v13
	global_store_dwordx2 v[24:25], v[12:13], off offset:128
	s_and_saveexec_b64 s[40:41], s[2:3]
	s_cbranch_execz .LBB0_3695
	v_lshl_add_u64 v[4:5], v[4:5], 3, s[14:15]
	s_waitcnt lgkmcnt(0)
	v_add_f32_e32 v3, v3, v8
	s_waitcnt lgkmcnt(0)
	v_add_f32_e32 v8, v9, v10
	global_atomic_add_f32 v[4:5], v3, off
	global_atomic_add_f32 v[4:5], v8, off offset:4
; __device__ __forceinline__ u32x2 pack8i8(const f32x4 a, const f32x4 b) { return (u32x2){pack4i8(a), pack4i8(b)}; }
; __device__ __forceinline__ u32x4 pack8bf(const f32x4 a, const f32x4 b) { u32x4 w; w.x = cvt_pk_bf16(a[0], a[1]); w.y = cvt_pk_bf16(a[2], a[3]); w.z = cvt_pk_bf16(b[0], b[1]); w.w = cvt_pk_bf16(b[2], b[3]); return w; }
;     __device__ __forceinline__ void operator()(EPI_ARGS) const {
;     ...
;             for (int m = 0; m < 4; ++m) { const int row = row0 + ai * HALF + m * 16; const size_t off = (size_t)row * DM + col0;
;                 float mu = 0.f, rs = 1.f; if constexpr (RESLN) ln_stats(stin, row, mu, rs);
;                 float ss = 0.f, qq = 0.f;
; #pragma unroll
;                 for (int bj = 0; bj < 2; ++bj) { f32x4 r0 = __builtin_nontemporal_load((const f32x4*)(res + off + bj * HALF)), r1 = __builtin_nontemporal_load((const f32x4*)(res + off + bj * HALF + 4));
;                     if constexpr (RESLN) { r0 = (r0 - mu) * rs * gg[bj][0] + bb[bj][0]; r1 = (r1 - mu) * rs * gg[bj][1] + bb[bj][1]; }
;                     const f32x4 y0 = r0 * DN_ALPHA + acc[ai][bj][m][0] * ascale, y1 = r1 * DN_ALPHA + acc[ai][bj][m][1] * ascale;
;                     if constexpr (COPY != 4) { __builtin_nontemporal_store(y0, (f32x4*)(Y + off + bj * HALF)); __builtin_nontemporal_store(y1, (f32x4*)(Y + off + bj * HALF + 4)); }
;                     if constexpr (STATS) { ss += ((y0[0] + y0[1]) + (y0[2] + y0[3])) + ((y1[0] + y1[1]) + (y1[2] + y1[3]));
;                         qq += ((y0[0] * y0[0] + y0[1] * y0[1]) + (y0[2] * y0[2] + y0[3] * y0[3])) + ((y1[0] * y1[0] + y1[1] * y1[1]) + (y1[2] * y1[2] + y1[3] * y1[3])); }
;                     if constexpr (COPY == 1) *(u32x2*)((unsigned char*)copy + off + bj * HALF) = pack8fp8(y0 * cscale, y1 * cscale);
;                     if constexpr (COPY == 3) *(u32x2*)((unsigned char*)copy + off + bj * HALF) = pack8i8(y0 * cscale, y1 * cscale);
;                     if constexpr (COPY == 2 || COPY == 4) *(u32x4*)((bf16_t*)copy + off + bj * HALF) = pack8bf(y0, y1); }
;                 if constexpr (STATS) { ss += __shfl_xor(ss, 16); ss += __shfl_xor(ss, 32); qq += __shfl_xor(qq, 16); qq += __shfl_xor(qq, 32);
;                     if (fq == 0) { unsafeAtomicAdd(stout + 2 * (size_t)row, ss); unsafeAtomicAdd(stout + 2 * (size_t)row + 1, qq); } }
.LBB0_3695:
	s_or_b64 exec, exec, s[40:41]
	v_or_b32_e32 v4, 48, v2
	v_ashrrev_i32_e32 v5, 31, v4
	s_waitcnt lgkmcnt(1)
	v_lshlrev_b64 v[8:9], 11, v[4:5]
	v_lshl_add_u64 v[16:17], v[8:9], 0, v[0:1]
	v_lshlrev_b64 v[18:19], 2, v[16:17]
	v_lshl_add_u64 v[20:21], s[6:7], 0, v[18:19]
	s_waitcnt lgkmcnt(0)
	global_load_dwordx4 v[8:11], v[20:21], off nt
	global_load_dwordx4 v[12:15], v[20:21], off offset:16 nt
	global_load_dwordx4 v[228:231], v[20:21], off offset:512 nt
	global_load_dwordx4 v[232:235], v[20:21], off offset:528 nt
	v_lshl_add_u64 v[24:25], s[12:13], 0, v[16:17]
	v_lshl_add_u64 v[26:27], s[10:11], 0, v[18:19]
	s_waitcnt vmcnt(3)
	v_pk_mul_f32 v[10:11], v[10:11], s[20:21] op_sel_hi:[1,0]
	v_pk_mul_f32 v[8:9], v[8:9], s[20:21] op_sel_hi:[1,0]
	s_waitcnt vmcnt(2)
	v_pk_mul_f32 v[14:15], v[14:15], s[20:21] op_sel_hi:[1,0]
	v_pk_mul_f32 v[12:13], v[12:13], s[20:21] op_sel_hi:[1,0]
	v_pk_fma_f32 v[10:11], v[110:111], s[24:25], v[10:11] op_sel_hi:[1,0,1]
	v_pk_fma_f32 v[8:9], v[108:109], s[24:25], v[8:9] op_sel_hi:[1,0,1]
	v_pk_fma_f32 v[14:15], v[106:107], s[24:25], v[14:15] op_sel_hi:[1,0,1]
	v_pk_fma_f32 v[12:13], v[104:105], s[24:25], v[12:13] op_sel_hi:[1,0,1]
	v_pk_mul_f32 v[16:17], v[10:11], s[26:27] op_sel_hi:[1,0]
	v_pk_mul_f32 v[18:19], v[8:9], s[26:27] op_sel_hi:[1,0]
	v_pk_mul_f32 v[22:23], v[14:15], s[26:27] op_sel_hi:[1,0]
	v_pk_mul_f32 v[28:29], v[12:13], s[26:27] op_sel_hi:[1,0]
	v_med3_f32 v3, v18, s63, v192
	v_med3_f32 v18, v19, s63, v192
	v_med3_f32 v16, v16, s63, v192
	v_med3_f32 v17, v17, s63, v192
	v_med3_f32 v19, v28, s63, v192
	v_med3_f32 v28, v29, s63, v192
	v_med3_f32 v22, v22, s63, v192
	v_med3_f32 v23, v23, s63, v192
	v_add_f32_e32 v3, 0x4b400000, v3
	v_add_f32_e32 v18, 0x4b400000, v18
	v_add_f32_e32 v16, 0x4b400000, v16
	v_add_f32_e32 v17, 0x4b400000, v17
	v_add_f32_e32 v19, 0x4b400000, v19
	v_add_f32_e32 v28, 0x4b400000, v28
	v_add_f32_e32 v22, 0x4b400000, v22
	v_add_f32_e32 v23, 0x4b400000, v23
	v_perm_b32 v3, v18, v3, s64
	v_perm_b32 v16, v17, v16, s65
	v_perm_b32 v17, v28, v19, s64
	v_perm_b32 v18, v23, v22, s65
	v_or_b32_e32 v16, v3, v16
	v_or_b32_e32 v17, v17, v18
	global_store_dwordx4 v[26:27], v[8:11], off nt
	global_store_dwordx4 v[26:27], v[12:15], off offset:16 nt
	global_store_dwordx2 v[24:25], v[16:17], off
	s_waitcnt vmcnt(3)
	s_nop 1
	v_mov_b32_e32 v16, v228
	v_mov_b32_e32 v17, v229
	v_mov_b32_e32 v18, v230
	v_mov_b32_e32 v19, v231
	v_mov_b32_e32 v20, v232
	v_mov_b32_e32 v21, v233
	v_mov_b32_e32 v22, v234
	v_mov_b32_e32 v23, v235
	v_add_f32_e32 v3, v8, v9
	v_add_f32_e32 v28, v10, v11
	v_add_f32_e32 v29, v12, v13
	v_add_f32_e32 v30, v14, v15
	v_mul_f32_e32 v9, v9, v9
	v_mul_f32_e32 v11, v11, v11
	v_mul_f32_e32 v13, v13, v13
	v_mul_f32_e32 v15, v15, v15
	v_fmac_f32_e32 v9, v8, v8
	v_fmac_f32_e32 v11, v10, v10
	v_fmac_f32_e32 v13, v12, v12
	v_fmac_f32_e32 v15, v14, v14
	v_add_f32_e32 v3, v3, v28
	v_add_f32_e32 v28, v29, v30
	v_add_f32_e32 v8, v9, v11
	v_add_f32_e32 v9, v13, v15
	v_add_f32_e32 v3, v3, v28
	v_add_f32_e32 v28, v8, v9
	v_add_f32_e32 v3, 0, v3
	v_pk_mul_f32 v[8:9], v[18:19], s[20:21] op_sel_hi:[1,0]
	v_pk_mul_f32 v[12:13], v[16:17], s[20:21] op_sel_hi:[1,0]
	v_pk_mul_f32 v[14:15], v[22:23], s[20:21] op_sel_hi:[1,0]
	v_pk_mul_f32 v[16:17], v[20:21], s[20:21] op_sel_hi:[1,0]
	v_pk_fma_f32 v[10:11], v[102:103], s[24:25], v[8:9] op_sel_hi:[1,0,1]
	v_pk_fma_f32 v[8:9], v[100:101], s[24:25], v[12:13] op_sel_hi:[1,0,1]
	v_pk_fma_f32 v[14:15], v[98:99], s[24:25], v[14:15] op_sel_hi:[1,0,1]
	v_pk_fma_f32 v[12:13], v[96:97], s[24:25], v[16:17] op_sel_hi:[1,0,1]
	global_store_dwordx4 v[26:27], v[8:11], off offset:512 nt
	global_store_dwordx4 v[26:27], v[12:15], off offset:528 nt
	v_add_f32_e32 v26, v8, v9
	v_add_f32_e32 v27, v10, v11
	v_add_f32_e32 v29, v12, v13
	v_add_f32_e32 v30, v14, v15
	v_mul_f32_e32 v31, v9, v9
	v_mul_f32_e32 v96, v11, v11
	v_mul_f32_e32 v97, v13, v13
	v_mul_f32_e32 v98, v15, v15
	v_pk_mul_f32 v[16:17], v[10:11], s[26:27] op_sel_hi:[1,0]
	v_pk_mul_f32 v[18:19], v[8:9], s[26:27] op_sel_hi:[1,0]
	v_add_f32_e32 v9, v26, v27
	v_add_f32_e32 v11, v29, v30
	v_fmac_f32_e32 v31, v8, v8
	v_fmac_f32_e32 v96, v10, v10
	v_fmac_f32_e32 v97, v12, v12
	v_fmac_f32_e32 v98, v14, v14
	v_med3_f32 v8, v18, s63, v192
	v_add_f32_e32 v9, v9, v11
	v_add_f32_e32 v11, v31, v96
	v_add_f32_e32 v18, v97, v98
	v_med3_f32 v10, v19, s63, v192
	v_add_f32_e32 v3, v3, v9
	v_add_f32_e32 v9, v11, v18
	v_add_f32_e32 v8, 0x4b400000, v8
	v_add_f32_e32 v10, 0x4b400000, v10
	v_add_f32_e32 v9, v28, v9
	v_perm_b32 v8, v10, v8, s64
	v_mov_b32_e32 v10, v3
	s_nop 1
	v_permlane16_swap_b32_e32 v3, v10
	v_mov_b32_e32 v11, v9
	s_nop 1
	v_permlane16_swap_b32_e32 v9, v11
	v_pk_mul_f32 v[22:23], v[12:13], s[26:27] op_sel_hi:[1,0]
	v_med3_f32 v12, v16, s63, v192
	v_med3_f32 v13, v17, s63, v192
	v_add_f32_e32 v12, 0x4b400000, v12
	v_add_f32_e32 v13, 0x4b400000, v13
	v_perm_b32 v12, v13, v12, s65
	s_waitcnt lgkmcnt(0)
	v_add_f32_e32 v3, v3, v10
	s_waitcnt lgkmcnt(0)
	v_add_f32_e32 v9, v9, v11
	v_pk_mul_f32 v[20:21], v[14:15], s[26:27] op_sel_hi:[1,0]
	v_or_b32_e32 v12, v8, v12
	v_mov_b32_e32 v8, v3
	s_nop 1
	v_permlane32_swap_b32_e32 v3, v8
	v_mov_b32_e32 v10, v9
	s_nop 1
	v_permlane32_swap_b32_e32 v9, v10
	v_med3_f32 v14, v22, s63, v192
	v_med3_f32 v15, v23, s63, v192
	v_med3_f32 v16, v20, s63, v192
	v_med3_f32 v17, v21, s63, v192
	v_add_f32_e32 v14, 0x4b400000, v14
	v_add_f32_e32 v15, 0x4b400000, v15
	v_add_f32_e32 v16, 0x4b400000, v16
	v_add_f32_e32 v17, 0x4b400000, v17
	v_perm_b32 v11, v15, v14, s64
	v_perm_b32 v13, v17, v16, s65
	v_or_b32_e32 v13, v11, v13
	global_store_dwordx2 v[24:25], v[12:13], off offset:128
	s_and_saveexec_b64 s[40:41], s[2:3]
	s_cbranch_execz .LBB0_3697
	v_lshl_add_u64 v[4:5], v[4:5], 3, s[14:15]
	s_waitcnt lgkmcnt(0)
	v_add_f32_e32 v3, v3, v8
	s_waitcnt lgkmcnt(0)
	v_add_f32_e32 v8, v9, v10
	global_atomic_add_f32 v[4:5], v3, off
	global_atomic_add_f32 v[4:5], v8, off offset:4
; __device__ __forceinline__ u32x2 pack8i8(const f32x4 a, const f32x4 b) { return (u32x2){pack4i8(a), pack4i8(b)}; }
; __device__ __forceinline__ u32x4 pack8bf(const f32x4 a, const f32x4 b) { u32x4 w; w.x = cvt_pk_bf16(a[0], a[1]); w.y = cvt_pk_bf16(a[2], a[3]); w.z = cvt_pk_bf16(b[0], b[1]); w.w = cvt_pk_bf16(b[2], b[3]); return w; }
;     __device__ __forceinline__ void operator()(EPI_ARGS) const {
;     ...
;             for (int m = 0; m < 4; ++m) { const int row = row0 + ai * HALF + m * 16; const size_t off = (size_t)row * DM + col0;
;                 float mu = 0.f, rs = 1.f; if constexpr (RESLN) ln_stats(stin, row, mu, rs);
;                 float ss = 0.f, qq = 0.f;
; #pragma unroll
;                 for (int bj = 0; bj < 2; ++bj) { f32x4 r0 = __builtin_nontemporal_load((const f32x4*)(res + off + bj * HALF)), r1 = __builtin_nontemporal_load((const f32x4*)(res + off + bj * HALF + 4));
;                     if constexpr (RESLN) { r0 = (r0 - mu) * rs * gg[bj][0] + bb[bj][0]; r1 = (r1 - mu) * rs * gg[bj][1] + bb[bj][1]; }
;                     const f32x4 y0 = r0 * DN_ALPHA + acc[ai][bj][m][0] * ascale, y1 = r1 * DN_ALPHA + acc[ai][bj][m][1] * ascale;
;                     if constexpr (COPY != 4) { __builtin_nontemporal_store(y0, (f32x4*)(Y + off + bj * HALF)); __builtin_nontemporal_store(y1, (f32x4*)(Y + off + bj * HALF + 4)); }
;                     if constexpr (STATS) { ss += ((y0[0] + y0[1]) + (y0[2] + y0[3])) + ((y1[0] + y1[1]) + (y1[2] + y1[3]));
;                         qq += ((y0[0] * y0[0] + y0[1] * y0[1]) + (y0[2] * y0[2] + y0[3] * y0[3])) + ((y1[0] * y1[0] + y1[1] * y1[1]) + (y1[2] * y1[2] + y1[3] * y1[3])); }
;                     if constexpr (COPY == 1) *(u32x2*)((unsigned char*)copy + off + bj * HALF) = pack8fp8(y0 * cscale, y1 * cscale);
;                     if constexpr (COPY == 3) *(u32x2*)((unsigned char*)copy + off + bj * HALF) = pack8i8(y0 * cscale, y1 * cscale);
;                     if constexpr (COPY == 2 || COPY == 4) *(u32x4*)((bf16_t*)copy + off + bj * HALF) = pack8bf(y0, y1); }
;                 if constexpr (STATS) { ss += __shfl_xor(ss, 16); ss += __shfl_xor(ss, 32); qq += __shfl_xor(qq, 16); qq += __shfl_xor(qq, 32);
;                     if (fq == 0) { unsafeAtomicAdd(stout + 2 * (size_t)row, ss); unsafeAtomicAdd(stout + 2 * (size_t)row + 1, qq); } }
.LBB0_3697:
	s_or_b64 exec, exec, s[40:41]
	v_add_u32_e32 v4, 0x80, v2
	v_ashrrev_i32_e32 v5, 31, v4
	s_waitcnt lgkmcnt(1)
	v_lshlrev_b64 v[8:9], 11, v[4:5]
	v_lshl_add_u64 v[16:17], v[8:9], 0, v[0:1]
	v_lshlrev_b64 v[18:19], 2, v[16:17]
	v_lshl_add_u64 v[20:21], s[6:7], 0, v[18:19]
	s_waitcnt lgkmcnt(0)
	global_load_dwordx4 v[8:11], v[20:21], off nt
	global_load_dwordx4 v[12:15], v[20:21], off offset:16 nt
	global_load_dwordx4 v[228:231], v[20:21], off offset:512 nt
	global_load_dwordx4 v[232:235], v[20:21], off offset:528 nt
	v_lshl_add_u64 v[24:25], s[12:13], 0, v[16:17]
	v_lshl_add_u64 v[26:27], s[10:11], 0, v[18:19]
	s_waitcnt vmcnt(3)
	v_pk_mul_f32 v[10:11], v[10:11], s[20:21] op_sel_hi:[1,0]
	v_pk_mul_f32 v[8:9], v[8:9], s[20:21] op_sel_hi:[1,0]
	s_waitcnt vmcnt(2)
	v_pk_mul_f32 v[14:15], v[14:15], s[20:21] op_sel_hi:[1,0]
	v_pk_mul_f32 v[12:13], v[12:13], s[20:21] op_sel_hi:[1,0]
	v_pk_fma_f32 v[10:11], v[94:95], s[24:25], v[10:11] op_sel_hi:[1,0,1]
	v_pk_fma_f32 v[8:9], v[92:93], s[24:25], v[8:9] op_sel_hi:[1,0,1]
	v_pk_fma_f32 v[14:15], v[90:91], s[24:25], v[14:15] op_sel_hi:[1,0,1]
	v_pk_fma_f32 v[12:13], v[88:89], s[24:25], v[12:13] op_sel_hi:[1,0,1]
	v_pk_mul_f32 v[16:17], v[10:11], s[26:27] op_sel_hi:[1,0]
	v_pk_mul_f32 v[18:19], v[8:9], s[26:27] op_sel_hi:[1,0]
	v_pk_mul_f32 v[22:23], v[14:15], s[26:27] op_sel_hi:[1,0]
	v_pk_mul_f32 v[28:29], v[12:13], s[26:27] op_sel_hi:[1,0]
	v_med3_f32 v3, v18, s63, v192
	v_med3_f32 v18, v19, s63, v192
	v_med3_f32 v16, v16, s63, v192
	v_med3_f32 v17, v17, s63, v192
	v_med3_f32 v19, v28, s63, v192
	v_med3_f32 v28, v29, s63, v192
	v_med3_f32 v22, v22, s63, v192
	v_med3_f32 v23, v23, s63, v192
	v_add_f32_e32 v3, 0x4b400000, v3
	v_add_f32_e32 v18, 0x4b400000, v18
	v_add_f32_e32 v16, 0x4b400000, v16
	v_add_f32_e32 v17, 0x4b400000, v17
	v_add_f32_e32 v19, 0x4b400000, v19
	v_add_f32_e32 v28, 0x4b400000, v28
	v_add_f32_e32 v22, 0x4b400000, v22
	v_add_f32_e32 v23, 0x4b400000, v23
	v_perm_b32 v3, v18, v3, s64
	v_perm_b32 v16, v17, v16, s65
	v_perm_b32 v17, v28, v19, s64
	v_perm_b32 v18, v23, v22, s65
	v_or_b32_e32 v16, v3, v16
	v_or_b32_e32 v17, v17, v18
	global_store_dwordx4 v[26:27], v[8:11], off nt
	global_store_dwordx4 v[26:27], v[12:15], off offset:16 nt
	global_store_dwordx2 v[24:25], v[16:17], off
	s_waitcnt vmcnt(3)
	s_nop 1
	v_mov_b32_e32 v16, v228
	v_mov_b32_e32 v17, v229
	v_mov_b32_e32 v18, v230
	v_mov_b32_e32 v19, v231
	v_mov_b32_e32 v20, v232
	v_mov_b32_e32 v21, v233
	v_mov_b32_e32 v22, v234
	v_mov_b32_e32 v23, v235
	v_add_f32_e32 v3, v8, v9
	v_add_f32_e32 v28, v10, v11
	v_add_f32_e32 v29, v12, v13
	v_add_f32_e32 v30, v14, v15
	v_mul_f32_e32 v9, v9, v9
	v_mul_f32_e32 v11, v11, v11
	v_mul_f32_e32 v13, v13, v13
	v_mul_f32_e32 v15, v15, v15
	v_fmac_f32_e32 v9, v8, v8
	v_fmac_f32_e32 v11, v10, v10
	v_fmac_f32_e32 v13, v12, v12
	v_fmac_f32_e32 v15, v14, v14
	v_add_f32_e32 v3, v3, v28
	v_add_f32_e32 v28, v29, v30
	v_add_f32_e32 v8, v9, v11
	v_add_f32_e32 v9, v13, v15
	v_add_f32_e32 v3, v3, v28
	v_add_f32_e32 v28, v8, v9
	v_add_f32_e32 v3, 0, v3
	v_pk_mul_f32 v[8:9], v[18:19], s[20:21] op_sel_hi:[1,0]
	v_pk_mul_f32 v[12:13], v[16:17], s[20:21] op_sel_hi:[1,0]
	v_pk_mul_f32 v[14:15], v[22:23], s[20:21] op_sel_hi:[1,0]
	v_pk_mul_f32 v[16:17], v[20:21], s[20:21] op_sel_hi:[1,0]
	v_pk_fma_f32 v[10:11], v[86:87], s[24:25], v[8:9] op_sel_hi:[1,0,1]
	v_pk_fma_f32 v[8:9], v[84:85], s[24:25], v[12:13] op_sel_hi:[1,0,1]
	v_pk_fma_f32 v[14:15], v[82:83], s[24:25], v[14:15] op_sel_hi:[1,0,1]
	v_pk_fma_f32 v[12:13], v[80:81], s[24:25], v[16:17] op_sel_hi:[1,0,1]
	global_store_dwordx4 v[26:27], v[8:11], off offset:512 nt
	global_store_dwordx4 v[26:27], v[12:15], off offset:528 nt
	v_add_f32_e32 v26, v8, v9
	v_add_f32_e32 v27, v10, v11
	v_add_f32_e32 v29, v12, v13
	v_add_f32_e32 v30, v14, v15
	v_mul_f32_e32 v31, v9, v9
	v_mul_f32_e32 v80, v11, v11
	v_mul_f32_e32 v81, v13, v13
	v_mul_f32_e32 v82, v15, v15
	v_pk_mul_f32 v[16:17], v[10:11], s[26:27] op_sel_hi:[1,0]
	v_pk_mul_f32 v[18:19], v[8:9], s[26:27] op_sel_hi:[1,0]
	v_add_f32_e32 v9, v26, v27
	v_add_f32_e32 v11, v29, v30
	v_fmac_f32_e32 v31, v8, v8
	v_fmac_f32_e32 v80, v10, v10
	v_fmac_f32_e32 v81, v12, v12
	v_fmac_f32_e32 v82, v14, v14
	v_med3_f32 v8, v18, s63, v192
	v_add_f32_e32 v9, v9, v11
	v_add_f32_e32 v11, v31, v80
	v_add_f32_e32 v18, v81, v82
	v_med3_f32 v10, v19, s63, v192
	v_add_f32_e32 v3, v3, v9
	v_add_f32_e32 v9, v11, v18
	v_add_f32_e32 v8, 0x4b400000, v8
	v_add_f32_e32 v10, 0x4b400000, v10
	v_add_f32_e32 v9, v28, v9
	v_perm_b32 v8, v10, v8, s64
	v_mov_b32_e32 v10, v3
	s_nop 1
	v_permlane16_swap_b32_e32 v3, v10
	v_mov_b32_e32 v11, v9
	s_nop 1
	v_permlane16_swap_b32_e32 v9, v11
	v_pk_mul_f32 v[22:23], v[12:13], s[26:27] op_sel_hi:[1,0]
	v_med3_f32 v12, v16, s63, v192
	v_med3_f32 v13, v17, s63, v192
	v_add_f32_e32 v12, 0x4b400000, v12
	v_add_f32_e32 v13, 0x4b400000, v13
	v_perm_b32 v12, v13, v12, s65
	s_waitcnt lgkmcnt(0)
	v_add_f32_e32 v3, v3, v10
	s_waitcnt lgkmcnt(0)
	v_add_f32_e32 v9, v9, v11
	v_pk_mul_f32 v[20:21], v[14:15], s[26:27] op_sel_hi:[1,0]
	v_or_b32_e32 v12, v8, v12
	v_mov_b32_e32 v8, v3
	s_nop 1
	v_permlane32_swap_b32_e32 v3, v8
	v_mov_b32_e32 v10, v9
	s_nop 1
	v_permlane32_swap_b32_e32 v9, v10
	v_med3_f32 v14, v22, s63, v192
	v_med3_f32 v15, v23, s63, v192
	v_med3_f32 v16, v20, s63, v192
	v_med3_f32 v17, v21, s63, v192
	v_add_f32_e32 v14, 0x4b400000, v14
	v_add_f32_e32 v15, 0x4b400000, v15
	v_add_f32_e32 v16, 0x4b400000, v16
	v_add_f32_e32 v17, 0x4b400000, v17
	v_perm_b32 v11, v15, v14, s64
	v_perm_b32 v13, v17, v16, s65
	v_or_b32_e32 v13, v11, v13
	global_store_dwordx2 v[24:25], v[12:13], off offset:128
	s_and_saveexec_b64 s[40:41], s[2:3]
	s_cbranch_execz .LBB0_3699
	v_lshl_add_u64 v[4:5], v[4:5], 3, s[14:15]
	s_waitcnt lgkmcnt(0)
	v_add_f32_e32 v3, v3, v8
	s_waitcnt lgkmcnt(0)
	v_add_f32_e32 v8, v9, v10
	global_atomic_add_f32 v[4:5], v3, off
	global_atomic_add_f32 v[4:5], v8, off offset:4
; __device__ __forceinline__ u32x2 pack8i8(const f32x4 a, const f32x4 b) { return (u32x2){pack4i8(a), pack4i8(b)}; }
; __device__ __forceinline__ u32x4 pack8bf(const f32x4 a, const f32x4 b) { u32x4 w; w.x = cvt_pk_bf16(a[0], a[1]); w.y = cvt_pk_bf16(a[2], a[3]); w.z = cvt_pk_bf16(b[0], b[1]); w.w = cvt_pk_bf16(b[2], b[3]); return w; }
;     __device__ __forceinline__ void operator()(EPI_ARGS) const {
;     ...
;             for (int m = 0; m < 4; ++m) { const int row = row0 + ai * HALF + m * 16; const size_t off = (size_t)row * DM + col0;
;                 float mu = 0.f, rs = 1.f; if constexpr (RESLN) ln_stats(stin, row, mu, rs);
;                 float ss = 0.f, qq = 0.f;
; #pragma unroll
;                 for (int bj = 0; bj < 2; ++bj) { f32x4 r0 = __builtin_nontemporal_load((const f32x4*)(res + off + bj * HALF)), r1 = __builtin_nontemporal_load((const f32x4*)(res + off + bj * HALF + 4));
;                     if constexpr (RESLN) { r0 = (r0 - mu) * rs * gg[bj][0] + bb[bj][0]; r1 = (r1 - mu) * rs * gg[bj][1] + bb[bj][1]; }
;                     const f32x4 y0 = r0 * DN_ALPHA + acc[ai][bj][m][0] * ascale, y1 = r1 * DN_ALPHA + acc[ai][bj][m][1] * ascale;
;                     if constexpr (COPY != 4) { __builtin_nontemporal_store(y0, (f32x4*)(Y + off + bj * HALF)); __builtin_nontemporal_store(y1, (f32x4*)(Y + off + bj * HALF + 4)); }
;                     if constexpr (STATS) { ss += ((y0[0] + y0[1]) + (y0[2] + y0[3])) + ((y1[0] + y1[1]) + (y1[2] + y1[3]));
;                         qq += ((y0[0] * y0[0] + y0[1] * y0[1]) + (y0[2] * y0[2] + y0[3] * y0[3])) + ((y1[0] * y1[0] + y1[1] * y1[1]) + (y1[2] * y1[2] + y1[3] * y1[3])); }
;                     if constexpr (COPY == 1) *(u32x2*)((unsigned char*)copy + off + bj * HALF) = pack8fp8(y0 * cscale, y1 * cscale);
;                     if constexpr (COPY == 3) *(u32x2*)((unsigned char*)copy + off + bj * HALF) = pack8i8(y0 * cscale, y1 * cscale);
;                     if constexpr (COPY == 2 || COPY == 4) *(u32x4*)((bf16_t*)copy + off + bj * HALF) = pack8bf(y0, y1); }
;                 if constexpr (STATS) { ss += __shfl_xor(ss, 16); ss += __shfl_xor(ss, 32); qq += __shfl_xor(qq, 16); qq += __shfl_xor(qq, 32);
;                     if (fq == 0) { unsafeAtomicAdd(stout + 2 * (size_t)row, ss); unsafeAtomicAdd(stout + 2 * (size_t)row + 1, qq); } }
.LBB0_3699:
	s_or_b64 exec, exec, s[40:41]
	v_add_u32_e32 v4, 0x90, v2
	v_ashrrev_i32_e32 v5, 31, v4
	s_waitcnt lgkmcnt(1)
	v_lshlrev_b64 v[8:9], 11, v[4:5]
	v_lshl_add_u64 v[16:17], v[8:9], 0, v[0:1]
	v_lshlrev_b64 v[18:19], 2, v[16:17]
	v_lshl_add_u64 v[20:21], s[6:7], 0, v[18:19]
	s_waitcnt lgkmcnt(0)
	global_load_dwordx4 v[8:11], v[20:21], off nt
	global_load_dwordx4 v[12:15], v[20:21], off offset:16 nt
	global_load_dwordx4 v[228:231], v[20:21], off offset:512 nt
	global_load_dwordx4 v[232:235], v[20:21], off offset:528 nt
	v_lshl_add_u64 v[24:25], s[12:13], 0, v[16:17]
	v_lshl_add_u64 v[26:27], s[10:11], 0, v[18:19]
	s_waitcnt vmcnt(3)
	v_pk_mul_f32 v[10:11], v[10:11], s[20:21] op_sel_hi:[1,0]
	v_pk_mul_f32 v[8:9], v[8:9], s[20:21] op_sel_hi:[1,0]
	s_waitcnt vmcnt(2)
	v_pk_mul_f32 v[14:15], v[14:15], s[20:21] op_sel_hi:[1,0]
	v_pk_mul_f32 v[12:13], v[12:13], s[20:21] op_sel_hi:[1,0]
	v_pk_fma_f32 v[10:11], v[78:79], s[24:25], v[10:11] op_sel_hi:[1,0,1]
	v_pk_fma_f32 v[8:9], v[76:77], s[24:25], v[8:9] op_sel_hi:[1,0,1]
	v_pk_fma_f32 v[14:15], v[74:75], s[24:25], v[14:15] op_sel_hi:[1,0,1]
	v_pk_fma_f32 v[12:13], v[72:73], s[24:25], v[12:13] op_sel_hi:[1,0,1]
	v_pk_mul_f32 v[16:17], v[10:11], s[26:27] op_sel_hi:[1,0]
	v_pk_mul_f32 v[18:19], v[8:9], s[26:27] op_sel_hi:[1,0]
	v_pk_mul_f32 v[22:23], v[14:15], s[26:27] op_sel_hi:[1,0]
	v_pk_mul_f32 v[28:29], v[12:13], s[26:27] op_sel_hi:[1,0]
	v_med3_f32 v3, v18, s63, v192
	v_med3_f32 v18, v19, s63, v192
	v_med3_f32 v16, v16, s63, v192
	v_med3_f32 v17, v17, s63, v192
	v_med3_f32 v19, v28, s63, v192
	v_med3_f32 v28, v29, s63, v192
	v_med3_f32 v22, v22, s63, v192
	v_med3_f32 v23, v23, s63, v192
	v_add_f32_e32 v3, 0x4b400000, v3
	v_add_f32_e32 v18, 0x4b400000, v18
	v_add_f32_e32 v16, 0x4b400000, v16
	v_add_f32_e32 v17, 0x4b400000, v17
	v_add_f32_e32 v19, 0x4b400000, v19
	v_add_f32_e32 v28, 0x4b400000, v28
	v_add_f32_e32 v22, 0x4b400000, v22
	v_add_f32_e32 v23, 0x4b400000, v23
	v_perm_b32 v3, v18, v3, s64
	v_perm_b32 v16, v17, v16, s65
	v_perm_b32 v17, v28, v19, s64
	v_perm_b32 v18, v23, v22, s65
	v_or_b32_e32 v16, v3, v16
	v_or_b32_e32 v17, v17, v18
	global_store_dwordx4 v[26:27], v[8:11], off nt
	global_store_dwordx4 v[26:27], v[12:15], off offset:16 nt
	global_store_dwordx2 v[24:25], v[16:17], off
	s_waitcnt vmcnt(3)
	s_nop 1
	v_mov_b32_e32 v16, v228
	v_mov_b32_e32 v17, v229
	v_mov_b32_e32 v18, v230
	v_mov_b32_e32 v19, v231
	v_mov_b32_e32 v20, v232
	v_mov_b32_e32 v21, v233
	v_mov_b32_e32 v22, v234
	v_mov_b32_e32 v23, v235
	v_add_f32_e32 v3, v8, v9
	v_add_f32_e32 v28, v10, v11
	v_add_f32_e32 v29, v12, v13
	v_add_f32_e32 v30, v14, v15
	v_mul_f32_e32 v9, v9, v9
	v_mul_f32_e32 v11, v11, v11
	v_mul_f32_e32 v13, v13, v13
	v_mul_f32_e32 v15, v15, v15
	v_fmac_f32_e32 v9, v8, v8
	v_fmac_f32_e32 v11, v10, v10
	v_fmac_f32_e32 v13, v12, v12
	v_fmac_f32_e32 v15, v14, v14
	v_add_f32_e32 v3, v3, v28
	v_add_f32_e32 v28, v29, v30
	v_add_f32_e32 v8, v9, v11
	v_add_f32_e32 v9, v13, v15
	v_add_f32_e32 v3, v3, v28
	v_add_f32_e32 v28, v8, v9
	v_add_f32_e32 v3, 0, v3
	v_pk_mul_f32 v[8:9], v[18:19], s[20:21] op_sel_hi:[1,0]
	v_pk_mul_f32 v[12:13], v[16:17], s[20:21] op_sel_hi:[1,0]
	v_pk_mul_f32 v[14:15], v[22:23], s[20:21] op_sel_hi:[1,0]
	v_pk_mul_f32 v[16:17], v[20:21], s[20:21] op_sel_hi:[1,0]
	v_pk_fma_f32 v[10:11], v[70:71], s[24:25], v[8:9] op_sel_hi:[1,0,1]
	v_pk_fma_f32 v[8:9], v[68:69], s[24:25], v[12:13] op_sel_hi:[1,0,1]
	v_pk_fma_f32 v[14:15], v[66:67], s[24:25], v[14:15] op_sel_hi:[1,0,1]
	v_pk_fma_f32 v[12:13], v[64:65], s[24:25], v[16:17] op_sel_hi:[1,0,1]
	global_store_dwordx4 v[26:27], v[8:11], off offset:512 nt
	global_store_dwordx4 v[26:27], v[12:15], off offset:528 nt
	v_add_f32_e32 v26, v8, v9
	v_add_f32_e32 v27, v10, v11
	v_add_f32_e32 v29, v12, v13
	v_add_f32_e32 v30, v14, v15
	v_mul_f32_e32 v31, v9, v9
	v_mul_f32_e32 v64, v11, v11
	v_mul_f32_e32 v65, v13, v13
	v_mul_f32_e32 v66, v15, v15
	v_pk_mul_f32 v[16:17], v[10:11], s[26:27] op_sel_hi:[1,0]
	v_pk_mul_f32 v[18:19], v[8:9], s[26:27] op_sel_hi:[1,0]
	v_add_f32_e32 v9, v26, v27
	v_add_f32_e32 v11, v29, v30
	v_fmac_f32_e32 v31, v8, v8
	v_fmac_f32_e32 v64, v10, v10
	v_fmac_f32_e32 v65, v12, v12
	v_fmac_f32_e32 v66, v14, v14
	v_med3_f32 v8, v18, s63, v192
	v_add_f32_e32 v9, v9, v11
	v_add_f32_e32 v11, v31, v64
	v_add_f32_e32 v18, v65, v66
	v_med3_f32 v10, v19, s63, v192
	v_add_f32_e32 v3, v3, v9
	v_add_f32_e32 v9, v11, v18
	v_add_f32_e32 v8, 0x4b400000, v8
	v_add_f32_e32 v10, 0x4b400000, v10
	v_add_f32_e32 v9, v28, v9
	v_perm_b32 v8, v10, v8, s64
	v_mov_b32_e32 v10, v3
	s_nop 1
	v_permlane16_swap_b32_e32 v3, v10
	v_mov_b32_e32 v11, v9
	s_nop 1
	v_permlane16_swap_b32_e32 v9, v11
	v_pk_mul_f32 v[22:23], v[12:13], s[26:27] op_sel_hi:[1,0]
	v_med3_f32 v12, v16, s63, v192
	v_med3_f32 v13, v17, s63, v192
	v_add_f32_e32 v12, 0x4b400000, v12
	v_add_f32_e32 v13, 0x4b400000, v13
	v_perm_b32 v12, v13, v12, s65
	s_waitcnt lgkmcnt(0)
	v_add_f32_e32 v3, v3, v10
	s_waitcnt lgkmcnt(0)
	v_add_f32_e32 v9, v9, v11
	v_pk_mul_f32 v[20:21], v[14:15], s[26:27] op_sel_hi:[1,0]
	v_or_b32_e32 v12, v8, v12
	v_mov_b32_e32 v8, v3
	s_nop 1
	v_permlane32_swap_b32_e32 v3, v8
	v_mov_b32_e32 v10, v9
	s_nop 1
	v_permlane32_swap_b32_e32 v9, v10
	v_med3_f32 v14, v22, s63, v192
	v_med3_f32 v15, v23, s63, v192
	v_med3_f32 v16, v20, s63, v192
	v_med3_f32 v17, v21, s63, v192
	v_add_f32_e32 v14, 0x4b400000, v14
	v_add_f32_e32 v15, 0x4b400000, v15
	v_add_f32_e32 v16, 0x4b400000, v16
	v_add_f32_e32 v17, 0x4b400000, v17
	v_perm_b32 v11, v15, v14, s64
	v_perm_b32 v13, v17, v16, s65
	v_or_b32_e32 v13, v11, v13
	global_store_dwordx2 v[24:25], v[12:13], off offset:128
	s_and_saveexec_b64 s[40:41], s[2:3]
	s_cbranch_execz .LBB0_3701
	v_lshl_add_u64 v[4:5], v[4:5], 3, s[14:15]
	s_waitcnt lgkmcnt(0)
	v_add_f32_e32 v3, v3, v8
	s_waitcnt lgkmcnt(0)
	v_add_f32_e32 v8, v9, v10
	global_atomic_add_f32 v[4:5], v3, off
	global_atomic_add_f32 v[4:5], v8, off offset:4
; __device__ __forceinline__ u32x2 pack8i8(const f32x4 a, const f32x4 b) { return (u32x2){pack4i8(a), pack4i8(b)}; }
; __device__ __forceinline__ u32x4 pack8bf(const f32x4 a, const f32x4 b) { u32x4 w; w.x = cvt_pk_bf16(a[0], a[1]); w.y = cvt_pk_bf16(a[2], a[3]); w.z = cvt_pk_bf16(b[0], b[1]); w.w = cvt_pk_bf16(b[2], b[3]); return w; }
;     __device__ __forceinline__ void operator()(EPI_ARGS) const {
;     ...
;             for (int m = 0; m < 4; ++m) { const int row = row0 + ai * HALF + m * 16; const size_t off = (size_t)row * DM + col0;
;                 float mu = 0.f, rs = 1.f; if constexpr (RESLN) ln_stats(stin, row, mu, rs);
;                 float ss = 0.f, qq = 0.f;
; #pragma unroll
;                 for (int bj = 0; bj < 2; ++bj) { f32x4 r0 = __builtin_nontemporal_load((const f32x4*)(res + off + bj * HALF)), r1 = __builtin_nontemporal_load((const f32x4*)(res + off + bj * HALF + 4));
;                     if constexpr (RESLN) { r0 = (r0 - mu) * rs * gg[bj][0] + bb[bj][0]; r1 = (r1 - mu) * rs * gg[bj][1] + bb[bj][1]; }
;                     const f32x4 y0 = r0 * DN_ALPHA + acc[ai][bj][m][0] * ascale, y1 = r1 * DN_ALPHA + acc[ai][bj][m][1] * ascale;
;                     if constexpr (COPY != 4) { __builtin_nontemporal_store(y0, (f32x4*)(Y + off + bj * HALF)); __builtin_nontemporal_store(y1, (f32x4*)(Y + off + bj * HALF + 4)); }
;                     if constexpr (STATS) { ss += ((y0[0] + y0[1]) + (y0[2] + y0[3])) + ((y1[0] + y1[1]) + (y1[2] + y1[3]));
;                         qq += ((y0[0] * y0[0] + y0[1] * y0[1]) + (y0[2] * y0[2] + y0[3] * y0[3])) + ((y1[0] * y1[0] + y1[1] * y1[1]) + (y1[2] * y1[2] + y1[3] * y1[3])); }
;                     if constexpr (COPY == 1) *(u32x2*)((unsigned char*)copy + off + bj * HALF) = pack8fp8(y0 * cscale, y1 * cscale);
;                     if constexpr (COPY == 3) *(u32x2*)((unsigned char*)copy + off + bj * HALF) = pack8i8(y0 * cscale, y1 * cscale);
;                     if constexpr (COPY == 2 || COPY == 4) *(u32x4*)((bf16_t*)copy + off + bj * HALF) = pack8bf(y0, y1); }
;                 if constexpr (STATS) { ss += __shfl_xor(ss, 16); ss += __shfl_xor(ss, 32); qq += __shfl_xor(qq, 16); qq += __shfl_xor(qq, 32);
;                     if (fq == 0) { unsafeAtomicAdd(stout + 2 * (size_t)row, ss); unsafeAtomicAdd(stout + 2 * (size_t)row + 1, qq); } }
.LBB0_3701:
	s_or_b64 exec, exec, s[40:41]
	v_add_u32_e32 v4, 0xa0, v2
	v_ashrrev_i32_e32 v5, 31, v4
	s_waitcnt lgkmcnt(1)
	v_lshlrev_b64 v[8:9], 11, v[4:5]
	v_lshl_add_u64 v[16:17], v[8:9], 0, v[0:1]
	v_lshlrev_b64 v[18:19], 2, v[16:17]
	v_lshl_add_u64 v[20:21], s[6:7], 0, v[18:19]
	s_waitcnt lgkmcnt(0)
	global_load_dwordx4 v[8:11], v[20:21], off nt
	global_load_dwordx4 v[12:15], v[20:21], off offset:16 nt
	global_load_dwordx4 v[228:231], v[20:21], off offset:512 nt
	global_load_dwordx4 v[232:235], v[20:21], off offset:528 nt
	v_lshl_add_u64 v[24:25], s[12:13], 0, v[16:17]
	v_lshl_add_u64 v[26:27], s[10:11], 0, v[18:19]
	s_waitcnt vmcnt(3)
	v_pk_mul_f32 v[10:11], v[10:11], s[20:21] op_sel_hi:[1,0]
	v_pk_mul_f32 v[8:9], v[8:9], s[20:21] op_sel_hi:[1,0]
	s_waitcnt vmcnt(2)
	v_pk_mul_f32 v[14:15], v[14:15], s[20:21] op_sel_hi:[1,0]
	v_pk_mul_f32 v[12:13], v[12:13], s[20:21] op_sel_hi:[1,0]
	v_pk_fma_f32 v[10:11], v[62:63], s[24:25], v[10:11] op_sel_hi:[1,0,1]
	v_pk_fma_f32 v[8:9], v[60:61], s[24:25], v[8:9] op_sel_hi:[1,0,1]
	v_pk_fma_f32 v[14:15], v[58:59], s[24:25], v[14:15] op_sel_hi:[1,0,1]
	v_pk_fma_f32 v[12:13], v[56:57], s[24:25], v[12:13] op_sel_hi:[1,0,1]
	v_pk_mul_f32 v[16:17], v[10:11], s[26:27] op_sel_hi:[1,0]
	v_pk_mul_f32 v[18:19], v[8:9], s[26:27] op_sel_hi:[1,0]
	v_pk_mul_f32 v[22:23], v[14:15], s[26:27] op_sel_hi:[1,0]
	v_pk_mul_f32 v[28:29], v[12:13], s[26:27] op_sel_hi:[1,0]
	v_med3_f32 v3, v18, s63, v192
	v_med3_f32 v18, v19, s63, v192
	v_med3_f32 v16, v16, s63, v192
	v_med3_f32 v17, v17, s63, v192
	v_med3_f32 v19, v28, s63, v192
	v_med3_f32 v28, v29, s63, v192
	v_med3_f32 v22, v22, s63, v192
	v_med3_f32 v23, v23, s63, v192
	v_add_f32_e32 v3, 0x4b400000, v3
	v_add_f32_e32 v18, 0x4b400000, v18
	v_add_f32_e32 v16, 0x4b400000, v16
	v_add_f32_e32 v17, 0x4b400000, v17
	v_add_f32_e32 v19, 0x4b400000, v19
	v_add_f32_e32 v28, 0x4b400000, v28
	v_add_f32_e32 v22, 0x4b400000, v22
	v_add_f32_e32 v23, 0x4b400000, v23
	v_perm_b32 v3, v18, v3, s64
	v_perm_b32 v16, v17, v16, s65
	v_perm_b32 v17, v28, v19, s64
	v_perm_b32 v18, v23, v22, s65
	v_or_b32_e32 v16, v3, v16
	v_or_b32_e32 v17, v17, v18
	global_store_dwordx4 v[26:27], v[8:11], off nt
	global_store_dwordx4 v[26:27], v[12:15], off offset:16 nt
	global_store_dwordx2 v[24:25], v[16:17], off
	s_waitcnt vmcnt(3)
	s_nop 1
	v_mov_b32_e32 v16, v228
	v_mov_b32_e32 v17, v229
	v_mov_b32_e32 v18, v230
	v_mov_b32_e32 v19, v231
	v_mov_b32_e32 v20, v232
	v_mov_b32_e32 v21, v233
	v_mov_b32_e32 v22, v234
	v_mov_b32_e32 v23, v235
	v_add_f32_e32 v3, v8, v9
	v_add_f32_e32 v28, v10, v11
	v_add_f32_e32 v29, v12, v13
	v_add_f32_e32 v30, v14, v15
	v_mul_f32_e32 v9, v9, v9
	v_mul_f32_e32 v11, v11, v11
	v_mul_f32_e32 v13, v13, v13
	v_mul_f32_e32 v15, v15, v15
	v_fmac_f32_e32 v9, v8, v8
	v_fmac_f32_e32 v11, v10, v10
	v_fmac_f32_e32 v13, v12, v12
	v_fmac_f32_e32 v15, v14, v14
	v_add_f32_e32 v3, v3, v28
	v_add_f32_e32 v28, v29, v30
	v_add_f32_e32 v8, v9, v11
	v_add_f32_e32 v9, v13, v15
	v_add_f32_e32 v3, v3, v28
	v_add_f32_e32 v28, v8, v9
	v_add_f32_e32 v3, 0, v3
	v_pk_mul_f32 v[8:9], v[18:19], s[20:21] op_sel_hi:[1,0]
	v_pk_mul_f32 v[12:13], v[16:17], s[20:21] op_sel_hi:[1,0]
	v_pk_mul_f32 v[14:15], v[22:23], s[20:21] op_sel_hi:[1,0]
	v_pk_mul_f32 v[16:17], v[20:21], s[20:21] op_sel_hi:[1,0]
	v_pk_fma_f32 v[10:11], v[54:55], s[24:25], v[8:9] op_sel_hi:[1,0,1]
	v_pk_fma_f32 v[8:9], v[52:53], s[24:25], v[12:13] op_sel_hi:[1,0,1]
	v_pk_fma_f32 v[14:15], v[50:51], s[24:25], v[14:15] op_sel_hi:[1,0,1]
	v_pk_fma_f32 v[12:13], v[48:49], s[24:25], v[16:17] op_sel_hi:[1,0,1]
	global_store_dwordx4 v[26:27], v[8:11], off offset:512 nt
	global_store_dwordx4 v[26:27], v[12:15], off offset:528 nt
	v_add_f32_e32 v26, v8, v9
	v_add_f32_e32 v27, v10, v11
	v_add_f32_e32 v29, v12, v13
	v_add_f32_e32 v30, v14, v15
	v_mul_f32_e32 v31, v9, v9
	v_mul_f32_e32 v48, v11, v11
	v_mul_f32_e32 v49, v13, v13
	v_mul_f32_e32 v50, v15, v15
	v_pk_mul_f32 v[16:17], v[10:11], s[26:27] op_sel_hi:[1,0]
	v_pk_mul_f32 v[18:19], v[8:9], s[26:27] op_sel_hi:[1,0]
	v_add_f32_e32 v9, v26, v27
	v_add_f32_e32 v11, v29, v30
	v_fmac_f32_e32 v31, v8, v8
	v_fmac_f32_e32 v48, v10, v10
	v_fmac_f32_e32 v49, v12, v12
	v_fmac_f32_e32 v50, v14, v14
	v_med3_f32 v8, v18, s63, v192
	v_add_f32_e32 v9, v9, v11
	v_add_f32_e32 v11, v31, v48
	v_add_f32_e32 v18, v49, v50
	v_med3_f32 v10, v19, s63, v192
	v_add_f32_e32 v3, v3, v9
	v_add_f32_e32 v9, v11, v18
	v_add_f32_e32 v8, 0x4b400000, v8
	v_add_f32_e32 v10, 0x4b400000, v10
	v_add_f32_e32 v9, v28, v9
	v_perm_b32 v8, v10, v8, s64
	v_mov_b32_e32 v10, v3
	s_nop 1
	v_permlane16_swap_b32_e32 v3, v10
	v_mov_b32_e32 v11, v9
	s_nop 1
	v_permlane16_swap_b32_e32 v9, v11
	v_pk_mul_f32 v[22:23], v[12:13], s[26:27] op_sel_hi:[1,0]
	v_med3_f32 v12, v16, s63, v192
	v_med3_f32 v13, v17, s63, v192
	v_add_f32_e32 v12, 0x4b400000, v12
	v_add_f32_e32 v13, 0x4b400000, v13
	v_perm_b32 v12, v13, v12, s65
	s_waitcnt lgkmcnt(0)
	v_add_f32_e32 v3, v3, v10
	s_waitcnt lgkmcnt(0)
	v_add_f32_e32 v9, v9, v11
	v_pk_mul_f32 v[20:21], v[14:15], s[26:27] op_sel_hi:[1,0]
	v_or_b32_e32 v12, v8, v12
	v_mov_b32_e32 v8, v3
	s_nop 1
	v_permlane32_swap_b32_e32 v3, v8
	v_mov_b32_e32 v10, v9
	s_nop 1
	v_permlane32_swap_b32_e32 v9, v10
	v_med3_f32 v14, v22, s63, v192
	v_med3_f32 v15, v23, s63, v192
	v_med3_f32 v16, v20, s63, v192
	v_med3_f32 v17, v21, s63, v192
	v_add_f32_e32 v14, 0x4b400000, v14
	v_add_f32_e32 v15, 0x4b400000, v15
	v_add_f32_e32 v16, 0x4b400000, v16
	v_add_f32_e32 v17, 0x4b400000, v17
	v_perm_b32 v11, v15, v14, s64
	v_perm_b32 v13, v17, v16, s65
	v_or_b32_e32 v13, v11, v13
	global_store_dwordx2 v[24:25], v[12:13], off offset:128
	s_and_saveexec_b64 s[40:41], s[2:3]
	s_cbranch_execz .LBB0_3703
	v_lshl_add_u64 v[4:5], v[4:5], 3, s[14:15]
	s_waitcnt lgkmcnt(0)
	v_add_f32_e32 v3, v3, v8
	s_waitcnt lgkmcnt(0)
	v_add_f32_e32 v8, v9, v10
	global_atomic_add_f32 v[4:5], v3, off
	global_atomic_add_f32 v[4:5], v8, off offset:4
; __device__ __forceinline__ u32x2 pack8i8(const f32x4 a, const f32x4 b) { return (u32x2){pack4i8(a), pack4i8(b)}; }
; __device__ __forceinline__ u32x4 pack8bf(const f32x4 a, const f32x4 b) { u32x4 w; w.x = cvt_pk_bf16(a[0], a[1]); w.y = cvt_pk_bf16(a[2], a[3]); w.z = cvt_pk_bf16(b[0], b[1]); w.w = cvt_pk_bf16(b[2], b[3]); return w; }
;     __device__ __forceinline__ void operator()(EPI_ARGS) const {
;     ...
;             for (int m = 0; m < 4; ++m) { const int row = row0 + ai * HALF + m * 16; const size_t off = (size_t)row * DM + col0;
;                 float mu = 0.f, rs = 1.f; if constexpr (RESLN) ln_stats(stin, row, mu, rs);
;                 float ss = 0.f, qq = 0.f;
; #pragma unroll
;                 for (int bj = 0; bj < 2; ++bj) { f32x4 r0 = __builtin_nontemporal_load((const f32x4*)(res + off + bj * HALF)), r1 = __builtin_nontemporal_load((const f32x4*)(res + off + bj * HALF + 4));
;                     if constexpr (RESLN) { r0 = (r0 - mu) * rs * gg[bj][0] + bb[bj][0]; r1 = (r1 - mu) * rs * gg[bj][1] + bb[bj][1]; }
;                     const f32x4 y0 = r0 * DN_ALPHA + acc[ai][bj][m][0] * ascale, y1 = r1 * DN_ALPHA + acc[ai][bj][m][1] * ascale;
;                     if constexpr (COPY != 4) { __builtin_nontemporal_store(y0, (f32x4*)(Y + off + bj * HALF)); __builtin_nontemporal_store(y1, (f32x4*)(Y + off + bj * HALF + 4)); }
;                     if constexpr (STATS) { ss += ((y0[0] + y0[1]) + (y0[2] + y0[3])) + ((y1[0] + y1[1]) + (y1[2] + y1[3]));
;                         qq += ((y0[0] * y0[0] + y0[1] * y0[1]) + (y0[2] * y0[2] + y0[3] * y0[3])) + ((y1[0] * y1[0] + y1[1] * y1[1]) + (y1[2] * y1[2] + y1[3] * y1[3])); }
;                     if constexpr (COPY == 1) *(u32x2*)((unsigned char*)copy + off + bj * HALF) = pack8fp8(y0 * cscale, y1 * cscale);
;                     if constexpr (COPY == 3) *(u32x2*)((unsigned char*)copy + off + bj * HALF) = pack8i8(y0 * cscale, y1 * cscale);
;                     if constexpr (COPY == 2 || COPY == 4) *(u32x4*)((bf16_t*)copy + off + bj * HALF) = pack8bf(y0, y1); }
;                 if constexpr (STATS) { ss += __shfl_xor(ss, 16); ss += __shfl_xor(ss, 32); qq += __shfl_xor(qq, 16); qq += __shfl_xor(qq, 32);
;                     if (fq == 0) { unsafeAtomicAdd(stout + 2 * (size_t)row, ss); unsafeAtomicAdd(stout + 2 * (size_t)row + 1, qq); } }
.LBB0_3703:
	s_or_b64 exec, exec, s[40:41]
	v_add_u32_e32 v2, 0xb0, v2
	v_ashrrev_i32_e32 v3, 31, v2
	v_lshlrev_b64 v[4:5], 11, v[2:3]
	v_lshl_add_u64 v[0:1], v[4:5], 0, v[0:1]
	v_lshlrev_b64 v[4:5], 2, v[0:1]
	v_lshl_add_u64 v[20:21], s[6:7], 0, v[4:5]
	s_waitcnt lgkmcnt(0)
	global_load_dwordx4 v[8:11], v[20:21], off nt
	global_load_dwordx4 v[12:15], v[20:21], off offset:16 nt
	global_load_dwordx4 v[228:231], v[20:21], off offset:512 nt
	global_load_dwordx4 v[232:235], v[20:21], off offset:528 nt
	v_lshl_add_u64 v[24:25], s[12:13], 0, v[0:1]
	v_lshl_add_u64 v[0:1], s[10:11], 0, v[4:5]
	s_waitcnt vmcnt(3)
	v_pk_mul_f32 v[4:5], v[10:11], s[20:21] op_sel_hi:[1,0]
	v_pk_mul_f32 v[8:9], v[8:9], s[20:21] op_sel_hi:[1,0]
	s_waitcnt vmcnt(2)
	v_pk_mul_f32 v[14:15], v[14:15], s[20:21] op_sel_hi:[1,0]
	v_pk_mul_f32 v[12:13], v[12:13], s[20:21] op_sel_hi:[1,0]
	v_pk_fma_f32 v[10:11], v[46:47], s[24:25], v[4:5] op_sel_hi:[1,0,1]
	v_pk_fma_f32 v[8:9], v[44:45], s[24:25], v[8:9] op_sel_hi:[1,0,1]
	v_pk_fma_f32 v[14:15], v[42:43], s[24:25], v[14:15] op_sel_hi:[1,0,1]
	v_pk_fma_f32 v[12:13], v[40:41], s[24:25], v[12:13] op_sel_hi:[1,0,1]
	v_pk_mul_f32 v[4:5], v[10:11], s[26:27] op_sel_hi:[1,0]
	v_pk_mul_f32 v[16:17], v[8:9], s[26:27] op_sel_hi:[1,0]
	v_pk_mul_f32 v[18:19], v[14:15], s[26:27] op_sel_hi:[1,0]
	v_pk_mul_f32 v[22:23], v[12:13], s[26:27] op_sel_hi:[1,0]
	v_med3_f32 v16, v16, s63, v192
	v_med3_f32 v17, v17, s63, v192
	v_med3_f32 v4, v4, s63, v192
	v_med3_f32 v5, v5, s63, v192
	v_med3_f32 v22, v22, s63, v192
	v_med3_f32 v23, v23, s63, v192
	v_med3_f32 v18, v18, s63, v192
	v_med3_f32 v19, v19, s63, v192
	v_add_f32_e32 v16, 0x4b400000, v16
	v_add_f32_e32 v17, 0x4b400000, v17
	v_add_f32_e32 v4, 0x4b400000, v4
	v_add_f32_e32 v5, 0x4b400000, v5
	v_add_f32_e32 v22, 0x4b400000, v22
	v_add_f32_e32 v23, 0x4b400000, v23
	v_add_f32_e32 v18, 0x4b400000, v18
	v_add_f32_e32 v19, 0x4b400000, v19
	v_perm_b32 v16, v17, v16, s64
	v_perm_b32 v4, v5, v4, s65
	v_perm_b32 v5, v23, v22, s64
	v_perm_b32 v17, v19, v18, s65
	v_or_b32_e32 v4, v16, v4
	v_or_b32_e32 v5, v5, v17
	global_store_dwordx4 v[0:1], v[8:11], off nt
	global_store_dwordx4 v[0:1], v[12:15], off offset:16 nt
	global_store_dwordx2 v[24:25], v[4:5], off
	s_waitcnt vmcnt(3)
	s_nop 1
	v_mov_b32_e32 v16, v228
	v_mov_b32_e32 v17, v229
	v_mov_b32_e32 v18, v230
	v_mov_b32_e32 v19, v231
	v_mov_b32_e32 v20, v232
	v_mov_b32_e32 v21, v233
	v_mov_b32_e32 v22, v234
	v_mov_b32_e32 v23, v235
	v_add_f32_e32 v4, v8, v9
	v_add_f32_e32 v5, v10, v11
	v_add_f32_e32 v26, v12, v13
	v_add_f32_e32 v27, v14, v15
	v_mul_f32_e32 v9, v9, v9
	v_mul_f32_e32 v11, v11, v11
	v_mul_f32_e32 v13, v13, v13
	v_mul_f32_e32 v15, v15, v15
	v_add_f32_e32 v4, v4, v5
	v_add_f32_e32 v5, v26, v27
	v_fmac_f32_e32 v9, v8, v8
	v_fmac_f32_e32 v11, v10, v10
	v_fmac_f32_e32 v13, v12, v12
	v_fmac_f32_e32 v15, v14, v14
	v_add_f32_e32 v4, v4, v5
	v_add_f32_e32 v5, v9, v11
	v_add_f32_e32 v8, v13, v15
	v_add_f32_e32 v26, 0, v4
	v_add_f32_e32 v27, v5, v8
	v_pk_mul_f32 v[4:5], v[18:19], s[20:21] op_sel_hi:[1,0]
	v_pk_mul_f32 v[8:9], v[16:17], s[20:21] op_sel_hi:[1,0]
	v_pk_mul_f32 v[12:13], v[22:23], s[20:21] op_sel_hi:[1,0]
	v_pk_mul_f32 v[16:17], v[20:21], s[20:21] op_sel_hi:[1,0]
	v_pk_fma_f32 v[10:11], v[38:39], s[24:25], v[4:5] op_sel_hi:[1,0,1]
	v_pk_fma_f32 v[8:9], v[36:37], s[24:25], v[8:9] op_sel_hi:[1,0,1]
	v_pk_fma_f32 v[14:15], v[34:35], s[24:25], v[12:13] op_sel_hi:[1,0,1]
	v_pk_fma_f32 v[12:13], v[32:33], s[24:25], v[16:17] op_sel_hi:[1,0,1]
	v_add_f32_e32 v20, v8, v9
	v_add_f32_e32 v21, v10, v11
	v_add_f32_e32 v22, v12, v13
	v_add_f32_e32 v23, v14, v15
	v_mul_f32_e32 v28, v9, v9
	v_mul_f32_e32 v29, v11, v11
	v_mul_f32_e32 v30, v13, v13
	v_mul_f32_e32 v31, v15, v15
	global_store_dwordx4 v[0:1], v[8:11], off offset:512 nt
	global_store_dwordx4 v[0:1], v[12:15], off offset:528 nt
	v_pk_mul_f32 v[0:1], v[10:11], s[26:27] op_sel_hi:[1,0]
	v_pk_mul_f32 v[4:5], v[8:9], s[26:27] op_sel_hi:[1,0]
	v_pk_mul_f32 v[18:19], v[12:13], s[26:27] op_sel_hi:[1,0]
	v_add_f32_e32 v9, v20, v21
	v_add_f32_e32 v11, v22, v23
	v_fmac_f32_e32 v28, v8, v8
	v_fmac_f32_e32 v29, v10, v10
	v_fmac_f32_e32 v30, v12, v12
	v_fmac_f32_e32 v31, v14, v14
	v_pk_mul_f32 v[16:17], v[14:15], s[26:27] op_sel_hi:[1,0]
	v_med3_f32 v8, v18, s63, v192
	v_add_f32_e32 v9, v9, v11
	v_add_f32_e32 v11, v28, v29
	v_add_f32_e32 v14, v30, v31
	v_med3_f32 v4, v4, s63, v192
	v_med3_f32 v5, v5, s63, v192
	v_add_f32_e32 v15, 0x4b400000, v8
	v_add_f32_e32 v8, v11, v14
	v_add_f32_e32 v4, 0x4b400000, v4
	v_add_f32_e32 v5, 0x4b400000, v5
	v_add_f32_e32 v9, v26, v9
	v_add_f32_e32 v11, v27, v8
	v_perm_b32 v4, v5, v4, s64
	v_mov_b32_e32 v5, v9
	s_nop 1
	v_permlane16_swap_b32_e32 v9, v5
	v_mov_b32_e32 v7, v11
	s_nop 1
	v_permlane16_swap_b32_e32 v11, v7
	v_med3_f32 v0, v0, s63, v192
	v_med3_f32 v1, v1, s63, v192
	v_add_f32_e32 v0, 0x4b400000, v0
	v_add_f32_e32 v1, 0x4b400000, v1
	v_perm_b32 v0, v1, v0, s65
	v_or_b32_e32 v8, v4, v0
	s_waitcnt lgkmcnt(0)
	v_add_f32_e32 v0, v9, v5
	s_waitcnt lgkmcnt(0)
	v_add_f32_e32 v4, v11, v7
	v_mov_b32_e32 v1, v0
	s_nop 1
	v_permlane32_swap_b32_e32 v0, v1
	v_mov_b32_e32 v5, v4
	s_nop 1
	v_permlane32_swap_b32_e32 v4, v5
	v_med3_f32 v10, v19, s63, v192
	v_med3_f32 v12, v16, s63, v192
	v_med3_f32 v13, v17, s63, v192
	v_add_f32_e32 v10, 0x4b400000, v10
	v_add_f32_e32 v12, 0x4b400000, v12
	v_add_f32_e32 v13, 0x4b400000, v13
	v_perm_b32 v6, v10, v15, s64
	v_perm_b32 v7, v13, v12, s65
	v_or_b32_e32 v9, v6, v7
	global_store_dwordx2 v[24:25], v[8:9], off offset:128
	s_and_saveexec_b64 s[40:41], s[2:3]
	s_cbranch_execz .LBB0_3705
	v_lshl_add_u64 v[2:3], v[2:3], 3, s[14:15]
	s_waitcnt lgkmcnt(0)
	v_add_f32_e32 v0, v0, v1
	s_waitcnt lgkmcnt(0)
	v_add_f32_e32 v1, v4, v5
	global_atomic_add_f32 v[2:3], v0, off
	global_atomic_add_f32 v[2:3], v1, off offset:4

;     __device__ __forceinline__ void operator()(EPI_ARGS) const {
;         const int row0 = u.pm * BM + wr * 64 + fr, col0 = u.pn * BM + wc * 32 + 8 * fq;
;         f32x4 gg[2][2], bb[2][2];
;         if constexpr (RESLN) {
; #pragma unroll
;             for (int bj = 0; bj < 2; ++bj)
; #pragma unroll
;                 for (int n = 0; n < 2; ++n) { gg[bj][n] = *(const f32x4*)(lg + col0 + bj * HALF + 4 * n); bb[bj][n] = *(const f32x4*)(lb + col0 + bj * HALF + 4 * n); } }
; #pragma unroll
;         for (int ai = 0; ai < 2; ++ai)
; #pragma unroll
;             for (int m = 0; m < 4; ++m) { const int row = row0 + ai * HALF + m * 16; const size_t off = (size_t)row * DM + col0;
;                 float mu = 0.f, rs = 1.f; if constexpr (RESLN) ln_stats(stin, row, mu, rs);
;                 float ss = 0.f, qq = 0.f;
; #pragma unroll
;                 for (int bj = 0; bj < 2; ++bj) { f32x4 r0 = __builtin_nontemporal_load((const f32x4*)(res + off + bj * HALF)), r1 = __builtin_nontemporal_load((const f32x4*)(res + off + bj * HALF + 4));
;                     if constexpr (RESLN) { r0 = (r0 - mu) * rs * gg[bj][0] + bb[bj][0]; r1 = (r1 - mu) * rs * gg[bj][1] + bb[bj][1]; }
;                     const f32x4 y0 = r0 * DN_ALPHA + acc[ai][bj][m][0] * ascale, y1 = r1 * DN_ALPHA + acc[ai][bj][m][1] * ascale;
;                     if constexpr (COPY != 4) { __builtin_nontemporal_store(y0, (f32x4*)(Y + off + bj * HALF)); __builtin_nontemporal_store(y1, (f32x4*)(Y + off + bj * HALF + 4)); }
;                     if constexpr (STATS) { ss += ((y0[0] + y0[1]) + (y0[2] + y0[3])) + ((y1[0] + y1[1]) + (y1[2] + y1[3]));
;                         qq += ((y0[0] * y0[0] + y0[1] * y0[1]) + (y0[2] * y0[2] + y0[3] * y0[3])) + ((y1[0] * y1[0] + y1[1] * y1[1]) + (y1[2] * y1[2] + y1[3] * y1[3])); }
;                     if constexpr (COPY == 1) *(u32x2*)((unsigned char*)copy + off + bj * HALF) = pack8fp8(y0 * cscale, y1 * cscale);
;                     if constexpr (COPY == 3) *(u32x2*)((unsigned char*)copy + off + bj * HALF) = pack8i8(y0 * cscale, y1 * cscale);
;                     if constexpr (COPY == 2 || COPY == 4) *(u32x4*)((bf16_t*)copy + off + bj * HALF) = pack8bf(y0, y1); }
;                 if constexpr (STATS) { ss += __shfl_xor(ss, 16); ss += __shfl_xor(ss, 32); qq += __shfl_xor(qq, 16); qq += __shfl_xor(qq, 32);
.LBB0_3861:
	v_lshl_add_u32 v178, s69, 8, v186
	v_lshl_or_b32 v176, s70, 8, v188
	v_ashrrev_i32_e32 v179, 31, v178
	v_ashrrev_i32_e32 v177, 31, v176
	v_lshlrev_b64 v[0:1], 11, v[178:179]
	v_lshlrev_b64 v[180:181], 3, v[178:179]
	v_lshl_add_u64 v[184:185], v[0:1], 0, v[176:177]
	v_lshl_add_u64 v[0:1], s[14:15], 0, v[180:181]
	global_load_dwordx2 v[204:205], v[0:1], off
	v_lshl_add_u64 v[182:183], v[184:185], 2, s[18:19]
	global_load_dwordx4 v[196:199], v[182:183], off nt
	global_load_dwordx4 v[200:203], v[182:183], off offset:16 nt
	global_load_dwordx4 v[228:231], v[182:183], off offset:512 nt
	global_load_dwordx4 v[232:235], v[182:183], off offset:528 nt
	v_lshlrev_b64 v[0:1], 2, v[176:177]
	v_lshl_add_u64 v[4:5], s[8:9], 0, v[0:1]
	v_lshl_add_u64 v[12:13], s[10:11], 0, v[0:1]
	global_load_dwordx4 v[16:19], v[12:13], off
	global_load_dwordx4 v[28:31], v[4:5], off
	global_load_dwordx4 v[20:23], v[4:5], off offset:16
	global_load_dwordx4 v[24:27], v[12:13], off offset:16
	global_load_dwordx4 v[0:3], v[4:5], off offset:528
	global_load_dwordx4 v[8:11], v[4:5], off offset:512
	s_nop 0
	global_load_dwordx4 v[4:7], v[12:13], off offset:528
	s_nop 0
	global_load_dwordx4 v[12:15], v[12:13], off offset:512
	v_lshl_add_u64 v[184:185], s[20:21], 0, v[184:185]
	s_waitcnt vmcnt(0)
	v_pk_mul_f32 v[208:209], v[204:205], s[28:29] op_sel_hi:[1,0]
	s_nop 0
	v_fma_f32 v179, -v208, v208, v209
	v_add_f32_e32 v179, 0x3727c5ac, v179
	v_rsq_f32_e32 v254, v179
	v_sub_f32_e32 v199, v199, v208
	v_sub_f32_e32 v198, v198, v208
	v_sub_f32_e32 v197, v197, v208
	v_sub_f32_e32 v196, v196, v208
	v_sub_f32_e32 v203, v203, v208
	v_sub_f32_e32 v202, v202, v208
	v_sub_f32_e32 v201, v201, v208
	v_sub_f32_e32 v200, v200, v208
	s_nop 0
	s_nop 1
	v_mov_b32_e32 v210, v254
	v_pk_mul_f32 v[196:197], v[196:197], v[210:211] op_sel_hi:[1,0]
	v_pk_mul_f32 v[198:199], v[198:199], v[210:211] op_sel_hi:[1,0]
	v_pk_mul_f32 v[200:201], v[200:201], v[210:211] op_sel_hi:[1,0]
	v_pk_mul_f32 v[202:203], v[202:203], v[210:211] op_sel_hi:[1,0]
	v_pk_fma_f32 v[198:199], v[30:31], v[198:199], v[18:19]
	v_pk_fma_f32 v[196:197], v[28:29], v[196:197], v[16:17]
	v_pk_fma_f32 v[202:203], v[22:23], v[202:203], v[26:27]
	v_pk_fma_f32 v[200:201], v[20:21], v[200:201], v[24:25]
	v_pk_mul_f32 v[196:197], v[196:197], s[30:31] op_sel_hi:[1,0]
	v_pk_mul_f32 v[198:199], v[198:199], s[30:31] op_sel_hi:[1,0]
	v_pk_mul_f32 v[200:201], v[200:201], s[30:31] op_sel_hi:[1,0]
	v_pk_mul_f32 v[202:203], v[202:203], s[30:31] op_sel_hi:[1,0]
	v_pk_fma_f32 v[158:159], v[158:159], s[36:37], v[198:199] op_sel_hi:[1,0,1]
	v_pk_fma_f32 v[156:157], v[156:157], s[36:37], v[196:197] op_sel_hi:[1,0,1]
	v_pk_fma_f32 v[198:199], v[154:155], s[36:37], v[202:203] op_sel_hi:[1,0,1]
	v_pk_fma_f32 v[196:197], v[152:153], s[36:37], v[200:201] op_sel_hi:[1,0,1]
	v_pk_mul_f32 v[152:153], v[158:159], s[38:39] op_sel_hi:[1,0]
	v_pk_mul_f32 v[154:155], v[156:157], s[38:39] op_sel_hi:[1,0]
	v_pk_mul_f32 v[200:201], v[198:199], s[38:39] op_sel_hi:[1,0]
	v_pk_mul_f32 v[202:203], v[196:197], s[38:39] op_sel_hi:[1,0]
	v_med3_f32 v154, v154, s64, v195
	v_med3_f32 v155, v155, s64, v195
	v_med3_f32 v152, v152, s64, v195
	v_med3_f32 v153, v153, s64, v195
	v_med3_f32 v179, v202, s64, v195
	v_med3_f32 v202, v203, s64, v195
	v_med3_f32 v200, v200, s64, v195
	v_med3_f32 v201, v201, s64, v195
	v_add_f32_e32 v154, 0x4b400000, v154
	v_add_f32_e32 v155, 0x4b400000, v155
	v_add_f32_e32 v152, 0x4b400000, v152
	v_add_f32_e32 v153, 0x4b400000, v153
	v_add_f32_e32 v179, 0x4b400000, v179
	v_add_f32_e32 v202, 0x4b400000, v202
	v_add_f32_e32 v200, 0x4b400000, v200
	v_add_f32_e32 v201, 0x4b400000, v201
	v_perm_b32 v154, v155, v154, s65
	v_perm_b32 v152, v153, v152, s66
	v_perm_b32 v153, v202, v179, s65
	v_perm_b32 v155, v201, v200, s66
	v_or_b32_e32 v152, v154, v152
	v_or_b32_e32 v153, v153, v155
	global_store_dwordx4 v[182:183], v[156:159], off nt
	global_store_dwordx4 v[182:183], v[196:199], off offset:16 nt
	global_store_dwordx2 v[184:185], v[152:153], off
	s_waitcnt vmcnt(11)
	s_nop 1
	v_mov_b32_e32 v200, v228
	v_mov_b32_e32 v201, v229
	v_mov_b32_e32 v202, v230
	v_mov_b32_e32 v203, v231
	v_mov_b32_e32 v204, v232
	v_mov_b32_e32 v205, v233
	v_mov_b32_e32 v206, v234
	v_mov_b32_e32 v207, v235
	v_and_b32_e32 v153, 64, v193
	v_xor_b32_e32 v152, 16, v193
	v_add_u32_e32 v153, 64, v153
	v_xor_b32_e32 v154, 32, v193
	v_cmp_lt_i32_e32 vcc, v152, v153
	v_add_f32_e32 v155, v158, v159
	v_add_f32_e32 v179, v196, v197
	v_cndmask_b32_e32 v152, v193, v152, vcc
	v_cmp_lt_i32_e32 vcc, v154, v153
	v_lshlrev_b32_e32 v153, 2, v152
	v_add_f32_e32 v209, v198, v199
	v_cndmask_b32_e32 v154, v193, v154, vcc
	v_lshlrev_b32_e32 v152, 2, v154
	v_add_f32_e32 v154, v156, v157
	v_mul_f32_e32 v157, v157, v157
	v_mul_f32_e32 v159, v159, v159
	v_mul_f32_e32 v197, v197, v197
	v_mul_f32_e32 v199, v199, v199
	v_add_f32_e32 v154, v154, v155
	v_add_f32_e32 v155, v179, v209
	v_fmac_f32_e32 v157, v156, v156
	v_fmac_f32_e32 v159, v158, v158
	v_fmac_f32_e32 v197, v196, v196
	v_fmac_f32_e32 v199, v198, v198
	v_add_f32_e32 v154, v154, v155
	v_add_f32_e32 v155, v157, v159
	v_add_f32_e32 v156, v197, v199
	v_add_f32_e32 v179, 0, v154
	v_add_f32_e32 v198, v155, v156
	v_sub_f32_e32 v155, v203, v208
	v_sub_f32_e32 v154, v202, v208
	v_sub_f32_e32 v157, v201, v208
	v_sub_f32_e32 v156, v200, v208
	v_sub_f32_e32 v159, v207, v208
	v_sub_f32_e32 v158, v206, v208
	v_sub_f32_e32 v197, v205, v208
	v_sub_f32_e32 v196, v204, v208
	v_pk_mul_f32 v[156:157], v[156:157], v[210:211] op_sel_hi:[1,0]
	v_pk_mul_f32 v[154:155], v[154:155], v[210:211] op_sel_hi:[1,0]
	v_pk_mul_f32 v[196:197], v[196:197], v[210:211] op_sel_hi:[1,0]
; __device__ __forceinline__ u32x2 pack8i8(const f32x4 a, const f32x4 b) { return (u32x2){pack4i8(a), pack4i8(b)}; }
; __device__ __forceinline__ u32x4 pack8bf(const f32x4 a, const f32x4 b) { u32x4 w; w.x = cvt_pk_bf16(a[0], a[1]); w.y = cvt_pk_bf16(a[2], a[3]); w.z = cvt_pk_bf16(b[0], b[1]); w.w = cvt_pk_bf16(b[2], b[3]); return w; }
;     __device__ __forceinline__ void operator()(EPI_ARGS) const {
;     ...
;             for (int m = 0; m < 4; ++m) { const int row = row0 + ai * HALF + m * 16; const size_t off = (size_t)row * DM + col0;
;                 float mu = 0.f, rs = 1.f; if constexpr (RESLN) ln_stats(stin, row, mu, rs);
;                 float ss = 0.f, qq = 0.f;
; #pragma unroll
;                 for (int bj = 0; bj < 2; ++bj) { f32x4 r0 = __builtin_nontemporal_load((const f32x4*)(res + off + bj * HALF)), r1 = __builtin_nontemporal_load((const f32x4*)(res + off + bj * HALF + 4));
;                     if constexpr (RESLN) { r0 = (r0 - mu) * rs * gg[bj][0] + bb[bj][0]; r1 = (r1 - mu) * rs * gg[bj][1] + bb[bj][1]; }
;                     const f32x4 y0 = r0 * DN_ALPHA + acc[ai][bj][m][0] * ascale, y1 = r1 * DN_ALPHA + acc[ai][bj][m][1] * ascale;
;                     if constexpr (COPY != 4) { __builtin_nontemporal_store(y0, (f32x4*)(Y + off + bj * HALF)); __builtin_nontemporal_store(y1, (f32x4*)(Y + off + bj * HALF + 4)); }
;                     if constexpr (STATS) { ss += ((y0[0] + y0[1]) + (y0[2] + y0[3])) + ((y1[0] + y1[1]) + (y1[2] + y1[3]));
;                         qq += ((y0[0] * y0[0] + y0[1] * y0[1]) + (y0[2] * y0[2] + y0[3] * y0[3])) + ((y1[0] * y1[0] + y1[1] * y1[1]) + (y1[2] * y1[2] + y1[3] * y1[3])); }
;                     if constexpr (COPY == 1) *(u32x2*)((unsigned char*)copy + off + bj * HALF) = pack8fp8(y0 * cscale, y1 * cscale);
;                     if constexpr (COPY == 3) *(u32x2*)((unsigned char*)copy + off + bj * HALF) = pack8i8(y0 * cscale, y1 * cscale);
;                     if constexpr (COPY == 2 || COPY == 4) *(u32x4*)((bf16_t*)copy + off + bj * HALF) = pack8bf(y0, y1); }
;                 if constexpr (STATS) { ss += __shfl_xor(ss, 16); ss += __shfl_xor(ss, 32); qq += __shfl_xor(qq, 16); qq += __shfl_xor(qq, 32);
;                     if (fq == 0) { unsafeAtomicAdd(stout + 2 * (size_t)row, ss); unsafeAtomicAdd(stout + 2 * (size_t)row + 1, qq); } }
	v_pk_mul_f32 v[158:159], v[158:159], v[210:211] op_sel_hi:[1,0]
	v_pk_fma_f32 v[154:155], v[10:11], v[154:155], v[14:15]
	v_pk_fma_f32 v[156:157], v[8:9], v[156:157], v[12:13]
	v_pk_fma_f32 v[158:159], v[2:3], v[158:159], v[6:7]
	v_pk_fma_f32 v[196:197], v[0:1], v[196:197], v[4:5]
	v_pk_mul_f32 v[156:157], v[156:157], s[30:31] op_sel_hi:[1,0]
	v_pk_mul_f32 v[154:155], v[154:155], s[30:31] op_sel_hi:[1,0]
	v_pk_mul_f32 v[196:197], v[196:197], s[30:31] op_sel_hi:[1,0]
	v_pk_mul_f32 v[158:159], v[158:159], s[30:31] op_sel_hi:[1,0]
	v_pk_fma_f32 v[150:151], v[150:151], s[36:37], v[154:155] op_sel_hi:[1,0,1]
	v_pk_fma_f32 v[148:149], v[148:149], s[36:37], v[156:157] op_sel_hi:[1,0,1]
	v_pk_fma_f32 v[146:147], v[146:147], s[36:37], v[158:159] op_sel_hi:[1,0,1]
	v_pk_fma_f32 v[144:145], v[144:145], s[36:37], v[196:197] op_sel_hi:[1,0,1]
	v_add_f32_e32 v196, v148, v149
	v_add_f32_e32 v197, v150, v151
	v_add_f32_e32 v199, v144, v145
	v_add_f32_e32 v200, v146, v147
	v_mul_f32_e32 v201, v149, v149
	v_mul_f32_e32 v202, v151, v151
	v_mul_f32_e32 v203, v145, v145
	v_mul_f32_e32 v204, v147, v147
	global_store_dwordx4 v[182:183], v[148:151], off offset:512 nt
	global_store_dwordx4 v[182:183], v[144:147], off offset:528 nt
	v_pk_mul_f32 v[156:157], v[148:149], s[38:39] op_sel_hi:[1,0]
	v_pk_mul_f32 v[158:159], v[146:147], s[38:39] op_sel_hi:[1,0]
	v_pk_mul_f32 v[182:183], v[144:145], s[38:39] op_sel_hi:[1,0]
	v_add_f32_e32 v145, v196, v197
	v_add_f32_e32 v147, v199, v200
	v_fmac_f32_e32 v201, v148, v148
	v_fmac_f32_e32 v202, v150, v150
	v_fmac_f32_e32 v203, v144, v144
	v_fmac_f32_e32 v204, v146, v146
	v_med3_f32 v144, v156, s64, v195
	v_add_f32_e32 v145, v145, v147
	v_add_f32_e32 v147, v201, v202
	v_add_f32_e32 v156, v203, v204
	v_med3_f32 v146, v157, s64, v195
	v_add_f32_e32 v147, v147, v156
	v_add_f32_e32 v144, 0x4b400000, v144
	v_add_f32_e32 v146, 0x4b400000, v146
	v_add_f32_e32 v145, v145, v179
	v_add_f32_e32 v147, v198, v147
	v_perm_b32 v144, v146, v144, s65
	v_mov_b32_e32 v146, v145
	s_nop 1
	v_permlane16_swap_b32_e32 v145, v146
	v_mov_b32_e32 v156, v147
	s_nop 1
	v_permlane16_swap_b32_e32 v147, v156
	v_pk_mul_f32 v[154:155], v[150:151], s[38:39] op_sel_hi:[1,0]
	v_med3_f32 v150, v182, s64, v195
	v_med3_f32 v148, v154, s64, v195
	v_med3_f32 v149, v155, s64, v195
	v_add_f32_e32 v148, 0x4b400000, v148
	v_add_f32_e32 v149, 0x4b400000, v149
	v_perm_b32 v148, v149, v148, s66
	v_or_b32_e32 v148, v144, v148
	s_waitcnt lgkmcnt(0)
	v_add_f32_e32 v144, v145, v146
	s_waitcnt lgkmcnt(0)
	v_add_f32_e32 v146, v147, v156
	v_mov_b32_e32 v145, v144
	s_nop 1
	v_permlane32_swap_b32_e32 v144, v145
	v_mov_b32_e32 v147, v146
	s_nop 1
	v_permlane32_swap_b32_e32 v146, v147
	v_med3_f32 v151, v183, s64, v195
	v_med3_f32 v154, v158, s64, v195
	v_med3_f32 v155, v159, s64, v195
	v_add_f32_e32 v150, 0x4b400000, v150
	v_add_f32_e32 v151, 0x4b400000, v151
	v_add_f32_e32 v154, 0x4b400000, v154
	v_add_f32_e32 v155, 0x4b400000, v155
	v_perm_b32 v149, v151, v150, s65
	v_perm_b32 v150, v155, v154, s66
	v_or_b32_e32 v149, v149, v150
	global_store_dwordx2 v[184:185], v[148:149], off offset:128
	s_and_saveexec_b64 s[6:7], s[2:3]
	s_cbranch_execz .LBB0_3863
	v_lshl_add_u64 v[148:149], s[12:13], 0, v[180:181]
	s_waitcnt lgkmcnt(0)
	v_add_f32_e32 v144, v144, v145
	s_waitcnt lgkmcnt(0)
	v_add_f32_e32 v145, v146, v147
	global_atomic_add_f32 v[148:149], v144, off
	global_atomic_add_f32 v[148:149], v145, off offset:4
.LBB0_3863:
	s_or_b64 exec, exec, s[6:7]
	v_or_b32_e32 v144, 16, v178
	s_waitcnt lgkmcnt(1)
	v_ashrrev_i32_e32 v145, 31, v144
	s_waitcnt lgkmcnt(0)
	v_lshlrev_b64 v[146:147], 11, v[144:145]
	v_lshlrev_b64 v[144:145], 3, v[144:145]
	v_lshl_add_u64 v[158:159], v[146:147], 0, v[176:177]
	v_lshl_add_u64 v[146:147], s[14:15], 0, v[144:145]
	global_load_dwordx2 v[180:181], v[146:147], off
	v_lshl_add_u64 v[146:147], v[158:159], 2, s[18:19]
	global_load_dwordx4 v[148:151], v[146:147], off nt
	global_load_dwordx4 v[154:157], v[146:147], off offset:16 nt
	global_load_dwordx4 v[228:231], v[146:147], off offset:512 nt
	global_load_dwordx4 v[232:235], v[146:147], off offset:528 nt
	v_lshl_add_u64 v[158:159], s[20:21], 0, v[158:159]
	s_waitcnt vmcnt(4)
	v_pk_mul_f32 v[180:181], v[180:181], s[28:29] op_sel_hi:[1,0]
	s_nop 0
	v_fma_f32 v179, -v180, v180, v181
	v_add_f32_e32 v179, 0x3727c5ac, v179
	v_rsq_f32_e32 v254, v179
	s_waitcnt vmcnt(3)
	v_sub_f32_e32 v151, v151, v180
	v_sub_f32_e32 v150, v150, v180
	v_sub_f32_e32 v149, v149, v180
	v_sub_f32_e32 v148, v148, v180
	s_waitcnt vmcnt(2)
; __device__ __forceinline__ u32x2 pack8i8(const f32x4 a, const f32x4 b) { return (u32x2){pack4i8(a), pack4i8(b)}; }
; __device__ __forceinline__ u32x4 pack8bf(const f32x4 a, const f32x4 b) { u32x4 w; w.x = cvt_pk_bf16(a[0], a[1]); w.y = cvt_pk_bf16(a[2], a[3]); w.z = cvt_pk_bf16(b[0], b[1]); w.w = cvt_pk_bf16(b[2], b[3]); return w; }
;     __device__ __forceinline__ void operator()(EPI_ARGS) const {
;     ...
;             for (int m = 0; m < 4; ++m) { const int row = row0 + ai * HALF + m * 16; const size_t off = (size_t)row * DM + col0;
;                 float mu = 0.f, rs = 1.f; if constexpr (RESLN) ln_stats(stin, row, mu, rs);
;                 float ss = 0.f, qq = 0.f;
; #pragma unroll
;                 for (int bj = 0; bj < 2; ++bj) { f32x4 r0 = __builtin_nontemporal_load((const f32x4*)(res + off + bj * HALF)), r1 = __builtin_nontemporal_load((const f32x4*)(res + off + bj * HALF + 4));
;                     if constexpr (RESLN) { r0 = (r0 - mu) * rs * gg[bj][0] + bb[bj][0]; r1 = (r1 - mu) * rs * gg[bj][1] + bb[bj][1]; }
;                     const f32x4 y0 = r0 * DN_ALPHA + acc[ai][bj][m][0] * ascale, y1 = r1 * DN_ALPHA + acc[ai][bj][m][1] * ascale;
;                     if constexpr (COPY != 4) { __builtin_nontemporal_store(y0, (f32x4*)(Y + off + bj * HALF)); __builtin_nontemporal_store(y1, (f32x4*)(Y + off + bj * HALF + 4)); }
;                     if constexpr (STATS) { ss += ((y0[0] + y0[1]) + (y0[2] + y0[3])) + ((y1[0] + y1[1]) + (y1[2] + y1[3]));
;                         qq += ((y0[0] * y0[0] + y0[1] * y0[1]) + (y0[2] * y0[2] + y0[3] * y0[3])) + ((y1[0] * y1[0] + y1[1] * y1[1]) + (y1[2] * y1[2] + y1[3] * y1[3])); }
;                     if constexpr (COPY == 1) *(u32x2*)((unsigned char*)copy + off + bj * HALF) = pack8fp8(y0 * cscale, y1 * cscale);
;                     if constexpr (COPY == 3) *(u32x2*)((unsigned char*)copy + off + bj * HALF) = pack8i8(y0 * cscale, y1 * cscale);
;                     if constexpr (COPY == 2 || COPY == 4) *(u32x4*)((bf16_t*)copy + off + bj * HALF) = pack8bf(y0, y1); }
;                 if constexpr (STATS) { ss += __shfl_xor(ss, 16); ss += __shfl_xor(ss, 32); qq += __shfl_xor(qq, 16); qq += __shfl_xor(qq, 32);
;                     if (fq == 0) { unsafeAtomicAdd(stout + 2 * (size_t)row, ss); unsafeAtomicAdd(stout + 2 * (size_t)row + 1, qq); } }
;                 asm volatile("" ::: "memory"); }
	v_sub_f32_e32 v157, v157, v180
	v_sub_f32_e32 v156, v156, v180
	v_sub_f32_e32 v155, v155, v180
	v_sub_f32_e32 v154, v154, v180
	s_nop 0
	s_nop 1
	v_mov_b32_e32 v182, v254
	v_pk_mul_f32 v[148:149], v[148:149], v[182:183] op_sel_hi:[1,0]
	v_pk_mul_f32 v[150:151], v[150:151], v[182:183] op_sel_hi:[1,0]
	v_pk_mul_f32 v[154:155], v[154:155], v[182:183] op_sel_hi:[1,0]
	v_pk_mul_f32 v[156:157], v[156:157], v[182:183] op_sel_hi:[1,0]
	v_pk_fma_f32 v[150:151], v[30:31], v[150:151], v[18:19]
	v_pk_fma_f32 v[148:149], v[28:29], v[148:149], v[16:17]
	v_pk_fma_f32 v[156:157], v[22:23], v[156:157], v[26:27]
	v_pk_fma_f32 v[154:155], v[20:21], v[154:155], v[24:25]
	v_pk_mul_f32 v[148:149], v[148:149], s[30:31] op_sel_hi:[1,0]
	v_pk_mul_f32 v[150:151], v[150:151], s[30:31] op_sel_hi:[1,0]
	v_pk_mul_f32 v[154:155], v[154:155], s[30:31] op_sel_hi:[1,0]
	v_pk_mul_f32 v[156:157], v[156:157], s[30:31] op_sel_hi:[1,0]
	v_pk_fma_f32 v[142:143], v[142:143], s[36:37], v[150:151] op_sel_hi:[1,0,1]
	v_pk_fma_f32 v[140:141], v[140:141], s[36:37], v[148:149] op_sel_hi:[1,0,1]
	v_pk_fma_f32 v[138:139], v[138:139], s[36:37], v[156:157] op_sel_hi:[1,0,1]
	v_pk_fma_f32 v[136:137], v[136:137], s[36:37], v[154:155] op_sel_hi:[1,0,1]
	v_pk_mul_f32 v[148:149], v[142:143], s[38:39] op_sel_hi:[1,0]
	v_pk_mul_f32 v[150:151], v[140:141], s[38:39] op_sel_hi:[1,0]
	v_pk_mul_f32 v[154:155], v[138:139], s[38:39] op_sel_hi:[1,0]
	v_pk_mul_f32 v[156:157], v[136:137], s[38:39] op_sel_hi:[1,0]
	v_med3_f32 v150, v150, s64, v195
	v_med3_f32 v151, v151, s64, v195
	v_med3_f32 v148, v148, s64, v195
	v_med3_f32 v149, v149, s64, v195
	v_med3_f32 v156, v156, s64, v195
	v_med3_f32 v157, v157, s64, v195
	v_med3_f32 v154, v154, s64, v195
	v_med3_f32 v155, v155, s64, v195
	v_add_f32_e32 v150, 0x4b400000, v150
	v_add_f32_e32 v151, 0x4b400000, v151
	v_add_f32_e32 v148, 0x4b400000, v148
	v_add_f32_e32 v149, 0x4b400000, v149
	v_add_f32_e32 v156, 0x4b400000, v156
	v_add_f32_e32 v157, 0x4b400000, v157
	v_add_f32_e32 v154, 0x4b400000, v154
	v_add_f32_e32 v155, 0x4b400000, v155
	v_perm_b32 v150, v151, v150, s65
	v_perm_b32 v148, v149, v148, s66
	v_perm_b32 v149, v157, v156, s65
	v_perm_b32 v151, v155, v154, s66
	v_or_b32_e32 v148, v150, v148
	v_or_b32_e32 v149, v149, v151
	global_store_dwordx4 v[146:147], v[140:143], off nt
	global_store_dwordx4 v[146:147], v[136:139], off offset:16 nt
	global_store_dwordx2 v[158:159], v[148:149], off
	s_waitcnt vmcnt(3)
	s_nop 1
	v_mov_b32_e32 v148, v228
	v_mov_b32_e32 v149, v229
	v_mov_b32_e32 v150, v230
	v_mov_b32_e32 v151, v231
	v_mov_b32_e32 v154, v232
	v_mov_b32_e32 v155, v233
	v_mov_b32_e32 v156, v234
	v_mov_b32_e32 v157, v235
	v_add_f32_e32 v179, v140, v141
	v_add_f32_e32 v181, v142, v143
	v_add_f32_e32 v183, v136, v137
	v_add_f32_e32 v184, v138, v139
	v_mul_f32_e32 v141, v141, v141
	v_mul_f32_e32 v143, v143, v143
	v_mul_f32_e32 v137, v137, v137
	v_mul_f32_e32 v139, v139, v139
	v_add_f32_e32 v179, v179, v181
	v_add_f32_e32 v181, v183, v184
	v_fmac_f32_e32 v141, v140, v140
	v_fmac_f32_e32 v143, v142, v142
	v_fmac_f32_e32 v137, v136, v136
	v_fmac_f32_e32 v139, v138, v138
	v_add_f32_e32 v136, v179, v181
	v_add_f32_e32 v138, v141, v143
	v_add_f32_e32 v137, v137, v139
	v_add_f32_e32 v179, 0, v136
	v_add_f32_e32 v181, v138, v137
	v_sub_f32_e32 v137, v151, v180
	v_sub_f32_e32 v136, v150, v180
	v_sub_f32_e32 v139, v149, v180
	v_sub_f32_e32 v138, v148, v180
	v_sub_f32_e32 v141, v157, v180
	v_sub_f32_e32 v140, v156, v180
	v_sub_f32_e32 v143, v155, v180
	v_sub_f32_e32 v142, v154, v180
	v_pk_mul_f32 v[138:139], v[138:139], v[182:183] op_sel_hi:[1,0]
	v_pk_mul_f32 v[136:137], v[136:137], v[182:183] op_sel_hi:[1,0]
	v_pk_mul_f32 v[142:143], v[142:143], v[182:183] op_sel_hi:[1,0]
	v_pk_mul_f32 v[140:141], v[140:141], v[182:183] op_sel_hi:[1,0]
	v_pk_fma_f32 v[136:137], v[10:11], v[136:137], v[14:15]
	v_pk_fma_f32 v[138:139], v[8:9], v[138:139], v[12:13]
	v_pk_fma_f32 v[140:141], v[2:3], v[140:141], v[6:7]
	v_pk_fma_f32 v[142:143], v[0:1], v[142:143], v[4:5]
	v_pk_mul_f32 v[138:139], v[138:139], s[30:31] op_sel_hi:[1,0]
	v_pk_mul_f32 v[136:137], v[136:137], s[30:31] op_sel_hi:[1,0]
	v_pk_mul_f32 v[142:143], v[142:143], s[30:31] op_sel_hi:[1,0]
	v_pk_mul_f32 v[140:141], v[140:141], s[30:31] op_sel_hi:[1,0]
	v_pk_fma_f32 v[134:135], v[134:135], s[36:37], v[136:137] op_sel_hi:[1,0,1]
	v_pk_fma_f32 v[132:133], v[132:133], s[36:37], v[138:139] op_sel_hi:[1,0,1]
	v_pk_fma_f32 v[130:131], v[130:131], s[36:37], v[140:141] op_sel_hi:[1,0,1]
	v_pk_fma_f32 v[128:129], v[128:129], s[36:37], v[142:143] op_sel_hi:[1,0,1]
	global_store_dwordx4 v[146:147], v[132:135], off offset:512 nt
	global_store_dwordx4 v[146:147], v[128:131], off offset:528 nt
	v_add_f32_e32 v146, v132, v133
	v_add_f32_e32 v147, v134, v135
	v_add_f32_e32 v148, v128, v129
	v_add_f32_e32 v149, v130, v131
	v_mul_f32_e32 v150, v133, v133
	v_mul_f32_e32 v151, v135, v135
	v_mul_f32_e32 v154, v129, v129
	v_mul_f32_e32 v155, v131, v131
	v_pk_mul_f32 v[138:139], v[132:133], s[38:39] op_sel_hi:[1,0]
	v_pk_mul_f32 v[140:141], v[130:131], s[38:39] op_sel_hi:[1,0]
	v_pk_mul_f32 v[142:143], v[128:129], s[38:39] op_sel_hi:[1,0]
	v_add_f32_e32 v129, v146, v147
	v_add_f32_e32 v131, v148, v149
	v_fmac_f32_e32 v150, v132, v132
	v_fmac_f32_e32 v151, v134, v134
	v_fmac_f32_e32 v154, v128, v128
	v_fmac_f32_e32 v155, v130, v130
	v_med3_f32 v128, v138, s64, v195
	v_add_f32_e32 v129, v129, v131
	v_add_f32_e32 v131, v150, v151
	v_add_f32_e32 v138, v154, v155
	v_med3_f32 v130, v139, s64, v195
	v_add_f32_e32 v131, v131, v138
	v_add_f32_e32 v128, 0x4b400000, v128
	v_add_f32_e32 v130, 0x4b400000, v130
	v_add_f32_e32 v129, v129, v179
	v_add_f32_e32 v131, v181, v131
	v_perm_b32 v128, v130, v128, s65
	v_mov_b32_e32 v130, v129
	s_nop 1
	v_permlane16_swap_b32_e32 v129, v130
	v_mov_b32_e32 v138, v131
	s_nop 1
	v_permlane16_swap_b32_e32 v131, v138
	v_pk_mul_f32 v[136:137], v[134:135], s[38:39] op_sel_hi:[1,0]
	v_med3_f32 v134, v142, s64, v195
	v_med3_f32 v132, v136, s64, v195
	v_med3_f32 v133, v137, s64, v195
	v_add_f32_e32 v132, 0x4b400000, v132
	v_add_f32_e32 v133, 0x4b400000, v133
	v_perm_b32 v132, v133, v132, s66
	v_or_b32_e32 v132, v128, v132
	s_waitcnt lgkmcnt(0)
	v_add_f32_e32 v128, v129, v130
	s_waitcnt lgkmcnt(0)
	v_add_f32_e32 v130, v131, v138
	v_mov_b32_e32 v129, v128
	s_nop 1
	v_permlane32_swap_b32_e32 v128, v129
	v_mov_b32_e32 v131, v130
	s_nop 1
	v_permlane32_swap_b32_e32 v130, v131
	v_med3_f32 v135, v143, s64, v195
	v_med3_f32 v136, v140, s64, v195
	v_med3_f32 v137, v141, s64, v195
	v_add_f32_e32 v134, 0x4b400000, v134
	v_add_f32_e32 v135, 0x4b400000, v135
	v_add_f32_e32 v136, 0x4b400000, v136
	v_add_f32_e32 v137, 0x4b400000, v137
	v_perm_b32 v133, v135, v134, s65
	v_perm_b32 v134, v137, v136, s66
	v_or_b32_e32 v133, v133, v134
	global_store_dwordx2 v[158:159], v[132:133], off offset:128
	s_and_saveexec_b64 s[6:7], s[2:3]
	s_cbranch_execz .LBB0_3865
; __device__ __forceinline__ u32x2 pack8i8(const f32x4 a, const f32x4 b) { return (u32x2){pack4i8(a), pack4i8(b)}; }
; __device__ __forceinline__ u32x4 pack8bf(const f32x4 a, const f32x4 b) { u32x4 w; w.x = cvt_pk_bf16(a[0], a[1]); w.y = cvt_pk_bf16(a[2], a[3]); w.z = cvt_pk_bf16(b[0], b[1]); w.w = cvt_pk_bf16(b[2], b[3]); return w; }
;     __device__ __forceinline__ void operator()(EPI_ARGS) const {
;     ...
;             for (int m = 0; m < 4; ++m) { const int row = row0 + ai * HALF + m * 16; const size_t off = (size_t)row * DM + col0;
;                 float mu = 0.f, rs = 1.f; if constexpr (RESLN) ln_stats(stin, row, mu, rs);
;                 float ss = 0.f, qq = 0.f;
; #pragma unroll
;                 for (int bj = 0; bj < 2; ++bj) { f32x4 r0 = __builtin_nontemporal_load((const f32x4*)(res + off + bj * HALF)), r1 = __builtin_nontemporal_load((const f32x4*)(res + off + bj * HALF + 4));
;                     if constexpr (RESLN) { r0 = (r0 - mu) * rs * gg[bj][0] + bb[bj][0]; r1 = (r1 - mu) * rs * gg[bj][1] + bb[bj][1]; }
;                     const f32x4 y0 = r0 * DN_ALPHA + acc[ai][bj][m][0] * ascale, y1 = r1 * DN_ALPHA + acc[ai][bj][m][1] * ascale;
;                     if constexpr (COPY != 4) { __builtin_nontemporal_store(y0, (f32x4*)(Y + off + bj * HALF)); __builtin_nontemporal_store(y1, (f32x4*)(Y + off + bj * HALF + 4)); }
;                     if constexpr (STATS) { ss += ((y0[0] + y0[1]) + (y0[2] + y0[3])) + ((y1[0] + y1[1]) + (y1[2] + y1[3]));
;                         qq += ((y0[0] * y0[0] + y0[1] * y0[1]) + (y0[2] * y0[2] + y0[3] * y0[3])) + ((y1[0] * y1[0] + y1[1] * y1[1]) + (y1[2] * y1[2] + y1[3] * y1[3])); }
;                     if constexpr (COPY == 1) *(u32x2*)((unsigned char*)copy + off + bj * HALF) = pack8fp8(y0 * cscale, y1 * cscale);
;                     if constexpr (COPY == 3) *(u32x2*)((unsigned char*)copy + off + bj * HALF) = pack8i8(y0 * cscale, y1 * cscale);
;                     if constexpr (COPY == 2 || COPY == 4) *(u32x4*)((bf16_t*)copy + off + bj * HALF) = pack8bf(y0, y1); }
;                 if constexpr (STATS) { ss += __shfl_xor(ss, 16); ss += __shfl_xor(ss, 32); qq += __shfl_xor(qq, 16); qq += __shfl_xor(qq, 32);
;                     if (fq == 0) { unsafeAtomicAdd(stout + 2 * (size_t)row, ss); unsafeAtomicAdd(stout + 2 * (size_t)row + 1, qq); } }
;                 asm volatile("" ::: "memory"); }
	v_lshl_add_u64 v[132:133], s[12:13], 0, v[144:145]
	s_waitcnt lgkmcnt(0)
	v_add_f32_e32 v128, v128, v129
	s_waitcnt lgkmcnt(0)
	v_add_f32_e32 v129, v130, v131
	global_atomic_add_f32 v[132:133], v128, off
	global_atomic_add_f32 v[132:133], v129, off offset:4
.LBB0_3865:
	s_or_b64 exec, exec, s[6:7]
	v_or_b32_e32 v128, 32, v178
	s_waitcnt lgkmcnt(1)
	v_ashrrev_i32_e32 v129, 31, v128
	s_waitcnt lgkmcnt(0)
	v_lshlrev_b64 v[130:131], 11, v[128:129]
	v_lshlrev_b64 v[128:129], 3, v[128:129]
	v_lshl_add_u64 v[140:141], v[130:131], 0, v[176:177]
	v_lshl_add_u64 v[130:131], s[14:15], 0, v[128:129]
	global_load_dwordx2 v[142:143], v[130:131], off
	v_lshl_add_u64 v[130:131], v[140:141], 2, s[18:19]
	global_load_dwordx4 v[132:135], v[130:131], off nt
	global_load_dwordx4 v[136:139], v[130:131], off offset:16 nt
	global_load_dwordx4 v[228:231], v[130:131], off offset:512 nt
	global_load_dwordx4 v[232:235], v[130:131], off offset:528 nt
	v_lshl_add_u64 v[140:141], s[20:21], 0, v[140:141]
	s_waitcnt vmcnt(4)
	v_pk_mul_f32 v[142:143], v[142:143], s[28:29] op_sel_hi:[1,0]
	s_nop 0
	v_fma_f32 v143, -v142, v142, v143
	v_add_f32_e32 v143, 0x3727c5ac, v143
	v_rsq_f32_e32 v254, v143
	s_waitcnt vmcnt(3)
	v_sub_f32_e32 v135, v135, v142
	v_sub_f32_e32 v134, v134, v142
	v_sub_f32_e32 v133, v133, v142
	v_sub_f32_e32 v132, v132, v142
	s_waitcnt vmcnt(2)
	v_sub_f32_e32 v139, v139, v142
	v_sub_f32_e32 v138, v138, v142
	v_sub_f32_e32 v137, v137, v142
	v_sub_f32_e32 v136, v136, v142
	s_nop 0
	s_nop 1
	v_mov_b32_e32 v144, v254
	v_pk_mul_f32 v[132:133], v[132:133], v[144:145] op_sel_hi:[1,0]
	v_pk_mul_f32 v[134:135], v[134:135], v[144:145] op_sel_hi:[1,0]
	v_pk_mul_f32 v[136:137], v[136:137], v[144:145] op_sel_hi:[1,0]
	v_pk_mul_f32 v[138:139], v[138:139], v[144:145] op_sel_hi:[1,0]
	v_pk_fma_f32 v[134:135], v[30:31], v[134:135], v[18:19]
	v_pk_fma_f32 v[132:133], v[28:29], v[132:133], v[16:17]
	v_pk_fma_f32 v[138:139], v[22:23], v[138:139], v[26:27]
	v_pk_fma_f32 v[136:137], v[20:21], v[136:137], v[24:25]
	v_pk_mul_f32 v[132:133], v[132:133], s[30:31] op_sel_hi:[1,0]
	v_pk_mul_f32 v[134:135], v[134:135], s[30:31] op_sel_hi:[1,0]
	v_pk_mul_f32 v[136:137], v[136:137], s[30:31] op_sel_hi:[1,0]
	v_pk_mul_f32 v[138:139], v[138:139], s[30:31] op_sel_hi:[1,0]
	v_pk_fma_f32 v[126:127], v[126:127], s[36:37], v[134:135] op_sel_hi:[1,0,1]
	v_pk_fma_f32 v[124:125], v[124:125], s[36:37], v[132:133] op_sel_hi:[1,0,1]
	v_pk_fma_f32 v[122:123], v[122:123], s[36:37], v[138:139] op_sel_hi:[1,0,1]
	v_pk_fma_f32 v[120:121], v[120:121], s[36:37], v[136:137] op_sel_hi:[1,0,1]
	v_pk_mul_f32 v[132:133], v[126:127], s[38:39] op_sel_hi:[1,0]
	v_pk_mul_f32 v[134:135], v[124:125], s[38:39] op_sel_hi:[1,0]
	v_pk_mul_f32 v[136:137], v[122:123], s[38:39] op_sel_hi:[1,0]
	v_pk_mul_f32 v[138:139], v[120:121], s[38:39] op_sel_hi:[1,0]
	v_med3_f32 v134, v134, s64, v195
	v_med3_f32 v135, v135, s64, v195
	v_med3_f32 v132, v132, s64, v195
	v_med3_f32 v133, v133, s64, v195
	v_med3_f32 v138, v138, s64, v195
	v_med3_f32 v139, v139, s64, v195
	v_med3_f32 v136, v136, s64, v195
	v_med3_f32 v137, v137, s64, v195
	v_add_f32_e32 v134, 0x4b400000, v134
	v_add_f32_e32 v135, 0x4b400000, v135
	v_add_f32_e32 v132, 0x4b400000, v132
	v_add_f32_e32 v133, 0x4b400000, v133
	v_add_f32_e32 v138, 0x4b400000, v138
	v_add_f32_e32 v139, 0x4b400000, v139
	v_add_f32_e32 v136, 0x4b400000, v136
	v_add_f32_e32 v137, 0x4b400000, v137
	v_perm_b32 v134, v135, v134, s65
	v_perm_b32 v132, v133, v132, s66
	v_perm_b32 v133, v139, v138, s65
	v_perm_b32 v135, v137, v136, s66
	v_or_b32_e32 v132, v134, v132
	v_or_b32_e32 v133, v133, v135
	global_store_dwordx4 v[130:131], v[124:127], off nt
	global_store_dwordx4 v[130:131], v[120:123], off offset:16 nt
	global_store_dwordx2 v[140:141], v[132:133], off
	s_waitcnt vmcnt(3)
	s_nop 1
	v_mov_b32_e32 v132, v228
	v_mov_b32_e32 v133, v229
	v_mov_b32_e32 v134, v230
	v_mov_b32_e32 v135, v231
	v_mov_b32_e32 v136, v232
	v_mov_b32_e32 v137, v233
	v_mov_b32_e32 v138, v234
	v_mov_b32_e32 v139, v235
	v_add_f32_e32 v143, v124, v125
	v_add_f32_e32 v145, v126, v127
	v_add_f32_e32 v146, v120, v121
	v_add_f32_e32 v147, v122, v123
	v_mul_f32_e32 v125, v125, v125
	v_mul_f32_e32 v127, v127, v127
	v_mul_f32_e32 v121, v121, v121
	v_mul_f32_e32 v123, v123, v123
	v_add_f32_e32 v143, v143, v145
	v_add_f32_e32 v145, v146, v147
	v_fmac_f32_e32 v125, v124, v124
	v_fmac_f32_e32 v127, v126, v126
	v_fmac_f32_e32 v121, v120, v120
	v_fmac_f32_e32 v123, v122, v122
	v_add_f32_e32 v120, v143, v145
	v_add_f32_e32 v122, v125, v127
	v_add_f32_e32 v121, v121, v123
	v_add_f32_e32 v143, 0, v120
	v_add_f32_e32 v145, v122, v121
	v_sub_f32_e32 v121, v135, v142
	v_sub_f32_e32 v120, v134, v142
	v_sub_f32_e32 v123, v133, v142
	v_sub_f32_e32 v122, v132, v142
	v_sub_f32_e32 v125, v139, v142
	v_sub_f32_e32 v124, v138, v142
	v_sub_f32_e32 v127, v137, v142
	v_sub_f32_e32 v126, v136, v142
	v_pk_mul_f32 v[122:123], v[122:123], v[144:145] op_sel_hi:[1,0]
	v_pk_mul_f32 v[120:121], v[120:121], v[144:145] op_sel_hi:[1,0]
	v_pk_mul_f32 v[126:127], v[126:127], v[144:145] op_sel_hi:[1,0]
	v_pk_mul_f32 v[124:125], v[124:125], v[144:145] op_sel_hi:[1,0]
	v_pk_fma_f32 v[120:121], v[10:11], v[120:121], v[14:15]
	v_pk_fma_f32 v[122:123], v[8:9], v[122:123], v[12:13]
	v_pk_fma_f32 v[124:125], v[2:3], v[124:125], v[6:7]
	v_pk_fma_f32 v[126:127], v[0:1], v[126:127], v[4:5]
	v_pk_mul_f32 v[122:123], v[122:123], s[30:31] op_sel_hi:[1,0]
	v_pk_mul_f32 v[120:121], v[120:121], s[30:31] op_sel_hi:[1,0]
	v_pk_mul_f32 v[126:127], v[126:127], s[30:31] op_sel_hi:[1,0]
	v_pk_mul_f32 v[124:125], v[124:125], s[30:31] op_sel_hi:[1,0]
	v_pk_fma_f32 v[118:119], v[118:119], s[36:37], v[120:121] op_sel_hi:[1,0,1]
; __device__ __forceinline__ u32x2 pack8i8(const f32x4 a, const f32x4 b) { return (u32x2){pack4i8(a), pack4i8(b)}; }
; __device__ __forceinline__ u32x4 pack8bf(const f32x4 a, const f32x4 b) { u32x4 w; w.x = cvt_pk_bf16(a[0], a[1]); w.y = cvt_pk_bf16(a[2], a[3]); w.z = cvt_pk_bf16(b[0], b[1]); w.w = cvt_pk_bf16(b[2], b[3]); return w; }
;     __device__ __forceinline__ void operator()(EPI_ARGS) const {
;     ...
;             for (int m = 0; m < 4; ++m) { const int row = row0 + ai * HALF + m * 16; const size_t off = (size_t)row * DM + col0;
;                 float mu = 0.f, rs = 1.f; if constexpr (RESLN) ln_stats(stin, row, mu, rs);
;                 float ss = 0.f, qq = 0.f;
; #pragma unroll
;                 for (int bj = 0; bj < 2; ++bj) { f32x4 r0 = __builtin_nontemporal_load((const f32x4*)(res + off + bj * HALF)), r1 = __builtin_nontemporal_load((const f32x4*)(res + off + bj * HALF + 4));
;                     if constexpr (RESLN) { r0 = (r0 - mu) * rs * gg[bj][0] + bb[bj][0]; r1 = (r1 - mu) * rs * gg[bj][1] + bb[bj][1]; }
;                     const f32x4 y0 = r0 * DN_ALPHA + acc[ai][bj][m][0] * ascale, y1 = r1 * DN_ALPHA + acc[ai][bj][m][1] * ascale;
;                     if constexpr (COPY != 4) { __builtin_nontemporal_store(y0, (f32x4*)(Y + off + bj * HALF)); __builtin_nontemporal_store(y1, (f32x4*)(Y + off + bj * HALF + 4)); }
;                     if constexpr (STATS) { ss += ((y0[0] + y0[1]) + (y0[2] + y0[3])) + ((y1[0] + y1[1]) + (y1[2] + y1[3]));
;                         qq += ((y0[0] * y0[0] + y0[1] * y0[1]) + (y0[2] * y0[2] + y0[3] * y0[3])) + ((y1[0] * y1[0] + y1[1] * y1[1]) + (y1[2] * y1[2] + y1[3] * y1[3])); }
;                     if constexpr (COPY == 1) *(u32x2*)((unsigned char*)copy + off + bj * HALF) = pack8fp8(y0 * cscale, y1 * cscale);
;                     if constexpr (COPY == 3) *(u32x2*)((unsigned char*)copy + off + bj * HALF) = pack8i8(y0 * cscale, y1 * cscale);
;                     if constexpr (COPY == 2 || COPY == 4) *(u32x4*)((bf16_t*)copy + off + bj * HALF) = pack8bf(y0, y1); }
;                 if constexpr (STATS) { ss += __shfl_xor(ss, 16); ss += __shfl_xor(ss, 32); qq += __shfl_xor(qq, 16); qq += __shfl_xor(qq, 32);
;                     if (fq == 0) { unsafeAtomicAdd(stout + 2 * (size_t)row, ss); unsafeAtomicAdd(stout + 2 * (size_t)row + 1, qq); } }
;                 asm volatile("" ::: "memory"); }
	v_pk_fma_f32 v[116:117], v[116:117], s[36:37], v[122:123] op_sel_hi:[1,0,1]
	v_pk_fma_f32 v[114:115], v[114:115], s[36:37], v[124:125] op_sel_hi:[1,0,1]
	v_pk_fma_f32 v[112:113], v[112:113], s[36:37], v[126:127] op_sel_hi:[1,0,1]
	global_store_dwordx4 v[130:131], v[116:119], off offset:512 nt
	global_store_dwordx4 v[130:131], v[112:115], off offset:528 nt
	v_add_f32_e32 v130, v116, v117
	v_add_f32_e32 v131, v118, v119
	v_add_f32_e32 v132, v112, v113
	v_add_f32_e32 v133, v114, v115
	v_mul_f32_e32 v134, v117, v117
	v_mul_f32_e32 v135, v119, v119
	v_mul_f32_e32 v136, v113, v113
	v_mul_f32_e32 v137, v115, v115
	v_pk_mul_f32 v[122:123], v[116:117], s[38:39] op_sel_hi:[1,0]
	v_pk_mul_f32 v[124:125], v[114:115], s[38:39] op_sel_hi:[1,0]
	v_pk_mul_f32 v[126:127], v[112:113], s[38:39] op_sel_hi:[1,0]
	v_add_f32_e32 v113, v130, v131
	v_add_f32_e32 v115, v132, v133
	v_fmac_f32_e32 v134, v116, v116
	v_fmac_f32_e32 v135, v118, v118
	v_fmac_f32_e32 v136, v112, v112
	v_fmac_f32_e32 v137, v114, v114
	v_med3_f32 v112, v122, s64, v195
	v_add_f32_e32 v113, v113, v115
	v_add_f32_e32 v115, v134, v135
	v_add_f32_e32 v122, v136, v137
	v_med3_f32 v114, v123, s64, v195
	v_add_f32_e32 v115, v115, v122
	v_add_f32_e32 v112, 0x4b400000, v112
	v_add_f32_e32 v114, 0x4b400000, v114
	v_add_f32_e32 v113, v113, v143
	v_add_f32_e32 v115, v145, v115
	v_perm_b32 v112, v114, v112, s65
	v_mov_b32_e32 v114, v113
	s_nop 1
	v_permlane16_swap_b32_e32 v113, v114
	v_mov_b32_e32 v122, v115
	s_nop 1
	v_permlane16_swap_b32_e32 v115, v122
	v_pk_mul_f32 v[120:121], v[118:119], s[38:39] op_sel_hi:[1,0]
	v_med3_f32 v118, v126, s64, v195
	v_med3_f32 v116, v120, s64, v195
	v_med3_f32 v117, v121, s64, v195
	v_add_f32_e32 v116, 0x4b400000, v116
	v_add_f32_e32 v117, 0x4b400000, v117
	v_perm_b32 v116, v117, v116, s66
	v_or_b32_e32 v116, v112, v116
	s_waitcnt lgkmcnt(0)
	v_add_f32_e32 v112, v113, v114
	s_waitcnt lgkmcnt(0)
	v_add_f32_e32 v114, v115, v122
	v_mov_b32_e32 v113, v112
	s_nop 1
	v_permlane32_swap_b32_e32 v112, v113
	v_mov_b32_e32 v115, v114
	s_nop 1
	v_permlane32_swap_b32_e32 v114, v115
	v_med3_f32 v119, v127, s64, v195
	v_med3_f32 v120, v124, s64, v195
	v_med3_f32 v121, v125, s64, v195
	v_add_f32_e32 v118, 0x4b400000, v118
	v_add_f32_e32 v119, 0x4b400000, v119
	v_add_f32_e32 v120, 0x4b400000, v120
	v_add_f32_e32 v121, 0x4b400000, v121
	v_perm_b32 v117, v119, v118, s65
	v_perm_b32 v118, v121, v120, s66
	v_or_b32_e32 v117, v117, v118
	global_store_dwordx2 v[140:141], v[116:117], off offset:128
	s_and_saveexec_b64 s[6:7], s[2:3]
	s_cbranch_execz .LBB0_3867
	v_lshl_add_u64 v[116:117], s[12:13], 0, v[128:129]
	s_waitcnt lgkmcnt(0)
	v_add_f32_e32 v112, v112, v113
	s_waitcnt lgkmcnt(0)
	v_add_f32_e32 v113, v114, v115
	global_atomic_add_f32 v[116:117], v112, off
	global_atomic_add_f32 v[116:117], v113, off offset:4
.LBB0_3867:
	s_or_b64 exec, exec, s[6:7]
	v_or_b32_e32 v112, 48, v178
	s_waitcnt lgkmcnt(1)
	v_ashrrev_i32_e32 v113, 31, v112
	s_waitcnt lgkmcnt(0)
	v_lshlrev_b64 v[114:115], 11, v[112:113]
	v_lshlrev_b64 v[112:113], 3, v[112:113]
	v_lshl_add_u64 v[124:125], v[114:115], 0, v[176:177]
	v_lshl_add_u64 v[114:115], s[14:15], 0, v[112:113]
	global_load_dwordx2 v[126:127], v[114:115], off
	v_lshl_add_u64 v[114:115], v[124:125], 2, s[18:19]
	global_load_dwordx4 v[116:119], v[114:115], off nt
	global_load_dwordx4 v[120:123], v[114:115], off offset:16 nt
	global_load_dwordx4 v[228:231], v[114:115], off offset:512 nt
	global_load_dwordx4 v[232:235], v[114:115], off offset:528 nt
	v_lshl_add_u64 v[124:125], s[20:21], 0, v[124:125]
	s_waitcnt vmcnt(4)
	v_pk_mul_f32 v[126:127], v[126:127], s[28:29] op_sel_hi:[1,0]
	s_nop 0
	v_fma_f32 v127, -v126, v126, v127
	v_add_f32_e32 v127, 0x3727c5ac, v127
	v_rsq_f32_e32 v254, v127
	s_waitcnt vmcnt(3)
	v_sub_f32_e32 v119, v119, v126
	v_sub_f32_e32 v118, v118, v126
	v_sub_f32_e32 v117, v117, v126
	v_sub_f32_e32 v116, v116, v126
	s_waitcnt vmcnt(2)
	v_sub_f32_e32 v123, v123, v126
	v_sub_f32_e32 v122, v122, v126
	v_sub_f32_e32 v121, v121, v126
	v_sub_f32_e32 v120, v120, v126
	s_nop 0
	s_nop 1
	v_mov_b32_e32 v128, v254
	v_pk_mul_f32 v[116:117], v[116:117], v[128:129] op_sel_hi:[1,0]
	v_pk_mul_f32 v[118:119], v[118:119], v[128:129] op_sel_hi:[1,0]
	v_pk_mul_f32 v[120:121], v[120:121], v[128:129] op_sel_hi:[1,0]
	v_pk_mul_f32 v[122:123], v[122:123], v[128:129] op_sel_hi:[1,0]
	v_pk_fma_f32 v[118:119], v[30:31], v[118:119], v[18:19]
	v_pk_fma_f32 v[116:117], v[28:29], v[116:117], v[16:17]
	v_pk_fma_f32 v[122:123], v[22:23], v[122:123], v[26:27]
	v_pk_fma_f32 v[120:121], v[20:21], v[120:121], v[24:25]
	v_pk_mul_f32 v[116:117], v[116:117], s[30:31] op_sel_hi:[1,0]
	v_pk_mul_f32 v[118:119], v[118:119], s[30:31] op_sel_hi:[1,0]
	v_pk_mul_f32 v[120:121], v[120:121], s[30:31] op_sel_hi:[1,0]
	v_pk_mul_f32 v[122:123], v[122:123], s[30:31] op_sel_hi:[1,0]
	v_pk_fma_f32 v[110:111], v[110:111], s[36:37], v[118:119] op_sel_hi:[1,0,1]
	v_pk_fma_f32 v[108:109], v[108:109], s[36:37], v[116:117] op_sel_hi:[1,0,1]
	v_pk_fma_f32 v[106:107], v[106:107], s[36:37], v[122:123] op_sel_hi:[1,0,1]
	v_pk_fma_f32 v[104:105], v[104:105], s[36:37], v[120:121] op_sel_hi:[1,0,1]
	v_pk_mul_f32 v[116:117], v[110:111], s[38:39] op_sel_hi:[1,0]
	v_pk_mul_f32 v[118:119], v[108:109], s[38:39] op_sel_hi:[1,0]
	v_pk_mul_f32 v[120:121], v[106:107], s[38:39] op_sel_hi:[1,0]
	v_pk_mul_f32 v[122:123], v[104:105], s[38:39] op_sel_hi:[1,0]
	v_med3_f32 v118, v118, s64, v195
	v_med3_f32 v119, v119, s64, v195
	v_med3_f32 v116, v116, s64, v195
	v_med3_f32 v117, v117, s64, v195
	v_med3_f32 v122, v122, s64, v195
	v_med3_f32 v123, v123, s64, v195
	v_med3_f32 v120, v120, s64, v195
	v_med3_f32 v121, v121, s64, v195
	v_add_f32_e32 v118, 0x4b400000, v118
	v_add_f32_e32 v119, 0x4b400000, v119
	v_add_f32_e32 v116, 0x4b400000, v116
	v_add_f32_e32 v117, 0x4b400000, v117
	v_add_f32_e32 v122, 0x4b400000, v122
	v_add_f32_e32 v123, 0x4b400000, v123
	v_add_f32_e32 v120, 0x4b400000, v120
	v_add_f32_e32 v121, 0x4b400000, v121
	v_perm_b32 v118, v119, v118, s65
	v_perm_b32 v116, v117, v116, s66
	v_perm_b32 v117, v123, v122, s65
	v_perm_b32 v119, v121, v120, s66
	v_or_b32_e32 v116, v118, v116
	v_or_b32_e32 v117, v117, v119
	global_store_dwordx4 v[114:115], v[108:111], off nt
	global_store_dwordx4 v[114:115], v[104:107], off offset:16 nt
	global_store_dwordx2 v[124:125], v[116:117], off
	s_waitcnt vmcnt(3)
; __device__ __forceinline__ u32x2 pack8i8(const f32x4 a, const f32x4 b) { return (u32x2){pack4i8(a), pack4i8(b)}; }
; __device__ __forceinline__ u32x4 pack8bf(const f32x4 a, const f32x4 b) { u32x4 w; w.x = cvt_pk_bf16(a[0], a[1]); w.y = cvt_pk_bf16(a[2], a[3]); w.z = cvt_pk_bf16(b[0], b[1]); w.w = cvt_pk_bf16(b[2], b[3]); return w; }
;     __device__ __forceinline__ void operator()(EPI_ARGS) const {
;     ...
;             for (int m = 0; m < 4; ++m) { const int row = row0 + ai * HALF + m * 16; const size_t off = (size_t)row * DM + col0;
;                 float mu = 0.f, rs = 1.f; if constexpr (RESLN) ln_stats(stin, row, mu, rs);
;                 float ss = 0.f, qq = 0.f;
; #pragma unroll
;                 for (int bj = 0; bj < 2; ++bj) { f32x4 r0 = __builtin_nontemporal_load((const f32x4*)(res + off + bj * HALF)), r1 = __builtin_nontemporal_load((const f32x4*)(res + off + bj * HALF + 4));
;                     if constexpr (RESLN) { r0 = (r0 - mu) * rs * gg[bj][0] + bb[bj][0]; r1 = (r1 - mu) * rs * gg[bj][1] + bb[bj][1]; }
;                     const f32x4 y0 = r0 * DN_ALPHA + acc[ai][bj][m][0] * ascale, y1 = r1 * DN_ALPHA + acc[ai][bj][m][1] * ascale;
;                     if constexpr (COPY != 4) { __builtin_nontemporal_store(y0, (f32x4*)(Y + off + bj * HALF)); __builtin_nontemporal_store(y1, (f32x4*)(Y + off + bj * HALF + 4)); }
;                     if constexpr (STATS) { ss += ((y0[0] + y0[1]) + (y0[2] + y0[3])) + ((y1[0] + y1[1]) + (y1[2] + y1[3]));
;                         qq += ((y0[0] * y0[0] + y0[1] * y0[1]) + (y0[2] * y0[2] + y0[3] * y0[3])) + ((y1[0] * y1[0] + y1[1] * y1[1]) + (y1[2] * y1[2] + y1[3] * y1[3])); }
;                     if constexpr (COPY == 1) *(u32x2*)((unsigned char*)copy + off + bj * HALF) = pack8fp8(y0 * cscale, y1 * cscale);
;                     if constexpr (COPY == 3) *(u32x2*)((unsigned char*)copy + off + bj * HALF) = pack8i8(y0 * cscale, y1 * cscale);
;                     if constexpr (COPY == 2 || COPY == 4) *(u32x4*)((bf16_t*)copy + off + bj * HALF) = pack8bf(y0, y1); }
;                 if constexpr (STATS) { ss += __shfl_xor(ss, 16); ss += __shfl_xor(ss, 32); qq += __shfl_xor(qq, 16); qq += __shfl_xor(qq, 32);
;                     if (fq == 0) { unsafeAtomicAdd(stout + 2 * (size_t)row, ss); unsafeAtomicAdd(stout + 2 * (size_t)row + 1, qq); } }
	s_nop 1
	v_mov_b32_e32 v116, v228
	v_mov_b32_e32 v117, v229
	v_mov_b32_e32 v118, v230
	v_mov_b32_e32 v119, v231
	v_mov_b32_e32 v120, v232
	v_mov_b32_e32 v121, v233
	v_mov_b32_e32 v122, v234
	v_mov_b32_e32 v123, v235
	v_add_f32_e32 v127, v108, v109
	v_add_f32_e32 v129, v110, v111
	v_add_f32_e32 v130, v104, v105
	v_add_f32_e32 v131, v106, v107
	v_mul_f32_e32 v109, v109, v109
	v_mul_f32_e32 v111, v111, v111
	v_mul_f32_e32 v105, v105, v105
	v_mul_f32_e32 v107, v107, v107
	v_add_f32_e32 v127, v127, v129
	v_add_f32_e32 v129, v130, v131
	v_fmac_f32_e32 v109, v108, v108
	v_fmac_f32_e32 v111, v110, v110
	v_fmac_f32_e32 v105, v104, v104
	v_fmac_f32_e32 v107, v106, v106
	v_add_f32_e32 v104, v127, v129
	v_add_f32_e32 v106, v109, v111
	v_add_f32_e32 v105, v105, v107
	v_add_f32_e32 v127, 0, v104
	v_add_f32_e32 v129, v106, v105
	v_sub_f32_e32 v105, v119, v126
	v_sub_f32_e32 v104, v118, v126
	v_sub_f32_e32 v107, v117, v126
	v_sub_f32_e32 v106, v116, v126
	v_sub_f32_e32 v109, v123, v126
	v_sub_f32_e32 v108, v122, v126
	v_sub_f32_e32 v111, v121, v126
	v_sub_f32_e32 v110, v120, v126
	v_pk_mul_f32 v[106:107], v[106:107], v[128:129] op_sel_hi:[1,0]
	v_pk_mul_f32 v[104:105], v[104:105], v[128:129] op_sel_hi:[1,0]
	v_pk_mul_f32 v[110:111], v[110:111], v[128:129] op_sel_hi:[1,0]
	v_pk_mul_f32 v[108:109], v[108:109], v[128:129] op_sel_hi:[1,0]
	v_pk_fma_f32 v[104:105], v[10:11], v[104:105], v[14:15]
	v_pk_fma_f32 v[106:107], v[8:9], v[106:107], v[12:13]
	v_pk_fma_f32 v[108:109], v[2:3], v[108:109], v[6:7]
	v_pk_fma_f32 v[110:111], v[0:1], v[110:111], v[4:5]
	v_pk_mul_f32 v[106:107], v[106:107], s[30:31] op_sel_hi:[1,0]
	v_pk_mul_f32 v[104:105], v[104:105], s[30:31] op_sel_hi:[1,0]
	v_pk_mul_f32 v[110:111], v[110:111], s[30:31] op_sel_hi:[1,0]
	v_pk_mul_f32 v[108:109], v[108:109], s[30:31] op_sel_hi:[1,0]
	v_pk_fma_f32 v[102:103], v[102:103], s[36:37], v[104:105] op_sel_hi:[1,0,1]
	v_pk_fma_f32 v[100:101], v[100:101], s[36:37], v[106:107] op_sel_hi:[1,0,1]
	v_pk_fma_f32 v[98:99], v[98:99], s[36:37], v[108:109] op_sel_hi:[1,0,1]
	v_pk_fma_f32 v[96:97], v[96:97], s[36:37], v[110:111] op_sel_hi:[1,0,1]
	global_store_dwordx4 v[114:115], v[100:103], off offset:512 nt
	global_store_dwordx4 v[114:115], v[96:99], off offset:528 nt
	v_add_f32_e32 v114, v100, v101
	v_add_f32_e32 v115, v102, v103
	v_add_f32_e32 v116, v96, v97
	v_add_f32_e32 v117, v98, v99
	v_mul_f32_e32 v118, v101, v101
	v_mul_f32_e32 v119, v103, v103
	v_mul_f32_e32 v120, v97, v97
	v_mul_f32_e32 v121, v99, v99
	v_pk_mul_f32 v[106:107], v[100:101], s[38:39] op_sel_hi:[1,0]
	v_pk_mul_f32 v[108:109], v[98:99], s[38:39] op_sel_hi:[1,0]
	v_pk_mul_f32 v[110:111], v[96:97], s[38:39] op_sel_hi:[1,0]
	v_add_f32_e32 v97, v114, v115
	v_add_f32_e32 v99, v116, v117
	v_fmac_f32_e32 v118, v100, v100
	v_fmac_f32_e32 v119, v102, v102
	v_fmac_f32_e32 v120, v96, v96
	v_fmac_f32_e32 v121, v98, v98
	v_med3_f32 v96, v106, s64, v195
	v_add_f32_e32 v97, v97, v99
	v_add_f32_e32 v99, v118, v119
	v_add_f32_e32 v106, v120, v121
	v_med3_f32 v98, v107, s64, v195
	v_add_f32_e32 v99, v99, v106
	v_add_f32_e32 v96, 0x4b400000, v96
	v_add_f32_e32 v98, 0x4b400000, v98
	v_add_f32_e32 v97, v97, v127
	v_add_f32_e32 v99, v129, v99
	v_perm_b32 v96, v98, v96, s65
	v_mov_b32_e32 v98, v97
	s_nop 1
	v_permlane16_swap_b32_e32 v97, v98
	v_mov_b32_e32 v106, v99
	s_nop 1
	v_permlane16_swap_b32_e32 v99, v106
	v_pk_mul_f32 v[104:105], v[102:103], s[38:39] op_sel_hi:[1,0]
	v_med3_f32 v102, v110, s64, v195
	v_med3_f32 v100, v104, s64, v195
	v_med3_f32 v101, v105, s64, v195
	v_add_f32_e32 v100, 0x4b400000, v100
	v_add_f32_e32 v101, 0x4b400000, v101
	v_perm_b32 v100, v101, v100, s66
	v_or_b32_e32 v100, v96, v100
	s_waitcnt lgkmcnt(0)
	v_add_f32_e32 v96, v97, v98
	s_waitcnt lgkmcnt(0)
	v_add_f32_e32 v98, v99, v106
	v_mov_b32_e32 v97, v96
	s_nop 1
	v_permlane32_swap_b32_e32 v96, v97
	v_mov_b32_e32 v99, v98
	s_nop 1
	v_permlane32_swap_b32_e32 v98, v99
	v_med3_f32 v103, v111, s64, v195
	v_med3_f32 v104, v108, s64, v195
	v_med3_f32 v105, v109, s64, v195
	v_add_f32_e32 v102, 0x4b400000, v102
	v_add_f32_e32 v103, 0x4b400000, v103
	v_add_f32_e32 v104, 0x4b400000, v104
	v_add_f32_e32 v105, 0x4b400000, v105
	v_perm_b32 v101, v103, v102, s65
	v_perm_b32 v102, v105, v104, s66
	v_or_b32_e32 v101, v101, v102
	global_store_dwordx2 v[124:125], v[100:101], off offset:128
	s_and_saveexec_b64 s[6:7], s[2:3]
	s_cbranch_execz .LBB0_3869
	v_lshl_add_u64 v[100:101], s[12:13], 0, v[112:113]
	s_waitcnt lgkmcnt(0)
	v_add_f32_e32 v96, v96, v97
	s_waitcnt lgkmcnt(0)
	v_add_f32_e32 v97, v98, v99
	global_atomic_add_f32 v[100:101], v96, off
	global_atomic_add_f32 v[100:101], v97, off offset:4
; __device__ __forceinline__ u32x2 pack8i8(const f32x4 a, const f32x4 b) { return (u32x2){pack4i8(a), pack4i8(b)}; }
; __device__ __forceinline__ u32x4 pack8bf(const f32x4 a, const f32x4 b) { u32x4 w; w.x = cvt_pk_bf16(a[0], a[1]); w.y = cvt_pk_bf16(a[2], a[3]); w.z = cvt_pk_bf16(b[0], b[1]); w.w = cvt_pk_bf16(b[2], b[3]); return w; }
;     __device__ __forceinline__ void operator()(EPI_ARGS) const {
;     ...
;             for (int m = 0; m < 4; ++m) { const int row = row0 + ai * HALF + m * 16; const size_t off = (size_t)row * DM + col0;
;                 float mu = 0.f, rs = 1.f; if constexpr (RESLN) ln_stats(stin, row, mu, rs);
;                 float ss = 0.f, qq = 0.f;
; #pragma unroll
;                 for (int bj = 0; bj < 2; ++bj) { f32x4 r0 = __builtin_nontemporal_load((const f32x4*)(res + off + bj * HALF)), r1 = __builtin_nontemporal_load((const f32x4*)(res + off + bj * HALF + 4));
;                     if constexpr (RESLN) { r0 = (r0 - mu) * rs * gg[bj][0] + bb[bj][0]; r1 = (r1 - mu) * rs * gg[bj][1] + bb[bj][1]; }
;                     const f32x4 y0 = r0 * DN_ALPHA + acc[ai][bj][m][0] * ascale, y1 = r1 * DN_ALPHA + acc[ai][bj][m][1] * ascale;
;                     if constexpr (COPY != 4) { __builtin_nontemporal_store(y0, (f32x4*)(Y + off + bj * HALF)); __builtin_nontemporal_store(y1, (f32x4*)(Y + off + bj * HALF + 4)); }
;                     if constexpr (STATS) { ss += ((y0[0] + y0[1]) + (y0[2] + y0[3])) + ((y1[0] + y1[1]) + (y1[2] + y1[3]));
;                         qq += ((y0[0] * y0[0] + y0[1] * y0[1]) + (y0[2] * y0[2] + y0[3] * y0[3])) + ((y1[0] * y1[0] + y1[1] * y1[1]) + (y1[2] * y1[2] + y1[3] * y1[3])); }
;                     if constexpr (COPY == 1) *(u32x2*)((unsigned char*)copy + off + bj * HALF) = pack8fp8(y0 * cscale, y1 * cscale);
;                     if constexpr (COPY == 3) *(u32x2*)((unsigned char*)copy + off + bj * HALF) = pack8i8(y0 * cscale, y1 * cscale);
;                     if constexpr (COPY == 2 || COPY == 4) *(u32x4*)((bf16_t*)copy + off + bj * HALF) = pack8bf(y0, y1); }
;                 if constexpr (STATS) { ss += __shfl_xor(ss, 16); ss += __shfl_xor(ss, 32); qq += __shfl_xor(qq, 16); qq += __shfl_xor(qq, 32);
;                     if (fq == 0) { unsafeAtomicAdd(stout + 2 * (size_t)row, ss); unsafeAtomicAdd(stout + 2 * (size_t)row + 1, qq); } }
;                 asm volatile("" ::: "memory"); }
.LBB0_3869:
	s_or_b64 exec, exec, s[6:7]
	v_add_u32_e32 v96, 0x80, v178
	s_waitcnt lgkmcnt(1)
	v_ashrrev_i32_e32 v97, 31, v96
	s_waitcnt lgkmcnt(0)
	v_lshlrev_b64 v[98:99], 11, v[96:97]
	v_lshlrev_b64 v[96:97], 3, v[96:97]
	v_lshl_add_u64 v[108:109], v[98:99], 0, v[176:177]
	v_lshl_add_u64 v[98:99], s[14:15], 0, v[96:97]
	global_load_dwordx2 v[110:111], v[98:99], off
	v_lshl_add_u64 v[98:99], v[108:109], 2, s[18:19]
	global_load_dwordx4 v[100:103], v[98:99], off nt
	global_load_dwordx4 v[104:107], v[98:99], off offset:16 nt
	global_load_dwordx4 v[228:231], v[98:99], off offset:512 nt
	global_load_dwordx4 v[232:235], v[98:99], off offset:528 nt
	v_lshl_add_u64 v[108:109], s[20:21], 0, v[108:109]
	s_waitcnt vmcnt(4)
	v_pk_mul_f32 v[110:111], v[110:111], s[28:29] op_sel_hi:[1,0]
	s_nop 0
	v_fma_f32 v111, -v110, v110, v111
	v_add_f32_e32 v111, 0x3727c5ac, v111
	v_rsq_f32_e32 v254, v111
	s_waitcnt vmcnt(3)
	v_sub_f32_e32 v103, v103, v110
	v_sub_f32_e32 v102, v102, v110
	v_sub_f32_e32 v101, v101, v110
	v_sub_f32_e32 v100, v100, v110
	s_waitcnt vmcnt(2)
	v_sub_f32_e32 v107, v107, v110
	v_sub_f32_e32 v106, v106, v110
	v_sub_f32_e32 v105, v105, v110
	v_sub_f32_e32 v104, v104, v110
	s_nop 0
	s_nop 1
	v_mov_b32_e32 v112, v254
	v_pk_mul_f32 v[100:101], v[100:101], v[112:113] op_sel_hi:[1,0]
	v_pk_mul_f32 v[102:103], v[102:103], v[112:113] op_sel_hi:[1,0]
	v_pk_mul_f32 v[104:105], v[104:105], v[112:113] op_sel_hi:[1,0]
	v_pk_mul_f32 v[106:107], v[106:107], v[112:113] op_sel_hi:[1,0]
	v_pk_fma_f32 v[102:103], v[30:31], v[102:103], v[18:19]
	v_pk_fma_f32 v[100:101], v[28:29], v[100:101], v[16:17]
	v_pk_fma_f32 v[106:107], v[22:23], v[106:107], v[26:27]
	v_pk_fma_f32 v[104:105], v[20:21], v[104:105], v[24:25]
	v_pk_mul_f32 v[100:101], v[100:101], s[30:31] op_sel_hi:[1,0]
	v_pk_mul_f32 v[102:103], v[102:103], s[30:31] op_sel_hi:[1,0]
	v_pk_mul_f32 v[104:105], v[104:105], s[30:31] op_sel_hi:[1,0]
	v_pk_mul_f32 v[106:107], v[106:107], s[30:31] op_sel_hi:[1,0]
	v_pk_fma_f32 v[94:95], v[94:95], s[36:37], v[102:103] op_sel_hi:[1,0,1]
	v_pk_fma_f32 v[92:93], v[92:93], s[36:37], v[100:101] op_sel_hi:[1,0,1]
	v_pk_fma_f32 v[90:91], v[90:91], s[36:37], v[106:107] op_sel_hi:[1,0,1]
	v_pk_fma_f32 v[88:89], v[88:89], s[36:37], v[104:105] op_sel_hi:[1,0,1]
	v_pk_mul_f32 v[100:101], v[94:95], s[38:39] op_sel_hi:[1,0]
	v_pk_mul_f32 v[102:103], v[92:93], s[38:39] op_sel_hi:[1,0]
	v_pk_mul_f32 v[104:105], v[90:91], s[38:39] op_sel_hi:[1,0]
	v_pk_mul_f32 v[106:107], v[88:89], s[38:39] op_sel_hi:[1,0]
	v_med3_f32 v102, v102, s64, v195
	v_med3_f32 v103, v103, s64, v195
	v_med3_f32 v100, v100, s64, v195
	v_med3_f32 v101, v101, s64, v195
	v_med3_f32 v106, v106, s64, v195
	v_med3_f32 v107, v107, s64, v195
	v_med3_f32 v104, v104, s64, v195
	v_med3_f32 v105, v105, s64, v195
	v_add_f32_e32 v102, 0x4b400000, v102
	v_add_f32_e32 v103, 0x4b400000, v103
	v_add_f32_e32 v100, 0x4b400000, v100
	v_add_f32_e32 v101, 0x4b400000, v101
	v_add_f32_e32 v106, 0x4b400000, v106
	v_add_f32_e32 v107, 0x4b400000, v107
	v_add_f32_e32 v104, 0x4b400000, v104
	v_add_f32_e32 v105, 0x4b400000, v105
	v_perm_b32 v102, v103, v102, s65
	v_perm_b32 v100, v101, v100, s66
	v_perm_b32 v101, v107, v106, s65
	v_perm_b32 v103, v105, v104, s66
	v_or_b32_e32 v100, v102, v100
	v_or_b32_e32 v101, v101, v103
	global_store_dwordx4 v[98:99], v[92:95], off nt
	global_store_dwordx4 v[98:99], v[88:91], off offset:16 nt
	global_store_dwordx2 v[108:109], v[100:101], off
	s_waitcnt vmcnt(3)
	s_nop 1
	v_mov_b32_e32 v100, v228
	v_mov_b32_e32 v101, v229
	v_mov_b32_e32 v102, v230
	v_mov_b32_e32 v103, v231
	v_mov_b32_e32 v104, v232
	v_mov_b32_e32 v105, v233
	v_mov_b32_e32 v106, v234
	v_mov_b32_e32 v107, v235
	v_add_f32_e32 v111, v92, v93
	v_add_f32_e32 v113, v94, v95
	v_add_f32_e32 v114, v88, v89
	v_add_f32_e32 v115, v90, v91
	v_mul_f32_e32 v93, v93, v93
	v_mul_f32_e32 v95, v95, v95
	v_mul_f32_e32 v89, v89, v89
	v_mul_f32_e32 v91, v91, v91
	v_add_f32_e32 v111, v111, v113
	v_add_f32_e32 v113, v114, v115
	v_fmac_f32_e32 v93, v92, v92
	v_fmac_f32_e32 v95, v94, v94
	v_fmac_f32_e32 v89, v88, v88
	v_fmac_f32_e32 v91, v90, v90
	v_add_f32_e32 v88, v111, v113
	v_add_f32_e32 v90, v93, v95
	v_add_f32_e32 v89, v89, v91
	v_add_f32_e32 v111, 0, v88
	v_add_f32_e32 v113, v90, v89
	v_sub_f32_e32 v89, v103, v110
	v_sub_f32_e32 v88, v102, v110
	v_sub_f32_e32 v91, v101, v110
	v_sub_f32_e32 v90, v100, v110
	v_sub_f32_e32 v93, v107, v110
	v_sub_f32_e32 v92, v106, v110
	v_sub_f32_e32 v95, v105, v110
	v_sub_f32_e32 v94, v104, v110
	v_pk_mul_f32 v[90:91], v[90:91], v[112:113] op_sel_hi:[1,0]
	v_pk_mul_f32 v[88:89], v[88:89], v[112:113] op_sel_hi:[1,0]
	v_pk_mul_f32 v[94:95], v[94:95], v[112:113] op_sel_hi:[1,0]
	v_pk_mul_f32 v[92:93], v[92:93], v[112:113] op_sel_hi:[1,0]
	v_pk_fma_f32 v[88:89], v[10:11], v[88:89], v[14:15]
	v_pk_fma_f32 v[90:91], v[8:9], v[90:91], v[12:13]
	v_pk_fma_f32 v[92:93], v[2:3], v[92:93], v[6:7]
	v_pk_fma_f32 v[94:95], v[0:1], v[94:95], v[4:5]
	v_pk_mul_f32 v[90:91], v[90:91], s[30:31] op_sel_hi:[1,0]
	v_pk_mul_f32 v[88:89], v[88:89], s[30:31] op_sel_hi:[1,0]
	v_pk_mul_f32 v[94:95], v[94:95], s[30:31] op_sel_hi:[1,0]
	v_pk_mul_f32 v[92:93], v[92:93], s[30:31] op_sel_hi:[1,0]
	v_pk_fma_f32 v[86:87], v[86:87], s[36:37], v[88:89] op_sel_hi:[1,0,1]
	v_pk_fma_f32 v[84:85], v[84:85], s[36:37], v[90:91] op_sel_hi:[1,0,1]
	v_pk_fma_f32 v[82:83], v[82:83], s[36:37], v[92:93] op_sel_hi:[1,0,1]
	v_pk_fma_f32 v[80:81], v[80:81], s[36:37], v[94:95] op_sel_hi:[1,0,1]
	global_store_dwordx4 v[98:99], v[84:87], off offset:512 nt
	global_store_dwordx4 v[98:99], v[80:83], off offset:528 nt
	v_add_f32_e32 v98, v84, v85
	v_add_f32_e32 v99, v86, v87
	v_add_f32_e32 v100, v80, v81
	v_add_f32_e32 v101, v82, v83
	v_mul_f32_e32 v102, v85, v85
	v_mul_f32_e32 v103, v87, v87
	v_mul_f32_e32 v104, v81, v81
	v_mul_f32_e32 v105, v83, v83
	v_pk_mul_f32 v[90:91], v[84:85], s[38:39] op_sel_hi:[1,0]
	v_pk_mul_f32 v[92:93], v[82:83], s[38:39] op_sel_hi:[1,0]
	v_pk_mul_f32 v[94:95], v[80:81], s[38:39] op_sel_hi:[1,0]
	v_add_f32_e32 v81, v98, v99
	v_add_f32_e32 v83, v100, v101
	v_fmac_f32_e32 v102, v84, v84
	v_fmac_f32_e32 v103, v86, v86
	v_fmac_f32_e32 v104, v80, v80
	v_fmac_f32_e32 v105, v82, v82
	v_med3_f32 v80, v90, s64, v195
	v_add_f32_e32 v81, v81, v83
	v_add_f32_e32 v83, v102, v103
	v_add_f32_e32 v90, v104, v105
	v_med3_f32 v82, v91, s64, v195
	v_add_f32_e32 v83, v83, v90
	v_add_f32_e32 v80, 0x4b400000, v80
	v_add_f32_e32 v82, 0x4b400000, v82
	v_add_f32_e32 v81, v81, v111
	v_add_f32_e32 v83, v113, v83
	v_perm_b32 v80, v82, v80, s65
	v_mov_b32_e32 v82, v81
	s_nop 1
	v_permlane16_swap_b32_e32 v81, v82
	v_mov_b32_e32 v90, v83
	s_nop 1
	v_permlane16_swap_b32_e32 v83, v90
	v_pk_mul_f32 v[88:89], v[86:87], s[38:39] op_sel_hi:[1,0]
	v_med3_f32 v86, v94, s64, v195
	v_med3_f32 v84, v88, s64, v195
	v_med3_f32 v85, v89, s64, v195
	v_add_f32_e32 v84, 0x4b400000, v84
	v_add_f32_e32 v85, 0x4b400000, v85
	v_perm_b32 v84, v85, v84, s66
	v_or_b32_e32 v84, v80, v84
	s_waitcnt lgkmcnt(0)
; __device__ __forceinline__ u32x2 pack8i8(const f32x4 a, const f32x4 b) { return (u32x2){pack4i8(a), pack4i8(b)}; }
; __device__ __forceinline__ u32x4 pack8bf(const f32x4 a, const f32x4 b) { u32x4 w; w.x = cvt_pk_bf16(a[0], a[1]); w.y = cvt_pk_bf16(a[2], a[3]); w.z = cvt_pk_bf16(b[0], b[1]); w.w = cvt_pk_bf16(b[2], b[3]); return w; }
;     __device__ __forceinline__ void operator()(EPI_ARGS) const {
;     ...
;             for (int m = 0; m < 4; ++m) { const int row = row0 + ai * HALF + m * 16; const size_t off = (size_t)row * DM + col0;
;                 float mu = 0.f, rs = 1.f; if constexpr (RESLN) ln_stats(stin, row, mu, rs);
;                 float ss = 0.f, qq = 0.f;
; #pragma unroll
;                 for (int bj = 0; bj < 2; ++bj) { f32x4 r0 = __builtin_nontemporal_load((const f32x4*)(res + off + bj * HALF)), r1 = __builtin_nontemporal_load((const f32x4*)(res + off + bj * HALF + 4));
;                     if constexpr (RESLN) { r0 = (r0 - mu) * rs * gg[bj][0] + bb[bj][0]; r1 = (r1 - mu) * rs * gg[bj][1] + bb[bj][1]; }
;                     const f32x4 y0 = r0 * DN_ALPHA + acc[ai][bj][m][0] * ascale, y1 = r1 * DN_ALPHA + acc[ai][bj][m][1] * ascale;
;                     if constexpr (COPY != 4) { __builtin_nontemporal_store(y0, (f32x4*)(Y + off + bj * HALF)); __builtin_nontemporal_store(y1, (f32x4*)(Y + off + bj * HALF + 4)); }
;                     if constexpr (STATS) { ss += ((y0[0] + y0[1]) + (y0[2] + y0[3])) + ((y1[0] + y1[1]) + (y1[2] + y1[3]));
;                         qq += ((y0[0] * y0[0] + y0[1] * y0[1]) + (y0[2] * y0[2] + y0[3] * y0[3])) + ((y1[0] * y1[0] + y1[1] * y1[1]) + (y1[2] * y1[2] + y1[3] * y1[3])); }
;                     if constexpr (COPY == 1) *(u32x2*)((unsigned char*)copy + off + bj * HALF) = pack8fp8(y0 * cscale, y1 * cscale);
;                     if constexpr (COPY == 3) *(u32x2*)((unsigned char*)copy + off + bj * HALF) = pack8i8(y0 * cscale, y1 * cscale);
;                     if constexpr (COPY == 2 || COPY == 4) *(u32x4*)((bf16_t*)copy + off + bj * HALF) = pack8bf(y0, y1); }
;                 if constexpr (STATS) { ss += __shfl_xor(ss, 16); ss += __shfl_xor(ss, 32); qq += __shfl_xor(qq, 16); qq += __shfl_xor(qq, 32);
;                     if (fq == 0) { unsafeAtomicAdd(stout + 2 * (size_t)row, ss); unsafeAtomicAdd(stout + 2 * (size_t)row + 1, qq); } }
;                 asm volatile("" ::: "memory"); }
	v_add_f32_e32 v80, v81, v82
	s_waitcnt lgkmcnt(0)
	v_add_f32_e32 v82, v83, v90
	v_mov_b32_e32 v81, v80
	s_nop 1
	v_permlane32_swap_b32_e32 v80, v81
	v_mov_b32_e32 v83, v82
	s_nop 1
	v_permlane32_swap_b32_e32 v82, v83
	v_med3_f32 v87, v95, s64, v195
	v_med3_f32 v88, v92, s64, v195
	v_med3_f32 v89, v93, s64, v195
	v_add_f32_e32 v86, 0x4b400000, v86
	v_add_f32_e32 v87, 0x4b400000, v87
	v_add_f32_e32 v88, 0x4b400000, v88
	v_add_f32_e32 v89, 0x4b400000, v89
	v_perm_b32 v85, v87, v86, s65
	v_perm_b32 v86, v89, v88, s66
	v_or_b32_e32 v85, v85, v86
	global_store_dwordx2 v[108:109], v[84:85], off offset:128
	s_and_saveexec_b64 s[6:7], s[2:3]
	s_cbranch_execz .LBB0_3871
	v_lshl_add_u64 v[84:85], s[12:13], 0, v[96:97]
	s_waitcnt lgkmcnt(0)
	v_add_f32_e32 v80, v80, v81
	s_waitcnt lgkmcnt(0)
	v_add_f32_e32 v81, v82, v83
	global_atomic_add_f32 v[84:85], v80, off
	global_atomic_add_f32 v[84:85], v81, off offset:4
.LBB0_3871:
	s_or_b64 exec, exec, s[6:7]
	v_add_u32_e32 v80, 0x90, v178
	s_waitcnt lgkmcnt(1)
	v_ashrrev_i32_e32 v81, 31, v80
	s_waitcnt lgkmcnt(0)
	v_lshlrev_b64 v[82:83], 11, v[80:81]
	v_lshlrev_b64 v[80:81], 3, v[80:81]
	v_lshl_add_u64 v[92:93], v[82:83], 0, v[176:177]
	v_lshl_add_u64 v[82:83], s[14:15], 0, v[80:81]
	global_load_dwordx2 v[94:95], v[82:83], off
	v_lshl_add_u64 v[82:83], v[92:93], 2, s[18:19]
	global_load_dwordx4 v[84:87], v[82:83], off nt
	global_load_dwordx4 v[88:91], v[82:83], off offset:16 nt
	global_load_dwordx4 v[228:231], v[82:83], off offset:512 nt
	global_load_dwordx4 v[232:235], v[82:83], off offset:528 nt
	v_lshl_add_u64 v[92:93], s[20:21], 0, v[92:93]
	s_waitcnt vmcnt(4)
	v_pk_mul_f32 v[94:95], v[94:95], s[28:29] op_sel_hi:[1,0]
	s_nop 0
	v_fma_f32 v95, -v94, v94, v95
	v_add_f32_e32 v95, 0x3727c5ac, v95
	v_rsq_f32_e32 v254, v95
	s_waitcnt vmcnt(3)
	v_sub_f32_e32 v87, v87, v94
	v_sub_f32_e32 v86, v86, v94
	v_sub_f32_e32 v85, v85, v94
	v_sub_f32_e32 v84, v84, v94
	s_waitcnt vmcnt(2)
	v_sub_f32_e32 v91, v91, v94
	v_sub_f32_e32 v90, v90, v94
	v_sub_f32_e32 v89, v89, v94
	v_sub_f32_e32 v88, v88, v94
	s_nop 0
	s_nop 1
	v_mov_b32_e32 v96, v254
	v_pk_mul_f32 v[84:85], v[84:85], v[96:97] op_sel_hi:[1,0]
	v_pk_mul_f32 v[86:87], v[86:87], v[96:97] op_sel_hi:[1,0]
	v_pk_mul_f32 v[88:89], v[88:89], v[96:97] op_sel_hi:[1,0]
	v_pk_mul_f32 v[90:91], v[90:91], v[96:97] op_sel_hi:[1,0]
	v_pk_fma_f32 v[86:87], v[30:31], v[86:87], v[18:19]
	v_pk_fma_f32 v[84:85], v[28:29], v[84:85], v[16:17]
	v_pk_fma_f32 v[90:91], v[22:23], v[90:91], v[26:27]
	v_pk_fma_f32 v[88:89], v[20:21], v[88:89], v[24:25]
	v_pk_mul_f32 v[84:85], v[84:85], s[30:31] op_sel_hi:[1,0]
	v_pk_mul_f32 v[86:87], v[86:87], s[30:31] op_sel_hi:[1,0]
	v_pk_mul_f32 v[88:89], v[88:89], s[30:31] op_sel_hi:[1,0]
	v_pk_mul_f32 v[90:91], v[90:91], s[30:31] op_sel_hi:[1,0]
	v_pk_fma_f32 v[78:79], v[78:79], s[36:37], v[86:87] op_sel_hi:[1,0,1]
	v_pk_fma_f32 v[76:77], v[76:77], s[36:37], v[84:85] op_sel_hi:[1,0,1]
	v_pk_fma_f32 v[74:75], v[74:75], s[36:37], v[90:91] op_sel_hi:[1,0,1]
	v_pk_fma_f32 v[72:73], v[72:73], s[36:37], v[88:89] op_sel_hi:[1,0,1]
	v_pk_mul_f32 v[84:85], v[78:79], s[38:39] op_sel_hi:[1,0]
	v_pk_mul_f32 v[86:87], v[76:77], s[38:39] op_sel_hi:[1,0]
	v_pk_mul_f32 v[88:89], v[74:75], s[38:39] op_sel_hi:[1,0]
	v_pk_mul_f32 v[90:91], v[72:73], s[38:39] op_sel_hi:[1,0]
	v_med3_f32 v86, v86, s64, v195
	v_med3_f32 v87, v87, s64, v195
	v_med3_f32 v84, v84, s64, v195
	v_med3_f32 v85, v85, s64, v195
	v_med3_f32 v90, v90, s64, v195
	v_med3_f32 v91, v91, s64, v195
	v_med3_f32 v88, v88, s64, v195
	v_med3_f32 v89, v89, s64, v195
	v_add_f32_e32 v86, 0x4b400000, v86
	v_add_f32_e32 v87, 0x4b400000, v87
	v_add_f32_e32 v84, 0x4b400000, v84
	v_add_f32_e32 v85, 0x4b400000, v85
	v_add_f32_e32 v90, 0x4b400000, v90
	v_add_f32_e32 v91, 0x4b400000, v91
	v_add_f32_e32 v88, 0x4b400000, v88
	v_add_f32_e32 v89, 0x4b400000, v89
	v_perm_b32 v86, v87, v86, s65
	v_perm_b32 v84, v85, v84, s66
	v_perm_b32 v85, v91, v90, s65
	v_perm_b32 v87, v89, v88, s66
	v_or_b32_e32 v84, v86, v84
	v_or_b32_e32 v85, v85, v87
	global_store_dwordx4 v[82:83], v[76:79], off nt
	global_store_dwordx4 v[82:83], v[72:75], off offset:16 nt
	global_store_dwordx2 v[92:93], v[84:85], off
	s_waitcnt vmcnt(3)
	s_nop 1
	v_mov_b32_e32 v84, v228
	v_mov_b32_e32 v85, v229
	v_mov_b32_e32 v86, v230
	v_mov_b32_e32 v87, v231
	v_mov_b32_e32 v88, v232
	v_mov_b32_e32 v89, v233
	v_mov_b32_e32 v90, v234
	v_mov_b32_e32 v91, v235
	v_add_f32_e32 v95, v76, v77
	v_add_f32_e32 v97, v78, v79
	v_add_f32_e32 v98, v72, v73
	v_add_f32_e32 v99, v74, v75
	v_mul_f32_e32 v77, v77, v77
	v_mul_f32_e32 v79, v79, v79
	v_mul_f32_e32 v73, v73, v73
	v_mul_f32_e32 v75, v75, v75
	v_add_f32_e32 v95, v95, v97
	v_add_f32_e32 v97, v98, v99
	v_fmac_f32_e32 v77, v76, v76
	v_fmac_f32_e32 v79, v78, v78
	v_fmac_f32_e32 v73, v72, v72
	v_fmac_f32_e32 v75, v74, v74
	v_add_f32_e32 v72, v95, v97
	v_add_f32_e32 v74, v77, v79
	v_add_f32_e32 v73, v73, v75
	v_add_f32_e32 v95, 0, v72
	v_add_f32_e32 v97, v74, v73
	v_sub_f32_e32 v73, v87, v94
	v_sub_f32_e32 v72, v86, v94
	v_sub_f32_e32 v75, v85, v94
	v_sub_f32_e32 v74, v84, v94
	v_sub_f32_e32 v77, v91, v94
	v_sub_f32_e32 v76, v90, v94
	v_sub_f32_e32 v79, v89, v94
	v_sub_f32_e32 v78, v88, v94
	v_pk_mul_f32 v[74:75], v[74:75], v[96:97] op_sel_hi:[1,0]
	v_pk_mul_f32 v[72:73], v[72:73], v[96:97] op_sel_hi:[1,0]
	v_pk_mul_f32 v[78:79], v[78:79], v[96:97] op_sel_hi:[1,0]
	v_pk_mul_f32 v[76:77], v[76:77], v[96:97] op_sel_hi:[1,0]
	v_pk_fma_f32 v[72:73], v[10:11], v[72:73], v[14:15]
	v_pk_fma_f32 v[74:75], v[8:9], v[74:75], v[12:13]
	v_pk_fma_f32 v[76:77], v[2:3], v[76:77], v[6:7]
	v_pk_fma_f32 v[78:79], v[0:1], v[78:79], v[4:5]
; __device__ __forceinline__ u32x2 pack8i8(const f32x4 a, const f32x4 b) { return (u32x2){pack4i8(a), pack4i8(b)}; }
; __device__ __forceinline__ u32x4 pack8bf(const f32x4 a, const f32x4 b) { u32x4 w; w.x = cvt_pk_bf16(a[0], a[1]); w.y = cvt_pk_bf16(a[2], a[3]); w.z = cvt_pk_bf16(b[0], b[1]); w.w = cvt_pk_bf16(b[2], b[3]); return w; }
;     __device__ __forceinline__ void operator()(EPI_ARGS) const {
;     ...
;             for (int m = 0; m < 4; ++m) { const int row = row0 + ai * HALF + m * 16; const size_t off = (size_t)row * DM + col0;
;                 float mu = 0.f, rs = 1.f; if constexpr (RESLN) ln_stats(stin, row, mu, rs);
;                 float ss = 0.f, qq = 0.f;
; #pragma unroll
;                 for (int bj = 0; bj < 2; ++bj) { f32x4 r0 = __builtin_nontemporal_load((const f32x4*)(res + off + bj * HALF)), r1 = __builtin_nontemporal_load((const f32x4*)(res + off + bj * HALF + 4));
;                     if constexpr (RESLN) { r0 = (r0 - mu) * rs * gg[bj][0] + bb[bj][0]; r1 = (r1 - mu) * rs * gg[bj][1] + bb[bj][1]; }
;                     const f32x4 y0 = r0 * DN_ALPHA + acc[ai][bj][m][0] * ascale, y1 = r1 * DN_ALPHA + acc[ai][bj][m][1] * ascale;
;                     if constexpr (COPY != 4) { __builtin_nontemporal_store(y0, (f32x4*)(Y + off + bj * HALF)); __builtin_nontemporal_store(y1, (f32x4*)(Y + off + bj * HALF + 4)); }
;                     if constexpr (STATS) { ss += ((y0[0] + y0[1]) + (y0[2] + y0[3])) + ((y1[0] + y1[1]) + (y1[2] + y1[3]));
;                         qq += ((y0[0] * y0[0] + y0[1] * y0[1]) + (y0[2] * y0[2] + y0[3] * y0[3])) + ((y1[0] * y1[0] + y1[1] * y1[1]) + (y1[2] * y1[2] + y1[3] * y1[3])); }
;                     if constexpr (COPY == 1) *(u32x2*)((unsigned char*)copy + off + bj * HALF) = pack8fp8(y0 * cscale, y1 * cscale);
;                     if constexpr (COPY == 3) *(u32x2*)((unsigned char*)copy + off + bj * HALF) = pack8i8(y0 * cscale, y1 * cscale);
;                     if constexpr (COPY == 2 || COPY == 4) *(u32x4*)((bf16_t*)copy + off + bj * HALF) = pack8bf(y0, y1); }
;                 if constexpr (STATS) { ss += __shfl_xor(ss, 16); ss += __shfl_xor(ss, 32); qq += __shfl_xor(qq, 16); qq += __shfl_xor(qq, 32);
;                     if (fq == 0) { unsafeAtomicAdd(stout + 2 * (size_t)row, ss); unsafeAtomicAdd(stout + 2 * (size_t)row + 1, qq); } }
;                 asm volatile("" ::: "memory"); }
	v_pk_mul_f32 v[74:75], v[74:75], s[30:31] op_sel_hi:[1,0]
	v_pk_mul_f32 v[72:73], v[72:73], s[30:31] op_sel_hi:[1,0]
	v_pk_mul_f32 v[78:79], v[78:79], s[30:31] op_sel_hi:[1,0]
	v_pk_mul_f32 v[76:77], v[76:77], s[30:31] op_sel_hi:[1,0]
	v_pk_fma_f32 v[70:71], v[70:71], s[36:37], v[72:73] op_sel_hi:[1,0,1]
	v_pk_fma_f32 v[68:69], v[68:69], s[36:37], v[74:75] op_sel_hi:[1,0,1]
	v_pk_fma_f32 v[66:67], v[66:67], s[36:37], v[76:77] op_sel_hi:[1,0,1]
	v_pk_fma_f32 v[64:65], v[64:65], s[36:37], v[78:79] op_sel_hi:[1,0,1]
	global_store_dwordx4 v[82:83], v[68:71], off offset:512 nt
	global_store_dwordx4 v[82:83], v[64:67], off offset:528 nt
	v_add_f32_e32 v82, v68, v69
	v_add_f32_e32 v83, v70, v71
	v_add_f32_e32 v84, v64, v65
	v_add_f32_e32 v85, v66, v67
	v_mul_f32_e32 v86, v69, v69
	v_mul_f32_e32 v87, v71, v71
	v_mul_f32_e32 v88, v65, v65
	v_mul_f32_e32 v89, v67, v67
	v_pk_mul_f32 v[74:75], v[68:69], s[38:39] op_sel_hi:[1,0]
	v_pk_mul_f32 v[76:77], v[66:67], s[38:39] op_sel_hi:[1,0]
	v_pk_mul_f32 v[78:79], v[64:65], s[38:39] op_sel_hi:[1,0]
	v_add_f32_e32 v65, v82, v83
	v_add_f32_e32 v67, v84, v85
	v_fmac_f32_e32 v86, v68, v68
	v_fmac_f32_e32 v87, v70, v70
	v_fmac_f32_e32 v88, v64, v64
	v_fmac_f32_e32 v89, v66, v66
	v_med3_f32 v64, v74, s64, v195
	v_add_f32_e32 v65, v65, v67
	v_add_f32_e32 v67, v86, v87
	v_add_f32_e32 v74, v88, v89
	v_med3_f32 v66, v75, s64, v195
	v_add_f32_e32 v67, v67, v74
	v_add_f32_e32 v64, 0x4b400000, v64
	v_add_f32_e32 v66, 0x4b400000, v66
	v_add_f32_e32 v65, v65, v95
	v_add_f32_e32 v67, v97, v67
	v_perm_b32 v64, v66, v64, s65
	v_mov_b32_e32 v66, v65
	s_nop 1
	v_permlane16_swap_b32_e32 v65, v66
	v_mov_b32_e32 v74, v67
	s_nop 1
	v_permlane16_swap_b32_e32 v67, v74
	v_pk_mul_f32 v[72:73], v[70:71], s[38:39] op_sel_hi:[1,0]
	v_med3_f32 v70, v78, s64, v195
	v_med3_f32 v68, v72, s64, v195
	v_med3_f32 v69, v73, s64, v195
	v_add_f32_e32 v68, 0x4b400000, v68
	v_add_f32_e32 v69, 0x4b400000, v69
	v_perm_b32 v68, v69, v68, s66
	v_or_b32_e32 v68, v64, v68
	s_waitcnt lgkmcnt(0)
	v_add_f32_e32 v64, v65, v66
	s_waitcnt lgkmcnt(0)
	v_add_f32_e32 v66, v67, v74
	v_mov_b32_e32 v65, v64
	s_nop 1
	v_permlane32_swap_b32_e32 v64, v65
	v_mov_b32_e32 v67, v66
	s_nop 1
	v_permlane32_swap_b32_e32 v66, v67
	v_med3_f32 v71, v79, s64, v195
	v_med3_f32 v72, v76, s64, v195
	v_med3_f32 v73, v77, s64, v195
	v_add_f32_e32 v70, 0x4b400000, v70
	v_add_f32_e32 v71, 0x4b400000, v71
	v_add_f32_e32 v72, 0x4b400000, v72
	v_add_f32_e32 v73, 0x4b400000, v73
	v_perm_b32 v69, v71, v70, s65
	v_perm_b32 v70, v73, v72, s66
	v_or_b32_e32 v69, v69, v70
	global_store_dwordx2 v[92:93], v[68:69], off offset:128
	s_and_saveexec_b64 s[6:7], s[2:3]
	s_cbranch_execz .LBB0_3873
	v_lshl_add_u64 v[68:69], s[12:13], 0, v[80:81]
	s_waitcnt lgkmcnt(0)
	v_add_f32_e32 v64, v64, v65
	s_waitcnt lgkmcnt(0)
	v_add_f32_e32 v65, v66, v67
	global_atomic_add_f32 v[68:69], v64, off
	global_atomic_add_f32 v[68:69], v65, off offset:4
.LBB0_3873:
	s_or_b64 exec, exec, s[6:7]
	v_add_u32_e32 v64, 0xa0, v178
	s_waitcnt lgkmcnt(1)
	v_ashrrev_i32_e32 v65, 31, v64
	s_waitcnt lgkmcnt(0)
	v_lshlrev_b64 v[66:67], 11, v[64:65]
	v_lshlrev_b64 v[64:65], 3, v[64:65]
	v_lshl_add_u64 v[76:77], v[66:67], 0, v[176:177]
	v_lshl_add_u64 v[66:67], s[14:15], 0, v[64:65]
	global_load_dwordx2 v[78:79], v[66:67], off
	v_lshl_add_u64 v[66:67], v[76:77], 2, s[18:19]
	global_load_dwordx4 v[68:71], v[66:67], off nt
	global_load_dwordx4 v[72:75], v[66:67], off offset:16 nt
	global_load_dwordx4 v[228:231], v[66:67], off offset:512 nt
	global_load_dwordx4 v[232:235], v[66:67], off offset:528 nt
	v_lshl_add_u64 v[76:77], s[20:21], 0, v[76:77]
	s_waitcnt vmcnt(4)
	v_pk_mul_f32 v[78:79], v[78:79], s[28:29] op_sel_hi:[1,0]
	s_nop 0
	v_fma_f32 v79, -v78, v78, v79
	v_add_f32_e32 v79, 0x3727c5ac, v79
	v_rsq_f32_e32 v254, v79
	s_waitcnt vmcnt(3)
	v_sub_f32_e32 v71, v71, v78
	v_sub_f32_e32 v70, v70, v78
	v_sub_f32_e32 v69, v69, v78
	v_sub_f32_e32 v68, v68, v78
	s_waitcnt vmcnt(2)
	v_sub_f32_e32 v75, v75, v78
	v_sub_f32_e32 v74, v74, v78
	v_sub_f32_e32 v73, v73, v78
	v_sub_f32_e32 v72, v72, v78
	s_nop 0
	s_nop 1
	v_mov_b32_e32 v80, v254
	v_pk_mul_f32 v[68:69], v[68:69], v[80:81] op_sel_hi:[1,0]
	v_pk_mul_f32 v[70:71], v[70:71], v[80:81] op_sel_hi:[1,0]
	v_pk_mul_f32 v[72:73], v[72:73], v[80:81] op_sel_hi:[1,0]
	v_pk_mul_f32 v[74:75], v[74:75], v[80:81] op_sel_hi:[1,0]
	v_pk_fma_f32 v[70:71], v[30:31], v[70:71], v[18:19]
	v_pk_fma_f32 v[68:69], v[28:29], v[68:69], v[16:17]
	v_pk_fma_f32 v[74:75], v[22:23], v[74:75], v[26:27]
	v_pk_fma_f32 v[72:73], v[20:21], v[72:73], v[24:25]
	v_pk_mul_f32 v[68:69], v[68:69], s[30:31] op_sel_hi:[1,0]
	v_pk_mul_f32 v[70:71], v[70:71], s[30:31] op_sel_hi:[1,0]
	v_pk_mul_f32 v[72:73], v[72:73], s[30:31] op_sel_hi:[1,0]
	v_pk_mul_f32 v[74:75], v[74:75], s[30:31] op_sel_hi:[1,0]
	v_pk_fma_f32 v[62:63], v[62:63], s[36:37], v[70:71] op_sel_hi:[1,0,1]
	v_pk_fma_f32 v[60:61], v[60:61], s[36:37], v[68:69] op_sel_hi:[1,0,1]
	v_pk_fma_f32 v[58:59], v[58:59], s[36:37], v[74:75] op_sel_hi:[1,0,1]
	v_pk_fma_f32 v[56:57], v[56:57], s[36:37], v[72:73] op_sel_hi:[1,0,1]
	v_pk_mul_f32 v[68:69], v[62:63], s[38:39] op_sel_hi:[1,0]
	v_pk_mul_f32 v[70:71], v[60:61], s[38:39] op_sel_hi:[1,0]
	v_pk_mul_f32 v[72:73], v[58:59], s[38:39] op_sel_hi:[1,0]
	v_pk_mul_f32 v[74:75], v[56:57], s[38:39] op_sel_hi:[1,0]
	v_med3_f32 v70, v70, s64, v195
	v_med3_f32 v71, v71, s64, v195
	v_med3_f32 v68, v68, s64, v195
	v_med3_f32 v69, v69, s64, v195
	v_med3_f32 v74, v74, s64, v195
	v_med3_f32 v75, v75, s64, v195
	v_med3_f32 v72, v72, s64, v195
	v_med3_f32 v73, v73, s64, v195
	v_add_f32_e32 v70, 0x4b400000, v70
	v_add_f32_e32 v71, 0x4b400000, v71
	v_add_f32_e32 v68, 0x4b400000, v68
	v_add_f32_e32 v69, 0x4b400000, v69
	v_add_f32_e32 v74, 0x4b400000, v74
	v_add_f32_e32 v75, 0x4b400000, v75
	v_add_f32_e32 v72, 0x4b400000, v72
	v_add_f32_e32 v73, 0x4b400000, v73
	v_perm_b32 v70, v71, v70, s65
	v_perm_b32 v68, v69, v68, s66
	v_perm_b32 v69, v75, v74, s65
	v_perm_b32 v71, v73, v72, s66
	v_or_b32_e32 v68, v70, v68
	v_or_b32_e32 v69, v69, v71
	global_store_dwordx4 v[66:67], v[60:63], off nt
	global_store_dwordx4 v[66:67], v[56:59], off offset:16 nt
	global_store_dwordx2 v[76:77], v[68:69], off
	s_waitcnt vmcnt(3)
; __device__ __forceinline__ u32x2 pack8i8(const f32x4 a, const f32x4 b) { return (u32x2){pack4i8(a), pack4i8(b)}; }
; __device__ __forceinline__ u32x4 pack8bf(const f32x4 a, const f32x4 b) { u32x4 w; w.x = cvt_pk_bf16(a[0], a[1]); w.y = cvt_pk_bf16(a[2], a[3]); w.z = cvt_pk_bf16(b[0], b[1]); w.w = cvt_pk_bf16(b[2], b[3]); return w; }
;     __device__ __forceinline__ void operator()(EPI_ARGS) const {
;     ...
;             for (int m = 0; m < 4; ++m) { const int row = row0 + ai * HALF + m * 16; const size_t off = (size_t)row * DM + col0;
;                 float mu = 0.f, rs = 1.f; if constexpr (RESLN) ln_stats(stin, row, mu, rs);
;                 float ss = 0.f, qq = 0.f;
; #pragma unroll
;                 for (int bj = 0; bj < 2; ++bj) { f32x4 r0 = __builtin_nontemporal_load((const f32x4*)(res + off + bj * HALF)), r1 = __builtin_nontemporal_load((const f32x4*)(res + off + bj * HALF + 4));
;                     if constexpr (RESLN) { r0 = (r0 - mu) * rs * gg[bj][0] + bb[bj][0]; r1 = (r1 - mu) * rs * gg[bj][1] + bb[bj][1]; }
;                     const f32x4 y0 = r0 * DN_ALPHA + acc[ai][bj][m][0] * ascale, y1 = r1 * DN_ALPHA + acc[ai][bj][m][1] * ascale;
;                     if constexpr (COPY != 4) { __builtin_nontemporal_store(y0, (f32x4*)(Y + off + bj * HALF)); __builtin_nontemporal_store(y1, (f32x4*)(Y + off + bj * HALF + 4)); }
;                     if constexpr (STATS) { ss += ((y0[0] + y0[1]) + (y0[2] + y0[3])) + ((y1[0] + y1[1]) + (y1[2] + y1[3]));
;                         qq += ((y0[0] * y0[0] + y0[1] * y0[1]) + (y0[2] * y0[2] + y0[3] * y0[3])) + ((y1[0] * y1[0] + y1[1] * y1[1]) + (y1[2] * y1[2] + y1[3] * y1[3])); }
;                     if constexpr (COPY == 1) *(u32x2*)((unsigned char*)copy + off + bj * HALF) = pack8fp8(y0 * cscale, y1 * cscale);
;                     if constexpr (COPY == 3) *(u32x2*)((unsigned char*)copy + off + bj * HALF) = pack8i8(y0 * cscale, y1 * cscale);
;                     if constexpr (COPY == 2 || COPY == 4) *(u32x4*)((bf16_t*)copy + off + bj * HALF) = pack8bf(y0, y1); }
;                 if constexpr (STATS) { ss += __shfl_xor(ss, 16); ss += __shfl_xor(ss, 32); qq += __shfl_xor(qq, 16); qq += __shfl_xor(qq, 32);
;                     if (fq == 0) { unsafeAtomicAdd(stout + 2 * (size_t)row, ss); unsafeAtomicAdd(stout + 2 * (size_t)row + 1, qq); } }
	s_nop 1
	v_mov_b32_e32 v68, v228
	v_mov_b32_e32 v69, v229
	v_mov_b32_e32 v70, v230
	v_mov_b32_e32 v71, v231
	v_mov_b32_e32 v72, v232
	v_mov_b32_e32 v73, v233
	v_mov_b32_e32 v74, v234
	v_mov_b32_e32 v75, v235
	v_add_f32_e32 v79, v60, v61
	v_add_f32_e32 v81, v62, v63
	v_add_f32_e32 v82, v56, v57
	v_add_f32_e32 v83, v58, v59
	v_mul_f32_e32 v61, v61, v61
	v_mul_f32_e32 v63, v63, v63
	v_mul_f32_e32 v57, v57, v57
	v_mul_f32_e32 v59, v59, v59
	v_add_f32_e32 v79, v79, v81
	v_add_f32_e32 v81, v82, v83
	v_fmac_f32_e32 v61, v60, v60
	v_fmac_f32_e32 v63, v62, v62
	v_fmac_f32_e32 v57, v56, v56
	v_fmac_f32_e32 v59, v58, v58
	v_add_f32_e32 v56, v79, v81
	v_add_f32_e32 v58, v61, v63
	v_add_f32_e32 v57, v57, v59
	v_add_f32_e32 v79, 0, v56
	v_add_f32_e32 v81, v58, v57
	v_sub_f32_e32 v57, v71, v78
	v_sub_f32_e32 v56, v70, v78
	v_sub_f32_e32 v59, v69, v78
	v_sub_f32_e32 v58, v68, v78
	v_sub_f32_e32 v61, v75, v78
	v_sub_f32_e32 v60, v74, v78
	v_sub_f32_e32 v63, v73, v78
	v_sub_f32_e32 v62, v72, v78
	v_pk_mul_f32 v[58:59], v[58:59], v[80:81] op_sel_hi:[1,0]
	v_pk_mul_f32 v[56:57], v[56:57], v[80:81] op_sel_hi:[1,0]
	v_pk_mul_f32 v[62:63], v[62:63], v[80:81] op_sel_hi:[1,0]
	v_pk_mul_f32 v[60:61], v[60:61], v[80:81] op_sel_hi:[1,0]
	v_pk_fma_f32 v[56:57], v[10:11], v[56:57], v[14:15]
	v_pk_fma_f32 v[58:59], v[8:9], v[58:59], v[12:13]
	v_pk_fma_f32 v[60:61], v[2:3], v[60:61], v[6:7]
	v_pk_fma_f32 v[62:63], v[0:1], v[62:63], v[4:5]
	v_pk_mul_f32 v[58:59], v[58:59], s[30:31] op_sel_hi:[1,0]
	v_pk_mul_f32 v[56:57], v[56:57], s[30:31] op_sel_hi:[1,0]
	v_pk_mul_f32 v[62:63], v[62:63], s[30:31] op_sel_hi:[1,0]
	v_pk_mul_f32 v[60:61], v[60:61], s[30:31] op_sel_hi:[1,0]
	v_pk_fma_f32 v[54:55], v[54:55], s[36:37], v[56:57] op_sel_hi:[1,0,1]
	v_pk_fma_f32 v[52:53], v[52:53], s[36:37], v[58:59] op_sel_hi:[1,0,1]
	v_pk_fma_f32 v[50:51], v[50:51], s[36:37], v[60:61] op_sel_hi:[1,0,1]
	v_pk_fma_f32 v[48:49], v[48:49], s[36:37], v[62:63] op_sel_hi:[1,0,1]
	global_store_dwordx4 v[66:67], v[52:55], off offset:512 nt
	global_store_dwordx4 v[66:67], v[48:51], off offset:528 nt
	v_add_f32_e32 v66, v52, v53
	v_add_f32_e32 v67, v54, v55
	v_add_f32_e32 v68, v48, v49
	v_add_f32_e32 v69, v50, v51
	v_mul_f32_e32 v70, v53, v53
	v_mul_f32_e32 v71, v55, v55
	v_mul_f32_e32 v72, v49, v49
	v_mul_f32_e32 v73, v51, v51
	v_pk_mul_f32 v[58:59], v[52:53], s[38:39] op_sel_hi:[1,0]
	v_pk_mul_f32 v[60:61], v[50:51], s[38:39] op_sel_hi:[1,0]
	v_pk_mul_f32 v[62:63], v[48:49], s[38:39] op_sel_hi:[1,0]
	v_add_f32_e32 v49, v66, v67
	v_add_f32_e32 v51, v68, v69
	v_fmac_f32_e32 v70, v52, v52
	v_fmac_f32_e32 v71, v54, v54
	v_fmac_f32_e32 v72, v48, v48
	v_fmac_f32_e32 v73, v50, v50
	v_med3_f32 v48, v58, s64, v195
	v_add_f32_e32 v49, v49, v51
	v_add_f32_e32 v51, v70, v71
	v_add_f32_e32 v58, v72, v73
	v_med3_f32 v50, v59, s64, v195
	v_add_f32_e32 v51, v51, v58
	v_add_f32_e32 v48, 0x4b400000, v48
	v_add_f32_e32 v50, 0x4b400000, v50
	v_add_f32_e32 v49, v49, v79
	v_add_f32_e32 v51, v81, v51
	v_perm_b32 v48, v50, v48, s65
	v_mov_b32_e32 v50, v49
	s_nop 1
	v_permlane16_swap_b32_e32 v49, v50
	v_mov_b32_e32 v58, v51
	s_nop 1
	v_permlane16_swap_b32_e32 v51, v58
	v_pk_mul_f32 v[56:57], v[54:55], s[38:39] op_sel_hi:[1,0]
	v_med3_f32 v54, v62, s64, v195
	v_med3_f32 v52, v56, s64, v195
	v_med3_f32 v53, v57, s64, v195
	v_add_f32_e32 v52, 0x4b400000, v52
	v_add_f32_e32 v53, 0x4b400000, v53
	v_perm_b32 v52, v53, v52, s66
	v_or_b32_e32 v52, v48, v52
	s_waitcnt lgkmcnt(0)
	v_add_f32_e32 v48, v49, v50
	s_waitcnt lgkmcnt(0)
	v_add_f32_e32 v50, v51, v58
	v_mov_b32_e32 v49, v48
	s_nop 1
	v_permlane32_swap_b32_e32 v48, v49
	v_mov_b32_e32 v51, v50
	s_nop 1
	v_permlane32_swap_b32_e32 v50, v51
	v_med3_f32 v55, v63, s64, v195
	v_med3_f32 v56, v60, s64, v195
	v_med3_f32 v57, v61, s64, v195
	v_add_f32_e32 v54, 0x4b400000, v54
	v_add_f32_e32 v55, 0x4b400000, v55
	v_add_f32_e32 v56, 0x4b400000, v56
	v_add_f32_e32 v57, 0x4b400000, v57
	v_perm_b32 v53, v55, v54, s65
	v_perm_b32 v54, v57, v56, s66
	v_or_b32_e32 v53, v53, v54
	global_store_dwordx2 v[76:77], v[52:53], off offset:128
	s_and_saveexec_b64 s[6:7], s[2:3]
	s_cbranch_execz .LBB0_3875
	v_lshl_add_u64 v[52:53], s[12:13], 0, v[64:65]
	s_waitcnt lgkmcnt(0)
	v_add_f32_e32 v48, v48, v49
	s_waitcnt lgkmcnt(0)
	v_add_f32_e32 v49, v50, v51
	global_atomic_add_f32 v[52:53], v48, off
	global_atomic_add_f32 v[52:53], v49, off offset:4
; __device__ __forceinline__ u32x2 pack8i8(const f32x4 a, const f32x4 b) { return (u32x2){pack4i8(a), pack4i8(b)}; }
; __device__ __forceinline__ u32x4 pack8bf(const f32x4 a, const f32x4 b) { u32x4 w; w.x = cvt_pk_bf16(a[0], a[1]); w.y = cvt_pk_bf16(a[2], a[3]); w.z = cvt_pk_bf16(b[0], b[1]); w.w = cvt_pk_bf16(b[2], b[3]); return w; }
;     __device__ __forceinline__ void operator()(EPI_ARGS) const {
;     ...
;             for (int m = 0; m < 4; ++m) { const int row = row0 + ai * HALF + m * 16; const size_t off = (size_t)row * DM + col0;
;                 float mu = 0.f, rs = 1.f; if constexpr (RESLN) ln_stats(stin, row, mu, rs);
;                 float ss = 0.f, qq = 0.f;
; #pragma unroll
;                 for (int bj = 0; bj < 2; ++bj) { f32x4 r0 = __builtin_nontemporal_load((const f32x4*)(res + off + bj * HALF)), r1 = __builtin_nontemporal_load((const f32x4*)(res + off + bj * HALF + 4));
;                     if constexpr (RESLN) { r0 = (r0 - mu) * rs * gg[bj][0] + bb[bj][0]; r1 = (r1 - mu) * rs * gg[bj][1] + bb[bj][1]; }
;                     const f32x4 y0 = r0 * DN_ALPHA + acc[ai][bj][m][0] * ascale, y1 = r1 * DN_ALPHA + acc[ai][bj][m][1] * ascale;
;                     if constexpr (COPY != 4) { __builtin_nontemporal_store(y0, (f32x4*)(Y + off + bj * HALF)); __builtin_nontemporal_store(y1, (f32x4*)(Y + off + bj * HALF + 4)); }
;                     if constexpr (STATS) { ss += ((y0[0] + y0[1]) + (y0[2] + y0[3])) + ((y1[0] + y1[1]) + (y1[2] + y1[3]));
;                         qq += ((y0[0] * y0[0] + y0[1] * y0[1]) + (y0[2] * y0[2] + y0[3] * y0[3])) + ((y1[0] * y1[0] + y1[1] * y1[1]) + (y1[2] * y1[2] + y1[3] * y1[3])); }
;                     if constexpr (COPY == 1) *(u32x2*)((unsigned char*)copy + off + bj * HALF) = pack8fp8(y0 * cscale, y1 * cscale);
;                     if constexpr (COPY == 3) *(u32x2*)((unsigned char*)copy + off + bj * HALF) = pack8i8(y0 * cscale, y1 * cscale);
;                     if constexpr (COPY == 2 || COPY == 4) *(u32x4*)((bf16_t*)copy + off + bj * HALF) = pack8bf(y0, y1); }
;                 if constexpr (STATS) { ss += __shfl_xor(ss, 16); ss += __shfl_xor(ss, 32); qq += __shfl_xor(qq, 16); qq += __shfl_xor(qq, 32);
;                     if (fq == 0) { unsafeAtomicAdd(stout + 2 * (size_t)row, ss); unsafeAtomicAdd(stout + 2 * (size_t)row + 1, qq); } }
;                 asm volatile("" ::: "memory"); }
.LBB0_3875:
	s_or_b64 exec, exec, s[6:7]
	v_add_u32_e32 v48, 0xb0, v178
	s_waitcnt lgkmcnt(1)
	v_ashrrev_i32_e32 v49, 31, v48
	s_waitcnt lgkmcnt(0)
	v_lshlrev_b64 v[50:51], 11, v[48:49]
	v_lshlrev_b64 v[48:49], 3, v[48:49]
	v_lshl_add_u64 v[60:61], v[50:51], 0, v[176:177]
	v_lshl_add_u64 v[50:51], s[14:15], 0, v[48:49]
	global_load_dwordx2 v[62:63], v[50:51], off
	v_lshl_add_u64 v[50:51], v[60:61], 2, s[18:19]
	global_load_dwordx4 v[52:55], v[50:51], off nt
	global_load_dwordx4 v[56:59], v[50:51], off offset:16 nt
	global_load_dwordx4 v[228:231], v[50:51], off offset:512 nt
	global_load_dwordx4 v[232:235], v[50:51], off offset:528 nt
	v_lshl_add_u64 v[60:61], s[20:21], 0, v[60:61]
	s_waitcnt vmcnt(4)
	v_pk_mul_f32 v[62:63], v[62:63], s[28:29] op_sel_hi:[1,0]
	s_nop 0
	v_fma_f32 v63, -v62, v62, v63
	v_add_f32_e32 v63, 0x3727c5ac, v63
	v_rsq_f32_e32 v254, v63
	s_waitcnt vmcnt(3)
	v_sub_f32_e32 v55, v55, v62
	v_sub_f32_e32 v54, v54, v62
	v_sub_f32_e32 v53, v53, v62
	v_sub_f32_e32 v52, v52, v62
	s_waitcnt vmcnt(2)
	v_sub_f32_e32 v59, v59, v62
	v_sub_f32_e32 v58, v58, v62
	v_sub_f32_e32 v57, v57, v62
	v_sub_f32_e32 v56, v56, v62
	s_nop 0
	s_nop 1
	v_mov_b32_e32 v64, v254
	v_pk_mul_f32 v[52:53], v[52:53], v[64:65] op_sel_hi:[1,0]
	v_pk_mul_f32 v[54:55], v[54:55], v[64:65] op_sel_hi:[1,0]
	v_pk_mul_f32 v[56:57], v[56:57], v[64:65] op_sel_hi:[1,0]
	v_pk_mul_f32 v[58:59], v[58:59], v[64:65] op_sel_hi:[1,0]
	v_pk_fma_f32 v[18:19], v[30:31], v[54:55], v[18:19]
	v_pk_fma_f32 v[16:17], v[28:29], v[52:53], v[16:17]
	v_pk_fma_f32 v[22:23], v[22:23], v[58:59], v[26:27]
	v_pk_fma_f32 v[20:21], v[20:21], v[56:57], v[24:25]
	v_pk_mul_f32 v[16:17], v[16:17], s[30:31] op_sel_hi:[1,0]
	v_pk_mul_f32 v[18:19], v[18:19], s[30:31] op_sel_hi:[1,0]
	v_pk_mul_f32 v[20:21], v[20:21], s[30:31] op_sel_hi:[1,0]
	v_pk_mul_f32 v[22:23], v[22:23], s[30:31] op_sel_hi:[1,0]
	v_pk_fma_f32 v[18:19], v[46:47], s[36:37], v[18:19] op_sel_hi:[1,0,1]
	v_pk_fma_f32 v[16:17], v[44:45], s[36:37], v[16:17] op_sel_hi:[1,0,1]
	v_pk_fma_f32 v[22:23], v[42:43], s[36:37], v[22:23] op_sel_hi:[1,0,1]
	v_pk_fma_f32 v[20:21], v[40:41], s[36:37], v[20:21] op_sel_hi:[1,0,1]
	v_pk_mul_f32 v[24:25], v[18:19], s[38:39] op_sel_hi:[1,0]
	v_pk_mul_f32 v[26:27], v[16:17], s[38:39] op_sel_hi:[1,0]
	v_pk_mul_f32 v[28:29], v[22:23], s[38:39] op_sel_hi:[1,0]
	v_pk_mul_f32 v[30:31], v[20:21], s[38:39] op_sel_hi:[1,0]
	v_med3_f32 v26, v26, s64, v195
	v_med3_f32 v27, v27, s64, v195
	v_med3_f32 v24, v24, s64, v195
	v_med3_f32 v25, v25, s64, v195
	v_med3_f32 v30, v30, s64, v195
	v_med3_f32 v31, v31, s64, v195
	v_med3_f32 v28, v28, s64, v195
	v_med3_f32 v29, v29, s64, v195
	v_add_f32_e32 v26, 0x4b400000, v26
	v_add_f32_e32 v27, 0x4b400000, v27
	v_add_f32_e32 v24, 0x4b400000, v24
	v_add_f32_e32 v25, 0x4b400000, v25
	v_add_f32_e32 v30, 0x4b400000, v30
	v_add_f32_e32 v31, 0x4b400000, v31
	v_add_f32_e32 v28, 0x4b400000, v28
	v_add_f32_e32 v29, 0x4b400000, v29
	v_perm_b32 v26, v27, v26, s65
	v_perm_b32 v24, v25, v24, s66
	v_perm_b32 v25, v31, v30, s65
	v_perm_b32 v27, v29, v28, s66
	v_or_b32_e32 v24, v26, v24
	v_or_b32_e32 v25, v25, v27
	global_store_dwordx4 v[50:51], v[16:19], off nt
	global_store_dwordx4 v[50:51], v[20:23], off offset:16 nt
	global_store_dwordx2 v[60:61], v[24:25], off
	s_waitcnt vmcnt(3)
; __device__ __forceinline__ u32x2 pack8i8(const f32x4 a, const f32x4 b) { return (u32x2){pack4i8(a), pack4i8(b)}; }
; __device__ __forceinline__ u32x4 pack8bf(const f32x4 a, const f32x4 b) { u32x4 w; w.x = cvt_pk_bf16(a[0], a[1]); w.y = cvt_pk_bf16(a[2], a[3]); w.z = cvt_pk_bf16(b[0], b[1]); w.w = cvt_pk_bf16(b[2], b[3]); return w; }
;     __device__ __forceinline__ void operator()(EPI_ARGS) const {
;     ...
;             for (int m = 0; m < 4; ++m) { const int row = row0 + ai * HALF + m * 16; const size_t off = (size_t)row * DM + col0;
;                 float mu = 0.f, rs = 1.f; if constexpr (RESLN) ln_stats(stin, row, mu, rs);
;                 float ss = 0.f, qq = 0.f;
; #pragma unroll
;                 for (int bj = 0; bj < 2; ++bj) { f32x4 r0 = __builtin_nontemporal_load((const f32x4*)(res + off + bj * HALF)), r1 = __builtin_nontemporal_load((const f32x4*)(res + off + bj * HALF + 4));
;                     if constexpr (RESLN) { r0 = (r0 - mu) * rs * gg[bj][0] + bb[bj][0]; r1 = (r1 - mu) * rs * gg[bj][1] + bb[bj][1]; }
;                     const f32x4 y0 = r0 * DN_ALPHA + acc[ai][bj][m][0] * ascale, y1 = r1 * DN_ALPHA + acc[ai][bj][m][1] * ascale;
;                     if constexpr (COPY != 4) { __builtin_nontemporal_store(y0, (f32x4*)(Y + off + bj * HALF)); __builtin_nontemporal_store(y1, (f32x4*)(Y + off + bj * HALF + 4)); }
;                     if constexpr (STATS) { ss += ((y0[0] + y0[1]) + (y0[2] + y0[3])) + ((y1[0] + y1[1]) + (y1[2] + y1[3]));
;                         qq += ((y0[0] * y0[0] + y0[1] * y0[1]) + (y0[2] * y0[2] + y0[3] * y0[3])) + ((y1[0] * y1[0] + y1[1] * y1[1]) + (y1[2] * y1[2] + y1[3] * y1[3])); }
;                     if constexpr (COPY == 1) *(u32x2*)((unsigned char*)copy + off + bj * HALF) = pack8fp8(y0 * cscale, y1 * cscale);
;                     if constexpr (COPY == 3) *(u32x2*)((unsigned char*)copy + off + bj * HALF) = pack8i8(y0 * cscale, y1 * cscale);
;                     if constexpr (COPY == 2 || COPY == 4) *(u32x4*)((bf16_t*)copy + off + bj * HALF) = pack8bf(y0, y1); }
;                 if constexpr (STATS) { ss += __shfl_xor(ss, 16); ss += __shfl_xor(ss, 32); qq += __shfl_xor(qq, 16); qq += __shfl_xor(qq, 32);
;                     if (fq == 0) { unsafeAtomicAdd(stout + 2 * (size_t)row, ss); unsafeAtomicAdd(stout + 2 * (size_t)row + 1, qq); } }
	s_nop 1
	v_mov_b32_e32 v24, v228
	v_mov_b32_e32 v25, v229
	v_mov_b32_e32 v26, v230
	v_mov_b32_e32 v27, v231
	v_mov_b32_e32 v28, v232
	v_mov_b32_e32 v29, v233
	v_mov_b32_e32 v30, v234
	v_mov_b32_e32 v31, v235
	v_add_f32_e32 v40, v16, v17
	v_add_f32_e32 v41, v18, v19
	v_add_f32_e32 v42, v20, v21
	v_add_f32_e32 v43, v22, v23
	v_mul_f32_e32 v17, v17, v17
	v_mul_f32_e32 v19, v19, v19
	v_mul_f32_e32 v21, v21, v21
	v_mul_f32_e32 v23, v23, v23
	v_add_f32_e32 v40, v40, v41
	v_add_f32_e32 v41, v42, v43
	v_fmac_f32_e32 v17, v16, v16
	v_fmac_f32_e32 v19, v18, v18
	v_fmac_f32_e32 v21, v20, v20
	v_fmac_f32_e32 v23, v22, v22
	v_add_f32_e32 v16, v40, v41
	v_add_f32_e32 v17, v17, v19
	v_add_f32_e32 v18, v21, v23
	v_add_f32_e32 v40, 0, v16
	v_add_f32_e32 v41, v17, v18
	v_sub_f32_e32 v17, v27, v62
	v_sub_f32_e32 v16, v26, v62
	v_sub_f32_e32 v19, v25, v62
	v_sub_f32_e32 v18, v24, v62
	v_sub_f32_e32 v21, v31, v62
	v_sub_f32_e32 v20, v30, v62
	v_sub_f32_e32 v23, v29, v62
	v_sub_f32_e32 v22, v28, v62
	v_pk_mul_f32 v[18:19], v[18:19], v[64:65] op_sel_hi:[1,0]
	v_pk_mul_f32 v[16:17], v[16:17], v[64:65] op_sel_hi:[1,0]
	v_pk_mul_f32 v[22:23], v[22:23], v[64:65] op_sel_hi:[1,0]
	v_pk_mul_f32 v[20:21], v[20:21], v[64:65] op_sel_hi:[1,0]
	v_pk_fma_f32 v[10:11], v[10:11], v[16:17], v[14:15]
	v_pk_fma_f32 v[8:9], v[8:9], v[18:19], v[12:13]
	v_pk_fma_f32 v[2:3], v[2:3], v[20:21], v[6:7]
	v_pk_fma_f32 v[0:1], v[0:1], v[22:23], v[4:5]
	v_pk_mul_f32 v[4:5], v[8:9], s[30:31] op_sel_hi:[1,0]
	v_pk_mul_f32 v[6:7], v[10:11], s[30:31] op_sel_hi:[1,0]
	v_pk_mul_f32 v[8:9], v[0:1], s[30:31] op_sel_hi:[1,0]
	v_pk_mul_f32 v[10:11], v[2:3], s[30:31] op_sel_hi:[1,0]
	v_pk_fma_f32 v[2:3], v[38:39], s[36:37], v[6:7] op_sel_hi:[1,0,1]
	v_pk_fma_f32 v[0:1], v[36:37], s[36:37], v[4:5] op_sel_hi:[1,0,1]
	v_pk_fma_f32 v[6:7], v[34:35], s[36:37], v[10:11] op_sel_hi:[1,0,1]
	v_pk_fma_f32 v[4:5], v[32:33], s[36:37], v[8:9] op_sel_hi:[1,0,1]
	v_add_f32_e32 v16, v0, v1
	v_add_f32_e32 v17, v2, v3
	v_add_f32_e32 v18, v4, v5
	v_add_f32_e32 v19, v6, v7
	v_mul_f32_e32 v20, v1, v1
	v_mul_f32_e32 v21, v3, v3
	v_mul_f32_e32 v22, v5, v5
	v_mul_f32_e32 v23, v7, v7
	global_store_dwordx4 v[50:51], v[0:3], off offset:512 nt
	global_store_dwordx4 v[50:51], v[4:7], off offset:528 nt
	v_pk_mul_f32 v[8:9], v[2:3], s[38:39] op_sel_hi:[1,0]
	v_pk_mul_f32 v[10:11], v[0:1], s[38:39] op_sel_hi:[1,0]
	v_add_f32_e32 v1, v16, v17
	v_add_f32_e32 v3, v18, v19
	v_fmac_f32_e32 v20, v0, v0
	v_fmac_f32_e32 v21, v2, v2
	v_fmac_f32_e32 v22, v4, v4
	v_fmac_f32_e32 v23, v6, v6
	v_med3_f32 v0, v10, s64, v195
	v_add_f32_e32 v1, v1, v3
	v_add_f32_e32 v3, v20, v21
	v_add_f32_e32 v10, v22, v23
	v_med3_f32 v2, v11, s64, v195
	v_add_f32_e32 v3, v3, v10
	v_add_f32_e32 v0, 0x4b400000, v0
	v_add_f32_e32 v2, 0x4b400000, v2
	v_add_f32_e32 v1, v1, v40
	v_add_f32_e32 v3, v41, v3
	v_perm_b32 v0, v2, v0, s65
	v_mov_b32_e32 v2, v1
	s_nop 1
	v_permlane16_swap_b32_e32 v1, v2
	v_mov_b32_e32 v10, v3
	s_nop 1
	v_permlane16_swap_b32_e32 v3, v10
	v_pk_mul_f32 v[14:15], v[4:5], s[38:39] op_sel_hi:[1,0]
	v_med3_f32 v4, v8, s64, v195
	v_med3_f32 v5, v9, s64, v195
	v_add_f32_e32 v4, 0x4b400000, v4
	v_add_f32_e32 v5, 0x4b400000, v5
	v_perm_b32 v4, v5, v4, s66
	v_or_b32_e32 v4, v0, v4
	s_waitcnt lgkmcnt(0)
	v_add_f32_e32 v0, v1, v2
	s_waitcnt lgkmcnt(0)
	v_add_f32_e32 v2, v3, v10
	v_pk_mul_f32 v[12:13], v[6:7], s[38:39] op_sel_hi:[1,0]
	v_mov_b32_e32 v1, v0
	s_nop 1
	v_permlane32_swap_b32_e32 v0, v1
	v_mov_b32_e32 v3, v2
	s_nop 1
	v_permlane32_swap_b32_e32 v2, v3
	v_med3_f32 v6, v14, s64, v195
	v_med3_f32 v7, v15, s64, v195
	v_med3_f32 v8, v12, s64, v195
	v_med3_f32 v9, v13, s64, v195
	v_add_f32_e32 v6, 0x4b400000, v6
	v_add_f32_e32 v7, 0x4b400000, v7
	v_add_f32_e32 v8, 0x4b400000, v8
	v_add_f32_e32 v9, 0x4b400000, v9
	v_perm_b32 v5, v7, v6, s65
	v_perm_b32 v6, v9, v8, s66
	v_or_b32_e32 v5, v5, v6
	global_store_dwordx2 v[60:61], v[4:5], off offset:128
	s_and_saveexec_b64 s[6:7], s[2:3]
	s_cbranch_execz .LBB0_3877
	v_lshl_add_u64 v[4:5], s[12:13], 0, v[48:49]
	s_waitcnt lgkmcnt(0)
	v_add_f32_e32 v0, v0, v1
	s_waitcnt lgkmcnt(0)
	v_add_f32_e32 v1, v2, v3
	global_atomic_add_f32 v[4:5], v0, off
	global_atomic_add_f32 v[4:5], v1, off offset:4

;     __device__ __forceinline__ void operator()(EPI_ARGS) const {
;         const int row0 = u.pm * BM + wr * 64 + fr, col0 = u.pn * BM + wc * 32 + 8 * fq;
;         f32x4 gg[2][2], bb[2][2];
;         if constexpr (RESLN) {
; #pragma unroll
;             for (int bj = 0; bj < 2; ++bj)
; #pragma unroll
;                 for (int n = 0; n < 2; ++n) { gg[bj][n] = *(const f32x4*)(lg + col0 + bj * HALF + 4 * n); bb[bj][n] = *(const f32x4*)(lb + col0 + bj * HALF + 4 * n); } }
; #pragma unroll
;         for (int ai = 0; ai < 2; ++ai)
; #pragma unroll
;             for (int m = 0; m < 4; ++m) { const int row = row0 + ai * HALF + m * 16; const size_t off = (size_t)row * DM + col0;
;                 float mu = 0.f, rs = 1.f; if constexpr (RESLN) ln_stats(stin, row, mu, rs);
;                 float ss = 0.f, qq = 0.f;
; #pragma unroll
;                 for (int bj = 0; bj < 2; ++bj) { f32x4 r0 = __builtin_nontemporal_load((const f32x4*)(res + off + bj * HALF)), r1 = __builtin_nontemporal_load((const f32x4*)(res + off + bj * HALF + 4));
;                     if constexpr (RESLN) { r0 = (r0 - mu) * rs * gg[bj][0] + bb[bj][0]; r1 = (r1 - mu) * rs * gg[bj][1] + bb[bj][1]; }
;                     const f32x4 y0 = r0 * DN_ALPHA + acc[ai][bj][m][0] * ascale, y1 = r1 * DN_ALPHA + acc[ai][bj][m][1] * ascale;
;                     if constexpr (COPY != 4) { __builtin_nontemporal_store(y0, (f32x4*)(Y + off + bj * HALF)); __builtin_nontemporal_store(y1, (f32x4*)(Y + off + bj * HALF + 4)); }
;                     if constexpr (STATS) { ss += ((y0[0] + y0[1]) + (y0[2] + y0[3])) + ((y1[0] + y1[1]) + (y1[2] + y1[3]));
;                         qq += ((y0[0] * y0[0] + y0[1] * y0[1]) + (y0[2] * y0[2] + y0[3] * y0[3])) + ((y1[0] * y1[0] + y1[1] * y1[1]) + (y1[2] * y1[2] + y1[3] * y1[3])); }
;                     if constexpr (COPY == 1) *(u32x2*)((unsigned char*)copy + off + bj * HALF) = pack8fp8(y0 * cscale, y1 * cscale);
;                     if constexpr (COPY == 3) *(u32x2*)((unsigned char*)copy + off + bj * HALF) = pack8i8(y0 * cscale, y1 * cscale);
;                     if constexpr (COPY == 2 || COPY == 4) *(u32x4*)((bf16_t*)copy + off + bj * HALF) = pack8bf(y0, y1); }
;                 if constexpr (STATS) { ss += __shfl_xor(ss, 16); ss += __shfl_xor(ss, 32); qq += __shfl_xor(qq, 16); qq += __shfl_xor(qq, 32);
.LBB0_4505:
	v_lshl_add_u32 v178, s4, 8, v184
	v_ashrrev_i32_e32 v179, 31, v178
	v_lshl_add_u64 v[2:3], v[178:179], 3, s[12:13]
	global_load_dwordx2 v[196:197], v[2:3], off
	v_lshl_or_b32 v176, s5, 8, v186
	v_ashrrev_i32_e32 v177, 31, v176
	v_lshlrev_b64 v[0:1], 11, v[178:179]
	v_lshl_add_u64 v[198:199], v[0:1], 0, v[176:177]
	v_lshl_add_u64 v[200:201], v[198:199], 2, s[14:15]
	global_load_dwordx4 v[180:183], v[200:201], off nt
	global_load_dwordx4 v[192:195], v[200:201], off offset:16 nt
	global_load_dwordx4 v[228:231], v[200:201], off offset:512 nt
	global_load_dwordx4 v[232:235], v[200:201], off offset:528 nt
	v_lshlrev_b64 v[0:1], 2, v[176:177]
	v_lshl_add_u64 v[4:5], s[8:9], 0, v[0:1]
	v_lshl_add_u64 v[12:13], s[10:11], 0, v[0:1]
	global_load_dwordx4 v[20:23], v[12:13], off
	global_load_dwordx4 v[24:27], v[4:5], off
	global_load_dwordx4 v[16:19], v[4:5], off offset:16
	global_load_dwordx4 v[28:31], v[12:13], off offset:16
	global_load_dwordx4 v[0:3], v[4:5], off offset:528
	global_load_dwordx4 v[8:11], v[4:5], off offset:512
	s_nop 0
	global_load_dwordx4 v[4:7], v[12:13], off offset:528
	s_nop 0
	global_load_dwordx4 v[12:15], v[12:13], off offset:512
	v_lshl_add_u64 v[198:199], v[198:199], 1, s[16:17]
	s_waitcnt vmcnt(0)
	v_pk_mul_f32 v[196:197], v[196:197], s[24:25] op_sel_hi:[1,0]
	s_nop 0
	v_fma_f32 v179, -v196, v196, v197
	v_add_f32_e32 v179, 0x3727c5ac, v179
	v_rsq_f32_e32 v254, v179
	v_sub_f32_e32 v181, v181, v196
	v_sub_f32_e32 v180, v180, v196
	v_sub_f32_e32 v195, v195, v196
	v_sub_f32_e32 v194, v194, v196
	v_sub_f32_e32 v193, v193, v196
	v_sub_f32_e32 v192, v192, v196
	v_sub_f32_e32 v183, v183, v196
	v_sub_f32_e32 v182, v182, v196
	s_nop 0
	s_nop 1
	v_mov_b32_e32 v202, v254
	v_pk_mul_f32 v[180:181], v[180:181], v[202:203] op_sel_hi:[1,0]
	v_pk_mul_f32 v[192:193], v[192:193], v[202:203] op_sel_hi:[1,0]
	v_pk_mul_f32 v[194:195], v[194:195], v[202:203] op_sel_hi:[1,0]
	v_pk_mul_f32 v[182:183], v[182:183], v[202:203] op_sel_hi:[1,0]
	v_pk_fma_f32 v[180:181], v[24:25], v[180:181], v[20:21]
	v_pk_fma_f32 v[194:195], v[18:19], v[194:195], v[30:31]
	v_pk_fma_f32 v[192:193], v[16:17], v[192:193], v[28:29]
	v_pk_fma_f32 v[182:183], v[26:27], v[182:183], v[22:23]
	v_pk_mul_f32 v[180:181], v[180:181], s[26:27] op_sel_hi:[1,0]
	v_pk_mul_f32 v[192:193], v[192:193], s[26:27] op_sel_hi:[1,0]
	v_pk_mul_f32 v[194:195], v[194:195], s[26:27] op_sel_hi:[1,0]
	v_pk_mul_f32 v[182:183], v[182:183], s[26:27] op_sel_hi:[1,0]
	v_pk_fma_f32 v[156:157], v[156:157], s[28:29], v[180:181] op_sel_hi:[1,0,1]
	v_pk_fma_f32 v[180:181], v[154:155], s[28:29], v[194:195] op_sel_hi:[1,0,1]
	v_pk_fma_f32 v[154:155], v[152:153], s[28:29], v[192:193] op_sel_hi:[1,0,1]
	v_pk_fma_f32 v[158:159], v[158:159], s[28:29], v[182:183] op_sel_hi:[1,0,1]
	v_cvt_pk_bf16_f32 v152, v156, v157
	s_nop 0
	v_cvt_pk_bf16_f32 v153, v158, v159
	v_cvt_pk_bf16_f32 v154, v154, v155
	v_cvt_pk_bf16_f32 v155, v180, v181
	global_store_dwordx4 v[198:199], v[152:155], off
	s_waitcnt vmcnt(9)
	s_nop 1
	v_mov_b32_e32 v152, v228
	v_mov_b32_e32 v153, v229
	v_mov_b32_e32 v154, v230
	v_mov_b32_e32 v155, v231
	v_mov_b32_e32 v156, v232
	v_mov_b32_e32 v157, v233
	v_mov_b32_e32 v158, v234
	v_mov_b32_e32 v159, v235
	v_or_b32_e32 v180, 16, v178
	v_ashrrev_i32_e32 v181, 31, v180
	v_lshlrev_b64 v[182:183], 11, v[180:181]
	v_lshl_add_u64 v[180:181], v[180:181], 3, s[12:13]
	v_lshl_add_u64 v[182:183], v[182:183], 0, v[176:177]
	v_sub_f32_e32 v153, v153, v196
	v_sub_f32_e32 v152, v152, v196
	v_sub_f32_e32 v159, v159, v196
	v_sub_f32_e32 v158, v158, v196
	v_sub_f32_e32 v157, v157, v196
	v_sub_f32_e32 v156, v156, v196
	v_sub_f32_e32 v155, v155, v196
	v_sub_f32_e32 v154, v154, v196
	v_pk_mul_f32 v[152:153], v[202:203], v[152:153] op_sel_hi:[0,1]
	v_pk_mul_f32 v[156:157], v[202:203], v[156:157] op_sel_hi:[0,1]
	v_pk_mul_f32 v[158:159], v[202:203], v[158:159] op_sel_hi:[0,1]
	v_pk_mul_f32 v[154:155], v[202:203], v[154:155] op_sel_hi:[0,1]
	v_pk_fma_f32 v[152:153], v[8:9], v[152:153], v[12:13]
	v_pk_fma_f32 v[158:159], v[2:3], v[158:159], v[6:7]
	v_pk_fma_f32 v[156:157], v[0:1], v[156:157], v[4:5]
	v_pk_fma_f32 v[154:155], v[10:11], v[154:155], v[14:15]
	v_pk_mul_f32 v[152:153], v[152:153], s[26:27] op_sel_hi:[1,0]
	v_pk_mul_f32 v[156:157], v[156:157], s[26:27] op_sel_hi:[1,0]
	v_pk_mul_f32 v[158:159], v[158:159], s[26:27] op_sel_hi:[1,0]
	v_pk_mul_f32 v[154:155], v[154:155], s[26:27] op_sel_hi:[1,0]
	v_pk_fma_f32 v[148:149], v[148:149], s[28:29], v[152:153] op_sel_hi:[1,0,1]
	v_pk_fma_f32 v[152:153], v[146:147], s[28:29], v[158:159] op_sel_hi:[1,0,1]
	v_pk_fma_f32 v[146:147], v[144:145], s[28:29], v[156:157] op_sel_hi:[1,0,1]
	v_pk_fma_f32 v[150:151], v[150:151], s[28:29], v[154:155] op_sel_hi:[1,0,1]
	v_cvt_pk_bf16_f32 v144, v148, v149
	v_lshl_add_u64 v[154:155], v[182:183], 2, s[14:15]
	v_cvt_pk_bf16_f32 v145, v150, v151
	v_cvt_pk_bf16_f32 v146, v146, v147
	v_cvt_pk_bf16_f32 v147, v152, v153
	global_store_dwordx4 v[198:199], v[144:147], off offset:256
	global_load_dwordx2 v[152:153], v[180:181], off
	global_load_dwordx4 v[144:147], v[154:155], off nt
	global_load_dwordx4 v[148:151], v[154:155], off offset:16 nt
	global_load_dwordx4 v[228:231], v[154:155], off offset:512 nt
	global_load_dwordx4 v[232:235], v[154:155], off offset:528 nt
	v_lshl_add_u64 v[156:157], v[182:183], 1, s[16:17]
	s_waitcnt vmcnt(4)
	v_pk_mul_f32 v[152:153], v[152:153], s[24:25] op_sel_hi:[1,0]
	s_nop 0
	v_fma_f32 v153, -v152, v152, v153
	v_add_f32_e32 v153, 0x3727c5ac, v153
	v_rsq_f32_e32 v254, v153
	s_waitcnt vmcnt(3)
	v_sub_f32_e32 v145, v145, v152
	v_sub_f32_e32 v144, v144, v152
	s_waitcnt vmcnt(2)
; __device__ __forceinline__ u32x2 pack8i8(const f32x4 a, const f32x4 b) { return (u32x2){pack4i8(a), pack4i8(b)}; }
; __device__ __forceinline__ u32x4 pack8bf(const f32x4 a, const f32x4 b) { u32x4 w; w.x = cvt_pk_bf16(a[0], a[1]); w.y = cvt_pk_bf16(a[2], a[3]); w.z = cvt_pk_bf16(b[0], b[1]); w.w = cvt_pk_bf16(b[2], b[3]); return w; }
; __device__ __forceinline__ void ln_stats(const float* st, int row, float& mu, float& rs) { const f32x2 s = *(const f32x2*)(st + 2 * (size_t)row); mu = s[0] * (1.0f / DM); rs = 1.0f / sqrtf(s[1] * (1.0f / DM) - mu * mu + LN_EPS); }
;     __device__ __forceinline__ void operator()(EPI_ARGS) const {
;     ...
;             for (int m = 0; m < 4; ++m) { const int row = row0 + ai * HALF + m * 16; const size_t off = (size_t)row * DM + col0;
;                 float mu = 0.f, rs = 1.f; if constexpr (RESLN) ln_stats(stin, row, mu, rs);
;                 float ss = 0.f, qq = 0.f;
; #pragma unroll
;                 for (int bj = 0; bj < 2; ++bj) { f32x4 r0 = __builtin_nontemporal_load((const f32x4*)(res + off + bj * HALF)), r1 = __builtin_nontemporal_load((const f32x4*)(res + off + bj * HALF + 4));
;                     if constexpr (RESLN) { r0 = (r0 - mu) * rs * gg[bj][0] + bb[bj][0]; r1 = (r1 - mu) * rs * gg[bj][1] + bb[bj][1]; }
;                     const f32x4 y0 = r0 * DN_ALPHA + acc[ai][bj][m][0] * ascale, y1 = r1 * DN_ALPHA + acc[ai][bj][m][1] * ascale;
;                     if constexpr (COPY != 4) { __builtin_nontemporal_store(y0, (f32x4*)(Y + off + bj * HALF)); __builtin_nontemporal_store(y1, (f32x4*)(Y + off + bj * HALF + 4)); }
;                     if constexpr (STATS) { ss += ((y0[0] + y0[1]) + (y0[2] + y0[3])) + ((y1[0] + y1[1]) + (y1[2] + y1[3]));
;                         qq += ((y0[0] * y0[0] + y0[1] * y0[1]) + (y0[2] * y0[2] + y0[3] * y0[3])) + ((y1[0] * y1[0] + y1[1] * y1[1]) + (y1[2] * y1[2] + y1[3] * y1[3])); }
;                     if constexpr (COPY == 1) *(u32x2*)((unsigned char*)copy + off + bj * HALF) = pack8fp8(y0 * cscale, y1 * cscale);
;                     if constexpr (COPY == 3) *(u32x2*)((unsigned char*)copy + off + bj * HALF) = pack8i8(y0 * cscale, y1 * cscale);
;                     if constexpr (COPY == 2 || COPY == 4) *(u32x4*)((bf16_t*)copy + off + bj * HALF) = pack8bf(y0, y1); }
	v_sub_f32_e32 v151, v151, v152
	v_sub_f32_e32 v150, v150, v152
	v_sub_f32_e32 v149, v149, v152
	v_sub_f32_e32 v148, v148, v152
	v_sub_f32_e32 v147, v147, v152
	v_sub_f32_e32 v146, v146, v152
	s_nop 0
	s_nop 1
	v_mov_b32_e32 v158, v254
	v_pk_mul_f32 v[144:145], v[144:145], v[158:159] op_sel_hi:[1,0]
	v_pk_mul_f32 v[148:149], v[148:149], v[158:159] op_sel_hi:[1,0]
	v_pk_mul_f32 v[150:151], v[150:151], v[158:159] op_sel_hi:[1,0]
	v_pk_mul_f32 v[146:147], v[146:147], v[158:159] op_sel_hi:[1,0]
	v_pk_fma_f32 v[144:145], v[24:25], v[144:145], v[20:21]
	v_pk_fma_f32 v[150:151], v[18:19], v[150:151], v[30:31]
	v_pk_fma_f32 v[148:149], v[16:17], v[148:149], v[28:29]
	v_pk_fma_f32 v[146:147], v[26:27], v[146:147], v[22:23]
	v_pk_mul_f32 v[144:145], v[144:145], s[26:27] op_sel_hi:[1,0]
	v_pk_mul_f32 v[148:149], v[148:149], s[26:27] op_sel_hi:[1,0]
	v_pk_mul_f32 v[150:151], v[150:151], s[26:27] op_sel_hi:[1,0]
	v_pk_mul_f32 v[146:147], v[146:147], s[26:27] op_sel_hi:[1,0]
	v_pk_fma_f32 v[140:141], v[140:141], s[28:29], v[144:145] op_sel_hi:[1,0,1]
	v_pk_fma_f32 v[144:145], v[138:139], s[28:29], v[150:151] op_sel_hi:[1,0,1]
	v_pk_fma_f32 v[138:139], v[136:137], s[28:29], v[148:149] op_sel_hi:[1,0,1]
	v_pk_fma_f32 v[142:143], v[142:143], s[28:29], v[146:147] op_sel_hi:[1,0,1]
	v_cvt_pk_bf16_f32 v136, v140, v141
	s_nop 0
	v_cvt_pk_bf16_f32 v137, v142, v143
	v_cvt_pk_bf16_f32 v138, v138, v139
	v_cvt_pk_bf16_f32 v139, v144, v145
	global_store_dwordx4 v[156:157], v[136:139], off
	s_waitcnt vmcnt(1)
	s_nop 1
	v_mov_b32_e32 v136, v228
	v_mov_b32_e32 v137, v229
	v_mov_b32_e32 v138, v230
	v_mov_b32_e32 v139, v231
	v_mov_b32_e32 v140, v232
	v_mov_b32_e32 v141, v233
	v_mov_b32_e32 v142, v234
	v_mov_b32_e32 v143, v235
	v_or_b32_e32 v144, 32, v178
	v_ashrrev_i32_e32 v145, 31, v144
	v_lshlrev_b64 v[146:147], 11, v[144:145]
	v_lshl_add_u64 v[144:145], v[144:145], 3, s[12:13]
	v_lshl_add_u64 v[146:147], v[146:147], 0, v[176:177]
	v_sub_f32_e32 v137, v137, v152
	v_sub_f32_e32 v136, v136, v152
	v_sub_f32_e32 v143, v143, v152
	v_sub_f32_e32 v142, v142, v152
	v_sub_f32_e32 v141, v141, v152
	v_sub_f32_e32 v140, v140, v152
	v_sub_f32_e32 v139, v139, v152
	v_sub_f32_e32 v138, v138, v152
	v_pk_mul_f32 v[136:137], v[158:159], v[136:137] op_sel_hi:[0,1]
	v_pk_mul_f32 v[140:141], v[158:159], v[140:141] op_sel_hi:[0,1]
	v_pk_mul_f32 v[142:143], v[158:159], v[142:143] op_sel_hi:[0,1]
	v_pk_mul_f32 v[138:139], v[158:159], v[138:139] op_sel_hi:[0,1]
	v_pk_fma_f32 v[136:137], v[8:9], v[136:137], v[12:13]
	v_pk_fma_f32 v[142:143], v[2:3], v[142:143], v[6:7]
	v_pk_fma_f32 v[140:141], v[0:1], v[140:141], v[4:5]
	v_pk_fma_f32 v[138:139], v[10:11], v[138:139], v[14:15]
	v_pk_mul_f32 v[136:137], v[136:137], s[26:27] op_sel_hi:[1,0]
	v_pk_mul_f32 v[140:141], v[140:141], s[26:27] op_sel_hi:[1,0]
	v_pk_mul_f32 v[142:143], v[142:143], s[26:27] op_sel_hi:[1,0]
	v_pk_mul_f32 v[138:139], v[138:139], s[26:27] op_sel_hi:[1,0]
	v_pk_fma_f32 v[132:133], v[132:133], s[28:29], v[136:137] op_sel_hi:[1,0,1]
	v_pk_fma_f32 v[136:137], v[130:131], s[28:29], v[142:143] op_sel_hi:[1,0,1]
	v_pk_fma_f32 v[130:131], v[128:129], s[28:29], v[140:141] op_sel_hi:[1,0,1]
	v_pk_fma_f32 v[134:135], v[134:135], s[28:29], v[138:139] op_sel_hi:[1,0,1]
	v_cvt_pk_bf16_f32 v128, v132, v133
	v_lshl_add_u64 v[138:139], v[146:147], 2, s[14:15]
	v_cvt_pk_bf16_f32 v129, v134, v135
	v_cvt_pk_bf16_f32 v130, v130, v131
	v_cvt_pk_bf16_f32 v131, v136, v137
	global_store_dwordx4 v[156:157], v[128:131], off offset:256
	global_load_dwordx2 v[136:137], v[144:145], off
	global_load_dwordx4 v[128:131], v[138:139], off nt
	global_load_dwordx4 v[132:135], v[138:139], off offset:16 nt
	global_load_dwordx4 v[228:231], v[138:139], off offset:512 nt
	global_load_dwordx4 v[232:235], v[138:139], off offset:528 nt
	v_lshl_add_u64 v[140:141], v[146:147], 1, s[16:17]
	s_waitcnt vmcnt(4)
	v_pk_mul_f32 v[136:137], v[136:137], s[24:25] op_sel_hi:[1,0]
	s_nop 0
	v_fma_f32 v137, -v136, v136, v137
	v_add_f32_e32 v137, 0x3727c5ac, v137
	v_rsq_f32_e32 v254, v137
	s_waitcnt vmcnt(3)
	v_sub_f32_e32 v129, v129, v136
	v_sub_f32_e32 v128, v128, v136
	s_waitcnt vmcnt(2)
	v_sub_f32_e32 v135, v135, v136
	v_sub_f32_e32 v134, v134, v136
	v_sub_f32_e32 v133, v133, v136
	v_sub_f32_e32 v132, v132, v136
	v_sub_f32_e32 v131, v131, v136
	v_sub_f32_e32 v130, v130, v136
	s_nop 0
	s_nop 1
	v_mov_b32_e32 v142, v254
	v_pk_mul_f32 v[128:129], v[128:129], v[142:143] op_sel_hi:[1,0]
	v_pk_mul_f32 v[132:133], v[132:133], v[142:143] op_sel_hi:[1,0]
	v_pk_mul_f32 v[134:135], v[134:135], v[142:143] op_sel_hi:[1,0]
	v_pk_mul_f32 v[130:131], v[130:131], v[142:143] op_sel_hi:[1,0]
	v_pk_fma_f32 v[128:129], v[24:25], v[128:129], v[20:21]
	v_pk_fma_f32 v[134:135], v[18:19], v[134:135], v[30:31]
	v_pk_fma_f32 v[132:133], v[16:17], v[132:133], v[28:29]
	v_pk_fma_f32 v[130:131], v[26:27], v[130:131], v[22:23]
	v_pk_mul_f32 v[128:129], v[128:129], s[26:27] op_sel_hi:[1,0]
	v_pk_mul_f32 v[132:133], v[132:133], s[26:27] op_sel_hi:[1,0]
	v_pk_mul_f32 v[134:135], v[134:135], s[26:27] op_sel_hi:[1,0]
	v_pk_mul_f32 v[130:131], v[130:131], s[26:27] op_sel_hi:[1,0]
	v_pk_fma_f32 v[124:125], v[124:125], s[28:29], v[128:129] op_sel_hi:[1,0,1]
	v_pk_fma_f32 v[128:129], v[122:123], s[28:29], v[134:135] op_sel_hi:[1,0,1]
	v_pk_fma_f32 v[122:123], v[120:121], s[28:29], v[132:133] op_sel_hi:[1,0,1]
	v_pk_fma_f32 v[126:127], v[126:127], s[28:29], v[130:131] op_sel_hi:[1,0,1]
	v_cvt_pk_bf16_f32 v120, v124, v125
	s_nop 0
	v_cvt_pk_bf16_f32 v121, v126, v127
	v_cvt_pk_bf16_f32 v122, v122, v123
	v_cvt_pk_bf16_f32 v123, v128, v129
	global_store_dwordx4 v[140:141], v[120:123], off
	s_waitcnt vmcnt(1)
; __device__ __forceinline__ u32x2 pack8i8(const f32x4 a, const f32x4 b) { return (u32x2){pack4i8(a), pack4i8(b)}; }
; __device__ __forceinline__ u32x4 pack8bf(const f32x4 a, const f32x4 b) { u32x4 w; w.x = cvt_pk_bf16(a[0], a[1]); w.y = cvt_pk_bf16(a[2], a[3]); w.z = cvt_pk_bf16(b[0], b[1]); w.w = cvt_pk_bf16(b[2], b[3]); return w; }
; __device__ __forceinline__ void ln_stats(const float* st, int row, float& mu, float& rs) { const f32x2 s = *(const f32x2*)(st + 2 * (size_t)row); mu = s[0] * (1.0f / DM); rs = 1.0f / sqrtf(s[1] * (1.0f / DM) - mu * mu + LN_EPS); }
;     __device__ __forceinline__ void operator()(EPI_ARGS) const {
;     ...
;             for (int m = 0; m < 4; ++m) { const int row = row0 + ai * HALF + m * 16; const size_t off = (size_t)row * DM + col0;
;                 float mu = 0.f, rs = 1.f; if constexpr (RESLN) ln_stats(stin, row, mu, rs);
;                 float ss = 0.f, qq = 0.f;
; #pragma unroll
;                 for (int bj = 0; bj < 2; ++bj) { f32x4 r0 = __builtin_nontemporal_load((const f32x4*)(res + off + bj * HALF)), r1 = __builtin_nontemporal_load((const f32x4*)(res + off + bj * HALF + 4));
;                     if constexpr (RESLN) { r0 = (r0 - mu) * rs * gg[bj][0] + bb[bj][0]; r1 = (r1 - mu) * rs * gg[bj][1] + bb[bj][1]; }
;                     const f32x4 y0 = r0 * DN_ALPHA + acc[ai][bj][m][0] * ascale, y1 = r1 * DN_ALPHA + acc[ai][bj][m][1] * ascale;
;                     if constexpr (COPY != 4) { __builtin_nontemporal_store(y0, (f32x4*)(Y + off + bj * HALF)); __builtin_nontemporal_store(y1, (f32x4*)(Y + off + bj * HALF + 4)); }
;                     if constexpr (STATS) { ss += ((y0[0] + y0[1]) + (y0[2] + y0[3])) + ((y1[0] + y1[1]) + (y1[2] + y1[3]));
;                         qq += ((y0[0] * y0[0] + y0[1] * y0[1]) + (y0[2] * y0[2] + y0[3] * y0[3])) + ((y1[0] * y1[0] + y1[1] * y1[1]) + (y1[2] * y1[2] + y1[3] * y1[3])); }
;                     if constexpr (COPY == 1) *(u32x2*)((unsigned char*)copy + off + bj * HALF) = pack8fp8(y0 * cscale, y1 * cscale);
;                     if constexpr (COPY == 3) *(u32x2*)((unsigned char*)copy + off + bj * HALF) = pack8i8(y0 * cscale, y1 * cscale);
;                     if constexpr (COPY == 2 || COPY == 4) *(u32x4*)((bf16_t*)copy + off + bj * HALF) = pack8bf(y0, y1); }
	s_nop 1
	v_mov_b32_e32 v120, v228
	v_mov_b32_e32 v121, v229
	v_mov_b32_e32 v122, v230
	v_mov_b32_e32 v123, v231
	v_mov_b32_e32 v124, v232
	v_mov_b32_e32 v125, v233
	v_mov_b32_e32 v126, v234
	v_mov_b32_e32 v127, v235
	v_or_b32_e32 v128, 48, v178
	v_ashrrev_i32_e32 v129, 31, v128
	v_lshlrev_b64 v[130:131], 11, v[128:129]
	v_lshl_add_u64 v[128:129], v[128:129], 3, s[12:13]
	v_lshl_add_u64 v[130:131], v[130:131], 0, v[176:177]
	v_sub_f32_e32 v121, v121, v136
	v_sub_f32_e32 v120, v120, v136
	v_sub_f32_e32 v127, v127, v136
	v_sub_f32_e32 v126, v126, v136
	v_sub_f32_e32 v125, v125, v136
	v_sub_f32_e32 v124, v124, v136
	v_sub_f32_e32 v123, v123, v136
	v_sub_f32_e32 v122, v122, v136
	v_pk_mul_f32 v[120:121], v[142:143], v[120:121] op_sel_hi:[0,1]
	v_pk_mul_f32 v[124:125], v[142:143], v[124:125] op_sel_hi:[0,1]
	v_pk_mul_f32 v[126:127], v[142:143], v[126:127] op_sel_hi:[0,1]
	v_pk_mul_f32 v[122:123], v[142:143], v[122:123] op_sel_hi:[0,1]
	v_pk_fma_f32 v[120:121], v[8:9], v[120:121], v[12:13]
	v_pk_fma_f32 v[126:127], v[2:3], v[126:127], v[6:7]
	v_pk_fma_f32 v[124:125], v[0:1], v[124:125], v[4:5]
	v_pk_fma_f32 v[122:123], v[10:11], v[122:123], v[14:15]
	v_pk_mul_f32 v[120:121], v[120:121], s[26:27] op_sel_hi:[1,0]
	v_pk_mul_f32 v[124:125], v[124:125], s[26:27] op_sel_hi:[1,0]
	v_pk_mul_f32 v[126:127], v[126:127], s[26:27] op_sel_hi:[1,0]
	v_pk_mul_f32 v[122:123], v[122:123], s[26:27] op_sel_hi:[1,0]
	v_pk_fma_f32 v[116:117], v[116:117], s[28:29], v[120:121] op_sel_hi:[1,0,1]
	v_pk_fma_f32 v[120:121], v[114:115], s[28:29], v[126:127] op_sel_hi:[1,0,1]
	v_pk_fma_f32 v[114:115], v[112:113], s[28:29], v[124:125] op_sel_hi:[1,0,1]
	v_pk_fma_f32 v[118:119], v[118:119], s[28:29], v[122:123] op_sel_hi:[1,0,1]
	v_cvt_pk_bf16_f32 v112, v116, v117
	v_lshl_add_u64 v[122:123], v[130:131], 2, s[14:15]
	v_cvt_pk_bf16_f32 v113, v118, v119
	v_cvt_pk_bf16_f32 v114, v114, v115
	v_cvt_pk_bf16_f32 v115, v120, v121
	global_store_dwordx4 v[140:141], v[112:115], off offset:256
	global_load_dwordx2 v[120:121], v[128:129], off
	global_load_dwordx4 v[112:115], v[122:123], off nt
	global_load_dwordx4 v[116:119], v[122:123], off offset:16 nt
	global_load_dwordx4 v[228:231], v[122:123], off offset:512 nt
	global_load_dwordx4 v[232:235], v[122:123], off offset:528 nt
	v_lshl_add_u64 v[124:125], v[130:131], 1, s[16:17]
	s_waitcnt vmcnt(4)
	v_pk_mul_f32 v[120:121], v[120:121], s[24:25] op_sel_hi:[1,0]
	s_nop 0
	v_fma_f32 v121, -v120, v120, v121
	v_add_f32_e32 v121, 0x3727c5ac, v121
	v_rsq_f32_e32 v254, v121
	s_waitcnt vmcnt(3)
	v_sub_f32_e32 v113, v113, v120
	v_sub_f32_e32 v112, v112, v120
	s_waitcnt vmcnt(2)
	v_sub_f32_e32 v119, v119, v120
	v_sub_f32_e32 v118, v118, v120
	v_sub_f32_e32 v117, v117, v120
	v_sub_f32_e32 v116, v116, v120
	v_sub_f32_e32 v115, v115, v120
	v_sub_f32_e32 v114, v114, v120
	s_nop 0
	s_nop 1
	v_mov_b32_e32 v126, v254
	v_pk_mul_f32 v[112:113], v[112:113], v[126:127] op_sel_hi:[1,0]
	v_pk_mul_f32 v[116:117], v[116:117], v[126:127] op_sel_hi:[1,0]
	v_pk_mul_f32 v[118:119], v[118:119], v[126:127] op_sel_hi:[1,0]
	v_pk_mul_f32 v[114:115], v[114:115], v[126:127] op_sel_hi:[1,0]
	v_pk_fma_f32 v[112:113], v[24:25], v[112:113], v[20:21]
	v_pk_fma_f32 v[118:119], v[18:19], v[118:119], v[30:31]
	v_pk_fma_f32 v[116:117], v[16:17], v[116:117], v[28:29]
	v_pk_fma_f32 v[114:115], v[26:27], v[114:115], v[22:23]
	v_pk_mul_f32 v[112:113], v[112:113], s[26:27] op_sel_hi:[1,0]
	v_pk_mul_f32 v[116:117], v[116:117], s[26:27] op_sel_hi:[1,0]
	v_pk_mul_f32 v[118:119], v[118:119], s[26:27] op_sel_hi:[1,0]
	v_pk_mul_f32 v[114:115], v[114:115], s[26:27] op_sel_hi:[1,0]
	v_pk_fma_f32 v[108:109], v[108:109], s[28:29], v[112:113] op_sel_hi:[1,0,1]
	v_pk_fma_f32 v[112:113], v[106:107], s[28:29], v[118:119] op_sel_hi:[1,0,1]
	v_pk_fma_f32 v[106:107], v[104:105], s[28:29], v[116:117] op_sel_hi:[1,0,1]
	v_pk_fma_f32 v[110:111], v[110:111], s[28:29], v[114:115] op_sel_hi:[1,0,1]
	v_cvt_pk_bf16_f32 v104, v108, v109
	s_nop 0
	v_cvt_pk_bf16_f32 v105, v110, v111
	v_cvt_pk_bf16_f32 v106, v106, v107
	v_cvt_pk_bf16_f32 v107, v112, v113
	global_store_dwordx4 v[124:125], v[104:107], off
	s_waitcnt vmcnt(1)
	s_nop 1
	v_mov_b32_e32 v104, v228
	v_mov_b32_e32 v105, v229
	v_mov_b32_e32 v106, v230
	v_mov_b32_e32 v107, v231
	v_mov_b32_e32 v108, v232
	v_mov_b32_e32 v109, v233
	v_mov_b32_e32 v110, v234
	v_mov_b32_e32 v111, v235
	v_add_u32_e32 v112, 0x80, v178
	v_ashrrev_i32_e32 v113, 31, v112
	v_lshlrev_b64 v[114:115], 11, v[112:113]
	v_lshl_add_u64 v[112:113], v[112:113], 3, s[12:13]
	v_lshl_add_u64 v[114:115], v[114:115], 0, v[176:177]
	v_sub_f32_e32 v105, v105, v120
	v_sub_f32_e32 v104, v104, v120
	v_sub_f32_e32 v111, v111, v120
	v_sub_f32_e32 v110, v110, v120
	v_sub_f32_e32 v109, v109, v120
	v_sub_f32_e32 v108, v108, v120
	v_sub_f32_e32 v107, v107, v120
	v_sub_f32_e32 v106, v106, v120
	v_pk_mul_f32 v[104:105], v[126:127], v[104:105] op_sel_hi:[0,1]
	v_pk_mul_f32 v[108:109], v[126:127], v[108:109] op_sel_hi:[0,1]
	v_pk_mul_f32 v[110:111], v[126:127], v[110:111] op_sel_hi:[0,1]
	v_pk_mul_f32 v[106:107], v[126:127], v[106:107] op_sel_hi:[0,1]
	v_pk_fma_f32 v[104:105], v[8:9], v[104:105], v[12:13]
	v_pk_fma_f32 v[110:111], v[2:3], v[110:111], v[6:7]
	v_pk_fma_f32 v[108:109], v[0:1], v[108:109], v[4:5]
	v_pk_fma_f32 v[106:107], v[10:11], v[106:107], v[14:15]
	v_pk_mul_f32 v[104:105], v[104:105], s[26:27] op_sel_hi:[1,0]
	v_pk_mul_f32 v[108:109], v[108:109], s[26:27] op_sel_hi:[1,0]
	v_pk_mul_f32 v[110:111], v[110:111], s[26:27] op_sel_hi:[1,0]
	v_pk_mul_f32 v[106:107], v[106:107], s[26:27] op_sel_hi:[1,0]
	v_pk_fma_f32 v[100:101], v[100:101], s[28:29], v[104:105] op_sel_hi:[1,0,1]
	v_pk_fma_f32 v[104:105], v[98:99], s[28:29], v[110:111] op_sel_hi:[1,0,1]
	v_pk_fma_f32 v[98:99], v[96:97], s[28:29], v[108:109] op_sel_hi:[1,0,1]
	v_pk_fma_f32 v[102:103], v[102:103], s[28:29], v[106:107] op_sel_hi:[1,0,1]
	v_cvt_pk_bf16_f32 v96, v100, v101
	v_lshl_add_u64 v[106:107], v[114:115], 2, s[14:15]
	v_cvt_pk_bf16_f32 v97, v102, v103
	v_cvt_pk_bf16_f32 v98, v98, v99
	v_cvt_pk_bf16_f32 v99, v104, v105
	global_store_dwordx4 v[124:125], v[96:99], off offset:256
	global_load_dwordx2 v[104:105], v[112:113], off
	global_load_dwordx4 v[96:99], v[106:107], off nt
	global_load_dwordx4 v[100:103], v[106:107], off offset:16 nt
	global_load_dwordx4 v[228:231], v[106:107], off offset:512 nt
	global_load_dwordx4 v[232:235], v[106:107], off offset:528 nt
	v_lshl_add_u64 v[108:109], v[114:115], 1, s[16:17]
	s_waitcnt vmcnt(4)
; __device__ __forceinline__ u32x2 pack8i8(const f32x4 a, const f32x4 b) { return (u32x2){pack4i8(a), pack4i8(b)}; }
; __device__ __forceinline__ u32x4 pack8bf(const f32x4 a, const f32x4 b) { u32x4 w; w.x = cvt_pk_bf16(a[0], a[1]); w.y = cvt_pk_bf16(a[2], a[3]); w.z = cvt_pk_bf16(b[0], b[1]); w.w = cvt_pk_bf16(b[2], b[3]); return w; }
; __device__ __forceinline__ void ln_stats(const float* st, int row, float& mu, float& rs) { const f32x2 s = *(const f32x2*)(st + 2 * (size_t)row); mu = s[0] * (1.0f / DM); rs = 1.0f / sqrtf(s[1] * (1.0f / DM) - mu * mu + LN_EPS); }
;     __device__ __forceinline__ void operator()(EPI_ARGS) const {
;     ...
;             for (int m = 0; m < 4; ++m) { const int row = row0 + ai * HALF + m * 16; const size_t off = (size_t)row * DM + col0;
;                 float mu = 0.f, rs = 1.f; if constexpr (RESLN) ln_stats(stin, row, mu, rs);
;                 float ss = 0.f, qq = 0.f;
; #pragma unroll
;                 for (int bj = 0; bj < 2; ++bj) { f32x4 r0 = __builtin_nontemporal_load((const f32x4*)(res + off + bj * HALF)), r1 = __builtin_nontemporal_load((const f32x4*)(res + off + bj * HALF + 4));
;                     if constexpr (RESLN) { r0 = (r0 - mu) * rs * gg[bj][0] + bb[bj][0]; r1 = (r1 - mu) * rs * gg[bj][1] + bb[bj][1]; }
;                     const f32x4 y0 = r0 * DN_ALPHA + acc[ai][bj][m][0] * ascale, y1 = r1 * DN_ALPHA + acc[ai][bj][m][1] * ascale;
;                     if constexpr (COPY != 4) { __builtin_nontemporal_store(y0, (f32x4*)(Y + off + bj * HALF)); __builtin_nontemporal_store(y1, (f32x4*)(Y + off + bj * HALF + 4)); }
;                     if constexpr (STATS) { ss += ((y0[0] + y0[1]) + (y0[2] + y0[3])) + ((y1[0] + y1[1]) + (y1[2] + y1[3]));
;                         qq += ((y0[0] * y0[0] + y0[1] * y0[1]) + (y0[2] * y0[2] + y0[3] * y0[3])) + ((y1[0] * y1[0] + y1[1] * y1[1]) + (y1[2] * y1[2] + y1[3] * y1[3])); }
;                     if constexpr (COPY == 1) *(u32x2*)((unsigned char*)copy + off + bj * HALF) = pack8fp8(y0 * cscale, y1 * cscale);
;                     if constexpr (COPY == 3) *(u32x2*)((unsigned char*)copy + off + bj * HALF) = pack8i8(y0 * cscale, y1 * cscale);
;                     if constexpr (COPY == 2 || COPY == 4) *(u32x4*)((bf16_t*)copy + off + bj * HALF) = pack8bf(y0, y1); }
	v_pk_mul_f32 v[104:105], v[104:105], s[24:25] op_sel_hi:[1,0]
	s_nop 0
	v_fma_f32 v105, -v104, v104, v105
	v_add_f32_e32 v105, 0x3727c5ac, v105
	v_rsq_f32_e32 v254, v105
	s_waitcnt vmcnt(3)
	v_sub_f32_e32 v97, v97, v104
	v_sub_f32_e32 v96, v96, v104
	s_waitcnt vmcnt(2)
	v_sub_f32_e32 v103, v103, v104
	v_sub_f32_e32 v102, v102, v104
	v_sub_f32_e32 v101, v101, v104
	v_sub_f32_e32 v100, v100, v104
	v_sub_f32_e32 v99, v99, v104
	v_sub_f32_e32 v98, v98, v104
	s_nop 0
	s_nop 1
	v_mov_b32_e32 v110, v254
	v_pk_mul_f32 v[96:97], v[96:97], v[110:111] op_sel_hi:[1,0]
	v_pk_mul_f32 v[100:101], v[100:101], v[110:111] op_sel_hi:[1,0]
	v_pk_mul_f32 v[102:103], v[102:103], v[110:111] op_sel_hi:[1,0]
	v_pk_mul_f32 v[98:99], v[98:99], v[110:111] op_sel_hi:[1,0]
	v_pk_fma_f32 v[96:97], v[24:25], v[96:97], v[20:21]
	v_pk_fma_f32 v[102:103], v[18:19], v[102:103], v[30:31]
	v_pk_fma_f32 v[100:101], v[16:17], v[100:101], v[28:29]
	v_pk_fma_f32 v[98:99], v[26:27], v[98:99], v[22:23]
	v_pk_mul_f32 v[96:97], v[96:97], s[26:27] op_sel_hi:[1,0]
	v_pk_mul_f32 v[100:101], v[100:101], s[26:27] op_sel_hi:[1,0]
	v_pk_mul_f32 v[102:103], v[102:103], s[26:27] op_sel_hi:[1,0]
	v_pk_mul_f32 v[98:99], v[98:99], s[26:27] op_sel_hi:[1,0]
	v_pk_fma_f32 v[92:93], v[92:93], s[28:29], v[96:97] op_sel_hi:[1,0,1]
	v_pk_fma_f32 v[96:97], v[90:91], s[28:29], v[102:103] op_sel_hi:[1,0,1]
	v_pk_fma_f32 v[90:91], v[88:89], s[28:29], v[100:101] op_sel_hi:[1,0,1]
	v_pk_fma_f32 v[94:95], v[94:95], s[28:29], v[98:99] op_sel_hi:[1,0,1]
	v_cvt_pk_bf16_f32 v88, v92, v93
	s_nop 0
	v_cvt_pk_bf16_f32 v89, v94, v95
	v_cvt_pk_bf16_f32 v90, v90, v91
	v_cvt_pk_bf16_f32 v91, v96, v97
	global_store_dwordx4 v[108:109], v[88:91], off
	s_waitcnt vmcnt(1)
	s_nop 1
	v_mov_b32_e32 v88, v228
	v_mov_b32_e32 v89, v229
	v_mov_b32_e32 v90, v230
	v_mov_b32_e32 v91, v231
	v_mov_b32_e32 v92, v232
	v_mov_b32_e32 v93, v233
	v_mov_b32_e32 v94, v234
	v_mov_b32_e32 v95, v235
	v_add_u32_e32 v96, 0x90, v178
	v_ashrrev_i32_e32 v97, 31, v96
	v_lshlrev_b64 v[98:99], 11, v[96:97]
	v_lshl_add_u64 v[96:97], v[96:97], 3, s[12:13]
	v_lshl_add_u64 v[98:99], v[98:99], 0, v[176:177]
	v_sub_f32_e32 v89, v89, v104
	v_sub_f32_e32 v88, v88, v104
	v_sub_f32_e32 v95, v95, v104
	v_sub_f32_e32 v94, v94, v104
	v_sub_f32_e32 v93, v93, v104
	v_sub_f32_e32 v92, v92, v104
	v_sub_f32_e32 v91, v91, v104
	v_sub_f32_e32 v90, v90, v104
	v_pk_mul_f32 v[88:89], v[110:111], v[88:89] op_sel_hi:[0,1]
	v_pk_mul_f32 v[92:93], v[110:111], v[92:93] op_sel_hi:[0,1]
	v_pk_mul_f32 v[94:95], v[110:111], v[94:95] op_sel_hi:[0,1]
	v_pk_mul_f32 v[90:91], v[110:111], v[90:91] op_sel_hi:[0,1]
	v_pk_fma_f32 v[88:89], v[8:9], v[88:89], v[12:13]
	v_pk_fma_f32 v[94:95], v[2:3], v[94:95], v[6:7]
	v_pk_fma_f32 v[92:93], v[0:1], v[92:93], v[4:5]
	v_pk_fma_f32 v[90:91], v[10:11], v[90:91], v[14:15]
	v_pk_mul_f32 v[88:89], v[88:89], s[26:27] op_sel_hi:[1,0]
	v_pk_mul_f32 v[92:93], v[92:93], s[26:27] op_sel_hi:[1,0]
	v_pk_mul_f32 v[94:95], v[94:95], s[26:27] op_sel_hi:[1,0]
	v_pk_mul_f32 v[90:91], v[90:91], s[26:27] op_sel_hi:[1,0]
	v_pk_fma_f32 v[84:85], v[84:85], s[28:29], v[88:89] op_sel_hi:[1,0,1]
	v_pk_fma_f32 v[88:89], v[82:83], s[28:29], v[94:95] op_sel_hi:[1,0,1]
	v_pk_fma_f32 v[82:83], v[80:81], s[28:29], v[92:93] op_sel_hi:[1,0,1]
	v_pk_fma_f32 v[86:87], v[86:87], s[28:29], v[90:91] op_sel_hi:[1,0,1]
	v_cvt_pk_bf16_f32 v80, v84, v85
	v_lshl_add_u64 v[90:91], v[98:99], 2, s[14:15]
	v_cvt_pk_bf16_f32 v81, v86, v87
	v_cvt_pk_bf16_f32 v82, v82, v83
	v_cvt_pk_bf16_f32 v83, v88, v89
	global_store_dwordx4 v[108:109], v[80:83], off offset:256
	global_load_dwordx2 v[88:89], v[96:97], off
	global_load_dwordx4 v[80:83], v[90:91], off nt
	global_load_dwordx4 v[84:87], v[90:91], off offset:16 nt
	global_load_dwordx4 v[228:231], v[90:91], off offset:512 nt
	global_load_dwordx4 v[232:235], v[90:91], off offset:528 nt
	v_lshl_add_u64 v[92:93], v[98:99], 1, s[16:17]
	s_waitcnt vmcnt(4)
	v_pk_mul_f32 v[88:89], v[88:89], s[24:25] op_sel_hi:[1,0]
	s_nop 0
	v_fma_f32 v89, -v88, v88, v89
	v_add_f32_e32 v89, 0x3727c5ac, v89
	v_rsq_f32_e32 v254, v89
	s_waitcnt vmcnt(3)
	v_sub_f32_e32 v81, v81, v88
	v_sub_f32_e32 v80, v80, v88
	s_waitcnt vmcnt(2)
	v_sub_f32_e32 v87, v87, v88
	v_sub_f32_e32 v86, v86, v88
	v_sub_f32_e32 v85, v85, v88
	v_sub_f32_e32 v84, v84, v88
	v_sub_f32_e32 v83, v83, v88
	v_sub_f32_e32 v82, v82, v88
	s_nop 0
	s_nop 1
	v_mov_b32_e32 v94, v254
	v_pk_mul_f32 v[80:81], v[80:81], v[94:95] op_sel_hi:[1,0]
	v_pk_mul_f32 v[84:85], v[84:85], v[94:95] op_sel_hi:[1,0]
	v_pk_mul_f32 v[86:87], v[86:87], v[94:95] op_sel_hi:[1,0]
	v_pk_mul_f32 v[82:83], v[82:83], v[94:95] op_sel_hi:[1,0]
	v_pk_fma_f32 v[80:81], v[24:25], v[80:81], v[20:21]
	v_pk_fma_f32 v[86:87], v[18:19], v[86:87], v[30:31]
	v_pk_fma_f32 v[84:85], v[16:17], v[84:85], v[28:29]
	v_pk_fma_f32 v[82:83], v[26:27], v[82:83], v[22:23]
	v_pk_mul_f32 v[80:81], v[80:81], s[26:27] op_sel_hi:[1,0]
	v_pk_mul_f32 v[84:85], v[84:85], s[26:27] op_sel_hi:[1,0]
	v_pk_mul_f32 v[86:87], v[86:87], s[26:27] op_sel_hi:[1,0]
	v_pk_mul_f32 v[82:83], v[82:83], s[26:27] op_sel_hi:[1,0]
	v_pk_fma_f32 v[76:77], v[76:77], s[28:29], v[80:81] op_sel_hi:[1,0,1]
	v_pk_fma_f32 v[80:81], v[74:75], s[28:29], v[86:87] op_sel_hi:[1,0,1]
	v_pk_fma_f32 v[74:75], v[72:73], s[28:29], v[84:85] op_sel_hi:[1,0,1]
	v_pk_fma_f32 v[78:79], v[78:79], s[28:29], v[82:83] op_sel_hi:[1,0,1]
	v_cvt_pk_bf16_f32 v72, v76, v77
	s_nop 0
	v_cvt_pk_bf16_f32 v73, v78, v79
	v_cvt_pk_bf16_f32 v74, v74, v75
	v_cvt_pk_bf16_f32 v75, v80, v81
	global_store_dwordx4 v[92:93], v[72:75], off
	s_waitcnt vmcnt(1)
; __device__ __forceinline__ u32x2 pack8i8(const f32x4 a, const f32x4 b) { return (u32x2){pack4i8(a), pack4i8(b)}; }
; __device__ __forceinline__ u32x4 pack8bf(const f32x4 a, const f32x4 b) { u32x4 w; w.x = cvt_pk_bf16(a[0], a[1]); w.y = cvt_pk_bf16(a[2], a[3]); w.z = cvt_pk_bf16(b[0], b[1]); w.w = cvt_pk_bf16(b[2], b[3]); return w; }
; __device__ __forceinline__ void ln_stats(const float* st, int row, float& mu, float& rs) { const f32x2 s = *(const f32x2*)(st + 2 * (size_t)row); mu = s[0] * (1.0f / DM); rs = 1.0f / sqrtf(s[1] * (1.0f / DM) - mu * mu + LN_EPS); }
;     __device__ __forceinline__ void operator()(EPI_ARGS) const {
;     ...
;             for (int m = 0; m < 4; ++m) { const int row = row0 + ai * HALF + m * 16; const size_t off = (size_t)row * DM + col0;
;                 float mu = 0.f, rs = 1.f; if constexpr (RESLN) ln_stats(stin, row, mu, rs);
;                 float ss = 0.f, qq = 0.f;
; #pragma unroll
;                 for (int bj = 0; bj < 2; ++bj) { f32x4 r0 = __builtin_nontemporal_load((const f32x4*)(res + off + bj * HALF)), r1 = __builtin_nontemporal_load((const f32x4*)(res + off + bj * HALF + 4));
;                     if constexpr (RESLN) { r0 = (r0 - mu) * rs * gg[bj][0] + bb[bj][0]; r1 = (r1 - mu) * rs * gg[bj][1] + bb[bj][1]; }
;                     const f32x4 y0 = r0 * DN_ALPHA + acc[ai][bj][m][0] * ascale, y1 = r1 * DN_ALPHA + acc[ai][bj][m][1] * ascale;
;                     if constexpr (COPY != 4) { __builtin_nontemporal_store(y0, (f32x4*)(Y + off + bj * HALF)); __builtin_nontemporal_store(y1, (f32x4*)(Y + off + bj * HALF + 4)); }
;                     if constexpr (STATS) { ss += ((y0[0] + y0[1]) + (y0[2] + y0[3])) + ((y1[0] + y1[1]) + (y1[2] + y1[3]));
;                         qq += ((y0[0] * y0[0] + y0[1] * y0[1]) + (y0[2] * y0[2] + y0[3] * y0[3])) + ((y1[0] * y1[0] + y1[1] * y1[1]) + (y1[2] * y1[2] + y1[3] * y1[3])); }
;                     if constexpr (COPY == 1) *(u32x2*)((unsigned char*)copy + off + bj * HALF) = pack8fp8(y0 * cscale, y1 * cscale);
;                     if constexpr (COPY == 3) *(u32x2*)((unsigned char*)copy + off + bj * HALF) = pack8i8(y0 * cscale, y1 * cscale);
;                     if constexpr (COPY == 2 || COPY == 4) *(u32x4*)((bf16_t*)copy + off + bj * HALF) = pack8bf(y0, y1); }
	s_nop 1
	v_mov_b32_e32 v72, v228
	v_mov_b32_e32 v73, v229
	v_mov_b32_e32 v74, v230
	v_mov_b32_e32 v75, v231
	v_mov_b32_e32 v76, v232
	v_mov_b32_e32 v77, v233
	v_mov_b32_e32 v78, v234
	v_mov_b32_e32 v79, v235
	v_add_u32_e32 v80, 0xa0, v178
	v_ashrrev_i32_e32 v81, 31, v80
	v_lshlrev_b64 v[82:83], 11, v[80:81]
	v_lshl_add_u64 v[80:81], v[80:81], 3, s[12:13]
	v_lshl_add_u64 v[82:83], v[82:83], 0, v[176:177]
	v_sub_f32_e32 v73, v73, v88
	v_sub_f32_e32 v72, v72, v88
	v_sub_f32_e32 v79, v79, v88
	v_sub_f32_e32 v78, v78, v88
	v_sub_f32_e32 v77, v77, v88
	v_sub_f32_e32 v76, v76, v88
	v_sub_f32_e32 v75, v75, v88
	v_sub_f32_e32 v74, v74, v88
	v_pk_mul_f32 v[72:73], v[94:95], v[72:73] op_sel_hi:[0,1]
	v_pk_mul_f32 v[76:77], v[94:95], v[76:77] op_sel_hi:[0,1]
	v_pk_mul_f32 v[78:79], v[94:95], v[78:79] op_sel_hi:[0,1]
	v_pk_mul_f32 v[74:75], v[94:95], v[74:75] op_sel_hi:[0,1]
	v_pk_fma_f32 v[72:73], v[8:9], v[72:73], v[12:13]
	v_pk_fma_f32 v[78:79], v[2:3], v[78:79], v[6:7]
	v_pk_fma_f32 v[76:77], v[0:1], v[76:77], v[4:5]
	v_pk_fma_f32 v[74:75], v[10:11], v[74:75], v[14:15]
	v_pk_mul_f32 v[72:73], v[72:73], s[26:27] op_sel_hi:[1,0]
	v_pk_mul_f32 v[76:77], v[76:77], s[26:27] op_sel_hi:[1,0]
	v_pk_mul_f32 v[78:79], v[78:79], s[26:27] op_sel_hi:[1,0]
	v_pk_mul_f32 v[74:75], v[74:75], s[26:27] op_sel_hi:[1,0]
	v_pk_fma_f32 v[68:69], v[68:69], s[28:29], v[72:73] op_sel_hi:[1,0,1]
	v_pk_fma_f32 v[72:73], v[66:67], s[28:29], v[78:79] op_sel_hi:[1,0,1]
	v_pk_fma_f32 v[66:67], v[64:65], s[28:29], v[76:77] op_sel_hi:[1,0,1]
	v_pk_fma_f32 v[70:71], v[70:71], s[28:29], v[74:75] op_sel_hi:[1,0,1]
	v_cvt_pk_bf16_f32 v64, v68, v69
	v_lshl_add_u64 v[74:75], v[82:83], 2, s[14:15]
	v_cvt_pk_bf16_f32 v65, v70, v71
	v_cvt_pk_bf16_f32 v66, v66, v67
	v_cvt_pk_bf16_f32 v67, v72, v73
	global_store_dwordx4 v[92:93], v[64:67], off offset:256
	global_load_dwordx2 v[72:73], v[80:81], off
	global_load_dwordx4 v[64:67], v[74:75], off nt
	global_load_dwordx4 v[68:71], v[74:75], off offset:16 nt
	global_load_dwordx4 v[228:231], v[74:75], off offset:512 nt
	global_load_dwordx4 v[232:235], v[74:75], off offset:528 nt
	v_lshl_add_u64 v[76:77], v[82:83], 1, s[16:17]
	s_waitcnt vmcnt(4)
	v_pk_mul_f32 v[72:73], v[72:73], s[24:25] op_sel_hi:[1,0]
	s_nop 0
	v_fma_f32 v73, -v72, v72, v73
	v_add_f32_e32 v73, 0x3727c5ac, v73
	v_rsq_f32_e32 v254, v73
	s_waitcnt vmcnt(3)
	v_sub_f32_e32 v65, v65, v72
	v_sub_f32_e32 v64, v64, v72
	s_waitcnt vmcnt(2)
	v_sub_f32_e32 v71, v71, v72
	v_sub_f32_e32 v70, v70, v72
	v_sub_f32_e32 v69, v69, v72
	v_sub_f32_e32 v68, v68, v72
	v_sub_f32_e32 v67, v67, v72
	v_sub_f32_e32 v66, v66, v72
	s_nop 0
	s_nop 1
	v_mov_b32_e32 v78, v254
	v_pk_mul_f32 v[64:65], v[64:65], v[78:79] op_sel_hi:[1,0]
	v_pk_mul_f32 v[68:69], v[68:69], v[78:79] op_sel_hi:[1,0]
	v_pk_mul_f32 v[70:71], v[70:71], v[78:79] op_sel_hi:[1,0]
	v_pk_mul_f32 v[66:67], v[66:67], v[78:79] op_sel_hi:[1,0]
	v_pk_fma_f32 v[64:65], v[24:25], v[64:65], v[20:21]
	v_pk_fma_f32 v[70:71], v[18:19], v[70:71], v[30:31]
	v_pk_fma_f32 v[68:69], v[16:17], v[68:69], v[28:29]
	v_pk_fma_f32 v[66:67], v[26:27], v[66:67], v[22:23]
	v_pk_mul_f32 v[64:65], v[64:65], s[26:27] op_sel_hi:[1,0]
	v_pk_mul_f32 v[68:69], v[68:69], s[26:27] op_sel_hi:[1,0]
	v_pk_mul_f32 v[70:71], v[70:71], s[26:27] op_sel_hi:[1,0]
	v_pk_mul_f32 v[66:67], v[66:67], s[26:27] op_sel_hi:[1,0]
	v_pk_fma_f32 v[60:61], v[60:61], s[28:29], v[64:65] op_sel_hi:[1,0,1]
	v_pk_fma_f32 v[64:65], v[58:59], s[28:29], v[70:71] op_sel_hi:[1,0,1]
	v_pk_fma_f32 v[58:59], v[56:57], s[28:29], v[68:69] op_sel_hi:[1,0,1]
	v_pk_fma_f32 v[62:63], v[62:63], s[28:29], v[66:67] op_sel_hi:[1,0,1]
	v_cvt_pk_bf16_f32 v56, v60, v61
	s_nop 0
	v_cvt_pk_bf16_f32 v57, v62, v63
	v_cvt_pk_bf16_f32 v58, v58, v59
	v_cvt_pk_bf16_f32 v59, v64, v65
	global_store_dwordx4 v[76:77], v[56:59], off
	s_waitcnt vmcnt(1)
; #define PG8_BAR __builtin_amdgcn_s_barrier()
; __device__ __forceinline__ u32x2 pack8i8(const f32x4 a, const f32x4 b) { return (u32x2){pack4i8(a), pack4i8(b)}; }
;     ...
;         if (wr == 0) PG8_BAR;
;         E(acc, cur, wr, wc, fr, fq);
;         if (!has_next) break;
;     __device__ __forceinline__ void operator()(EPI_ARGS) const {
;     ...
;             for (int m = 0; m < 4; ++m) { const int row = row0 + ai * HALF + m * 16; const size_t off = (size_t)row * DM + col0;
;                 float mu = 0.f, rs = 1.f; if constexpr (RESLN) ln_stats(stin, row, mu, rs);
;                 float ss = 0.f, qq = 0.f;
; #pragma unroll
;                 for (int bj = 0; bj < 2; ++bj) { f32x4 r0 = __builtin_nontemporal_load((const f32x4*)(res + off + bj * HALF)), r1 = __builtin_nontemporal_load((const f32x4*)(res + off + bj * HALF + 4));
;                     if constexpr (RESLN) { r0 = (r0 - mu) * rs * gg[bj][0] + bb[bj][0]; r1 = (r1 - mu) * rs * gg[bj][1] + bb[bj][1]; }
;                     const f32x4 y0 = r0 * DN_ALPHA + acc[ai][bj][m][0] * ascale, y1 = r1 * DN_ALPHA + acc[ai][bj][m][1] * ascale;
;                     if constexpr (COPY != 4) { __builtin_nontemporal_store(y0, (f32x4*)(Y + off + bj * HALF)); __builtin_nontemporal_store(y1, (f32x4*)(Y + off + bj * HALF + 4)); }
;                     if constexpr (STATS) { ss += ((y0[0] + y0[1]) + (y0[2] + y0[3])) + ((y1[0] + y1[1]) + (y1[2] + y1[3]));
;                         qq += ((y0[0] * y0[0] + y0[1] * y0[1]) + (y0[2] * y0[2] + y0[3] * y0[3])) + ((y1[0] * y1[0] + y1[1] * y1[1]) + (y1[2] * y1[2] + y1[3] * y1[3])); }
;                     if constexpr (COPY == 1) *(u32x2*)((unsigned char*)copy + off + bj * HALF) = pack8fp8(y0 * cscale, y1 * cscale);
;                     if constexpr (COPY == 3) *(u32x2*)((unsigned char*)copy + off + bj * HALF) = pack8i8(y0 * cscale, y1 * cscale);
;                     if constexpr (COPY == 2 || COPY == 4) *(u32x4*)((bf16_t*)copy + off + bj * HALF) = pack8bf(y0, y1); }
;                 if constexpr (STATS) { ss += __shfl_xor(ss, 16); ss += __shfl_xor(ss, 32); qq += __shfl_xor(qq, 16); qq += __shfl_xor(qq, 32);
;                     if (fq == 0) { unsafeAtomicAdd(stout + 2 * (size_t)row, ss); unsafeAtomicAdd(stout + 2 * (size_t)row + 1, qq); } }
;                 asm volatile("" ::: "memory"); }
	s_nop 1
	v_mov_b32_e32 v56, v228
	v_mov_b32_e32 v57, v229
	v_mov_b32_e32 v58, v230
	v_mov_b32_e32 v59, v231
	v_mov_b32_e32 v60, v232
	v_mov_b32_e32 v61, v233
	v_mov_b32_e32 v62, v234
	v_mov_b32_e32 v63, v235
	v_add_u32_e32 v64, 0xb0, v178
	v_ashrrev_i32_e32 v65, 31, v64
	v_lshlrev_b64 v[66:67], 11, v[64:65]
	v_lshl_add_u64 v[64:65], v[64:65], 3, s[12:13]
	v_lshl_add_u64 v[66:67], v[66:67], 0, v[176:177]
	v_sub_f32_e32 v57, v57, v72
	v_sub_f32_e32 v56, v56, v72
	v_sub_f32_e32 v63, v63, v72
	v_sub_f32_e32 v62, v62, v72
	v_sub_f32_e32 v61, v61, v72
	v_sub_f32_e32 v60, v60, v72
	v_sub_f32_e32 v59, v59, v72
	v_sub_f32_e32 v58, v58, v72
	v_pk_mul_f32 v[56:57], v[78:79], v[56:57] op_sel_hi:[0,1]
	v_pk_mul_f32 v[60:61], v[78:79], v[60:61] op_sel_hi:[0,1]
	v_pk_mul_f32 v[62:63], v[78:79], v[62:63] op_sel_hi:[0,1]
	v_pk_mul_f32 v[58:59], v[78:79], v[58:59] op_sel_hi:[0,1]
	v_pk_fma_f32 v[56:57], v[8:9], v[56:57], v[12:13]
	v_pk_fma_f32 v[62:63], v[2:3], v[62:63], v[6:7]
	v_pk_fma_f32 v[60:61], v[0:1], v[60:61], v[4:5]
	v_pk_fma_f32 v[58:59], v[10:11], v[58:59], v[14:15]
	v_pk_mul_f32 v[56:57], v[56:57], s[26:27] op_sel_hi:[1,0]
	v_pk_mul_f32 v[60:61], v[60:61], s[26:27] op_sel_hi:[1,0]
	v_pk_mul_f32 v[62:63], v[62:63], s[26:27] op_sel_hi:[1,0]
	v_pk_mul_f32 v[58:59], v[58:59], s[26:27] op_sel_hi:[1,0]
	v_pk_fma_f32 v[52:53], v[52:53], s[28:29], v[56:57] op_sel_hi:[1,0,1]
	v_pk_fma_f32 v[56:57], v[50:51], s[28:29], v[62:63] op_sel_hi:[1,0,1]
	v_pk_fma_f32 v[50:51], v[48:49], s[28:29], v[60:61] op_sel_hi:[1,0,1]
	v_pk_fma_f32 v[54:55], v[54:55], s[28:29], v[58:59] op_sel_hi:[1,0,1]
	v_cvt_pk_bf16_f32 v48, v52, v53
	v_lshl_add_u64 v[58:59], v[66:67], 2, s[14:15]
	v_cvt_pk_bf16_f32 v49, v54, v55
	v_cvt_pk_bf16_f32 v50, v50, v51
	v_cvt_pk_bf16_f32 v51, v56, v57
	global_store_dwordx4 v[76:77], v[48:51], off offset:256
	global_load_dwordx2 v[56:57], v[64:65], off
	global_load_dwordx4 v[48:51], v[58:59], off nt
	global_load_dwordx4 v[52:55], v[58:59], off offset:16 nt
	global_load_dwordx4 v[228:231], v[58:59], off offset:512 nt
	global_load_dwordx4 v[232:235], v[58:59], off offset:528 nt
	v_lshl_add_u64 v[60:61], v[66:67], 1, s[16:17]
	s_waitcnt vmcnt(4)
	v_pk_mul_f32 v[56:57], v[56:57], s[24:25] op_sel_hi:[1,0]
	s_nop 0
	v_fma_f32 v57, -v56, v56, v57
	v_add_f32_e32 v57, 0x3727c5ac, v57
	v_rsq_f32_e32 v254, v57
	s_waitcnt vmcnt(2)
	v_sub_f32_e32 v55, v55, v56
	v_sub_f32_e32 v54, v54, v56
	v_sub_f32_e32 v53, v53, v56
	v_sub_f32_e32 v52, v52, v56
	v_sub_f32_e32 v51, v51, v56
	v_sub_f32_e32 v50, v50, v56
	v_sub_f32_e32 v49, v49, v56
	v_sub_f32_e32 v48, v48, v56
	s_nop 0
	s_nop 1
	v_mov_b32_e32 v62, v254
	v_pk_mul_f32 v[52:53], v[52:53], v[62:63] op_sel_hi:[1,0]
	v_pk_mul_f32 v[54:55], v[54:55], v[62:63] op_sel_hi:[1,0]
	v_pk_mul_f32 v[48:49], v[48:49], v[62:63] op_sel_hi:[1,0]
	v_pk_mul_f32 v[50:51], v[50:51], v[62:63] op_sel_hi:[1,0]
	v_pk_fma_f32 v[18:19], v[18:19], v[54:55], v[30:31]
	v_pk_fma_f32 v[16:17], v[16:17], v[52:53], v[28:29]
	v_pk_fma_f32 v[22:23], v[26:27], v[50:51], v[22:23]
	v_pk_fma_f32 v[20:21], v[24:25], v[48:49], v[20:21]
	v_pk_mul_f32 v[16:17], v[16:17], s[26:27] op_sel_hi:[1,0]
	v_pk_mul_f32 v[18:19], v[18:19], s[26:27] op_sel_hi:[1,0]
	v_pk_mul_f32 v[20:21], v[20:21], s[26:27] op_sel_hi:[1,0]
	v_pk_mul_f32 v[22:23], v[22:23], s[26:27] op_sel_hi:[1,0]
	v_pk_fma_f32 v[24:25], v[42:43], s[28:29], v[18:19] op_sel_hi:[1,0,1]
	v_pk_fma_f32 v[18:19], v[40:41], s[28:29], v[16:17] op_sel_hi:[1,0,1]
	v_pk_fma_f32 v[22:23], v[46:47], s[28:29], v[22:23] op_sel_hi:[1,0,1]
	v_pk_fma_f32 v[20:21], v[44:45], s[28:29], v[20:21] op_sel_hi:[1,0,1]
	s_andn2_b64 vcc, exec, s[2:3]
	v_cvt_pk_bf16_f32 v16, v20, v21
	v_cvt_pk_bf16_f32 v17, v22, v23
	v_cvt_pk_bf16_f32 v18, v18, v19
	v_cvt_pk_bf16_f32 v19, v24, v25
	global_store_dwordx4 v[60:61], v[16:19], off
	s_waitcnt vmcnt(1)
	s_nop 1
	v_mov_b32_e32 v16, v228
	v_mov_b32_e32 v17, v229
	v_mov_b32_e32 v18, v230
	v_mov_b32_e32 v19, v231
	v_mov_b32_e32 v20, v232
	v_mov_b32_e32 v21, v233
	v_mov_b32_e32 v22, v234
	v_mov_b32_e32 v23, v235
	s_mov_b64 s[2:3], -1
	v_sub_f32_e32 v19, v19, v56
	v_sub_f32_e32 v23, v23, v56
	v_sub_f32_e32 v22, v22, v56
	v_sub_f32_e32 v21, v21, v56
	v_sub_f32_e32 v20, v20, v56
	v_sub_f32_e32 v18, v18, v56
	v_sub_f32_e32 v17, v17, v56
	v_sub_f32_e32 v16, v16, v56
	v_pk_mul_f32 v[20:21], v[62:63], v[20:21] op_sel_hi:[0,1]
	v_pk_mul_f32 v[22:23], v[62:63], v[22:23] op_sel_hi:[0,1]
	v_pk_mul_f32 v[16:17], v[62:63], v[16:17] op_sel_hi:[0,1]
	v_pk_mul_f32 v[18:19], v[62:63], v[18:19] op_sel_hi:[0,1]
	v_pk_fma_f32 v[2:3], v[2:3], v[22:23], v[6:7]
	v_pk_fma_f32 v[0:1], v[0:1], v[20:21], v[4:5]
	v_pk_fma_f32 v[10:11], v[10:11], v[18:19], v[14:15]
	v_pk_fma_f32 v[8:9], v[8:9], v[16:17], v[12:13]
	v_pk_mul_f32 v[0:1], v[0:1], s[26:27] op_sel_hi:[1,0]
	v_pk_mul_f32 v[2:3], v[2:3], s[26:27] op_sel_hi:[1,0]
	v_pk_mul_f32 v[4:5], v[8:9], s[26:27] op_sel_hi:[1,0]
	v_pk_mul_f32 v[6:7], v[10:11], s[26:27] op_sel_hi:[1,0]
	v_pk_fma_f32 v[8:9], v[34:35], s[28:29], v[2:3] op_sel_hi:[1,0,1]
	v_pk_fma_f32 v[2:3], v[32:33], s[28:29], v[0:1] op_sel_hi:[1,0,1]
	v_pk_fma_f32 v[6:7], v[38:39], s[28:29], v[6:7] op_sel_hi:[1,0,1]
	v_pk_fma_f32 v[4:5], v[36:37], s[28:29], v[4:5] op_sel_hi:[1,0,1]
	s_nop 0
	v_cvt_pk_bf16_f32 v0, v4, v5
	v_cvt_pk_bf16_f32 v1, v6, v7
	v_cvt_pk_bf16_f32 v2, v2, v3
	v_cvt_pk_bf16_f32 v3, v8, v9
	global_store_dwordx4 v[60:61], v[0:3], off offset:256
	s_cbranch_vccnz .LBB0_4494
	s_andn2_b64 vcc, exec, s[6:7]
	s_cbranch_vccnz .LBB0_4493
	s_barrier
	s_branch .LBB0_4493
